# also removed the back-to-back s_setprio 0 / s_setprio 1 pair between the two 16-MFMA groups of every MMA segment
# baseline (speedup 1.0000x reference)
; #define PG8_STAGE(bufoff, gbase, voff) do { _Pragma("unroll") for (int _i = 0; _i < 2; ++_i) \
;         __builtin_amdgcn_global_load_lds((const unsigned*)((const char*)(gbase) + (voff)[_i]), (LAS unsigned*)(lds + (bufoff) + ldsw + _i * 8192), 16, 0, 0); } while (0)
; #define PG8_LDA(dst, b, h) do { _Pragma("unroll") for (int m = 0; m < 4; ++m) _Pragma("unroll") for (int k = 0; k < 2; ++k) dst[m][k] = *(const LAS bf16x8*)(lds + PG8_SA(b, h) + aoff + m * 2048 + k * 1024); } while (0)
; #define PG8_LDB(dst, b, h) do { _Pragma("unroll") for (int n = 0; n < 2; ++n) _Pragma("unroll") for (int k = 0; k < 2; ++k) dst[n][k] = *(const LAS bf16x8*)(lds + PG8_SB(b, h) + boff + n * 2048 + k * 1024); } while (0)
; #define PG8_WAIT_V(n) asm volatile("s_waitcnt vmcnt(" #n ")" ::: "memory")
; #define PG8_WAIT_L(n) asm volatile("s_waitcnt lgkmcnt(" #n ")" ::: "memory")
; #define PG8_BAR __builtin_amdgcn_s_barrier()
; #define PG8_SCHED __builtin_amdgcn_sched_barrier(0)
; template <class Epi, bool SP2, class Sched>
; __device__ __forceinline__ void gemm_phase(LAS unsigned char* lds, const Gemm g, const Sched& S, const Epi& E) {
;     ...
;         const bool has_next = S.next(ui + 1, nxt);
;         const char* nA = has_next ? (const char*)g.A + (size_t)nxt.pm * tstep + nxt.ko : cA; const char* nB = has_next ? (const char*)g.Bt + (size_t)nxt.pn * tstepB + nxt.ko : cB;
;         for (int t = 0; t < nt; t += 2) {
;             const bool last = (t == nt - 2);
;             const char* a1 = cA + (size_t)(t + 1) * kstep;
;             const char* a2 = last ? nA : cA + (size_t)(t + 2) * kstep; const char* b2 = last ? nB : cB + (size_t)(t + 2) * kstep;
;             const char* a3 = a2 + kstep; const char* b3 = b2 + kstep;
;             if constexpr (Epi::MID) { if (t == (nt >> 1)) E.mid(acc, cur, wr, fr); }
;             if constexpr (SP2) {
;             PG8_LDB(B0, 0, 0); PG8_LDB(B1, 0, 1); PG8_SCHED; PG8_LDA(At, 0, 0); PG8_STAGE(PG8_SA(1, 1), a1 + hstep, voffA);
;             PG8_WAIT_V(8); PG8_WAIT_L(0); PG8_BAR; PG8_MMA(0, 0, At, B0); PG8_MMA(0, 1, At, B1); PG8_BAR; PG8_SCHED;
;             PG8_LDA(At, 0, 1); PG8_STAGE(PG8_SB(0, 0), b2, voffB); PG8_STAGE(PG8_SB(0, 1), b2 + hstepB, voffB); PG8_STAGE(PG8_SA(0, 0), a2, voffA);
;             PG8_WAIT_V(8); PG8_WAIT_L(0); PG8_BAR; PG8_MMA(1, 0, At, B0); PG8_MMA(1, 1, At, B1); PG8_BAR; PG8_SCHED;
.LBB0_313:
	s_add_u32 s10, vcc_lo, 0xfffc0080
	s_addc_u32 s11, vcc_hi, -1
	s_add_i32 s22, 0, 0x10000
	s_cmp_eq_u32 s21, 12
	s_cselect_b32 s97, s3, s11
	s_cselect_b32 s96, s17, s10
	v_add_u32_e32 v64, s22, v155
	s_cselect_b32 s11, s62, s20
	s_cselect_b32 s10, s93, s95
	s_add_i32 s24, 0, 0x14000
	ds_read_b128 v[130:133], v64
	ds_read_b128 v[148:151], v64 offset:1024
	ds_read_b128 v[156:159], v64 offset:2048
	ds_read_b128 v[164:167], v64 offset:3072
	v_add_u32_e32 v64, s24, v155
	ds_read_b128 v[168:171], v64
	ds_read_b128 v[172:175], v64 offset:1024
	ds_read_b128 v[176:179], v64 offset:2048
	ds_read_b128 v[180:183], v64 offset:3072
	v_lshl_add_u64 v[152:153], vcc, 0, v[146:147]
	s_add_i32 m0, s73, 0xc000
	ds_read_b128 v[184:187], v162
	ds_read_b128 v[188:191], v162 offset:1024
	ds_read_b128 v[214:217], v162 offset:2048
	ds_read_b128 v[218:221], v162 offset:3072
	ds_read_b128 v[222:225], v162 offset:4096
	ds_read_b128 v[226:229], v162 offset:5120
	ds_read_b128 v[230:233], v162 offset:6144
	ds_read_b128 v[234:237], v162 offset:7168
	global_load_lds_dwordx4 v[152:153], off
	v_lshl_add_u64 v[152:153], vcc, 0, v[144:145]
	s_add_i32 m0, s73, 0xe000
	s_nop 0
	global_load_lds_dwordx4 v[152:153], off
	s_waitcnt vmcnt(8) lgkmcnt(0)
	s_barrier
	s_setprio 1
	v_mfma_f32_16x16x32_bf16 v[126:129], v[130:133], v[184:187], v[126:129]
	v_mfma_f32_16x16x32_bf16 v[122:125], v[156:159], v[184:187], v[122:125]
	v_mfma_f32_16x16x32_bf16 v[110:113], v[130:133], v[214:217], v[110:113]
	v_mfma_f32_16x16x32_bf16 v[106:109], v[156:159], v[214:217], v[106:109]
	v_mfma_f32_16x16x32_bf16 v[94:97], v[130:133], v[222:225], v[94:97]
	v_mfma_f32_16x16x32_bf16 v[90:93], v[156:159], v[222:225], v[90:93]
	v_mfma_f32_16x16x32_bf16 v[78:81], v[130:133], v[230:233], v[78:81]
	v_mfma_f32_16x16x32_bf16 v[74:77], v[156:159], v[230:233], v[74:77]
	v_mfma_f32_16x16x32_bf16 v[126:129], v[148:151], v[188:191], v[126:129]
	v_mfma_f32_16x16x32_bf16 v[122:125], v[164:167], v[188:191], v[122:125]
	v_mfma_f32_16x16x32_bf16 v[110:113], v[148:151], v[218:221], v[110:113]
	v_mfma_f32_16x16x32_bf16 v[106:109], v[164:167], v[218:221], v[106:109]
	v_mfma_f32_16x16x32_bf16 v[94:97], v[148:151], v[226:229], v[94:97]
	v_mfma_f32_16x16x32_bf16 v[90:93], v[164:167], v[226:229], v[90:93]
	v_mfma_f32_16x16x32_bf16 v[78:81], v[148:151], v[234:237], v[78:81]
	v_mfma_f32_16x16x32_bf16 v[74:77], v[164:167], v[234:237], v[74:77]
	v_mfma_f32_16x16x32_bf16 v[118:121], v[168:171], v[184:187], v[118:121]
	v_mfma_f32_16x16x32_bf16 v[114:117], v[176:179], v[184:187], v[114:117]
	v_mfma_f32_16x16x32_bf16 v[102:105], v[168:171], v[214:217], v[102:105]
	v_mfma_f32_16x16x32_bf16 v[98:101], v[176:179], v[214:217], v[98:101]
	v_mfma_f32_16x16x32_bf16 v[86:89], v[168:171], v[222:225], v[86:89]
	v_mfma_f32_16x16x32_bf16 v[82:85], v[176:179], v[222:225], v[82:85]
	v_mfma_f32_16x16x32_bf16 v[70:73], v[168:171], v[230:233], v[70:73]
	v_mfma_f32_16x16x32_bf16 v[66:69], v[176:179], v[230:233], v[66:69]
	v_mfma_f32_16x16x32_bf16 v[118:121], v[172:175], v[188:191], v[118:121]
	v_mfma_f32_16x16x32_bf16 v[114:117], v[180:183], v[188:191], v[114:117]
	v_mfma_f32_16x16x32_bf16 v[102:105], v[172:175], v[218:221], v[102:105]
	v_mfma_f32_16x16x32_bf16 v[98:101], v[180:183], v[218:221], v[98:101]
	v_mfma_f32_16x16x32_bf16 v[86:89], v[172:175], v[226:229], v[86:89]
	v_mfma_f32_16x16x32_bf16 v[82:85], v[180:183], v[226:229], v[82:85]
	v_mfma_f32_16x16x32_bf16 v[70:73], v[172:175], v[234:237], v[70:73]
	v_mfma_f32_16x16x32_bf16 v[66:69], v[180:183], v[234:237], v[66:69]
	s_setprio 0
	s_barrier
	s_add_i32 s22, s22, s72
	v_lshl_add_u64 v[152:153], s[10:11], 0, v[136:137]
	s_mov_b32 m0, s22
	ds_read_b128 v[184:187], v162 offset:16384
	ds_read_b128 v[188:191], v162 offset:17408
	ds_read_b128 v[214:217], v162 offset:18432
	ds_read_b128 v[218:221], v162 offset:19456
	ds_read_b128 v[222:225], v162 offset:20480
	ds_read_b128 v[226:229], v162 offset:21504
	ds_read_b128 v[230:233], v162 offset:22528
	ds_read_b128 v[234:237], v162 offset:23552
	global_load_lds_dwordx4 v[152:153], off
	s_add_i32 m0, s22, 0x2000
	s_add_u32 s22, s10, 0x40000
	v_lshl_add_u64 v[192:193], s[10:11], 0, v[140:141]
	s_addc_u32 s23, s11, 0
	s_add_i32 s24, s24, s72
	global_load_lds_dwordx4 v[192:193], off
	v_lshl_add_u64 v[238:239], s[22:23], 0, v[136:137]
	s_mov_b32 m0, s24
	v_lshl_add_u64 v[240:241], s[96:97], 0, v[138:139]
	global_load_lds_dwordx4 v[238:239], off
	v_lshl_add_u64 v[238:239], s[22:23], 0, v[140:141]
	s_add_i32 m0, s24, 0x2000
	s_nop 0
	global_load_lds_dwordx4 v[238:239], off
	v_lshl_add_u64 v[238:239], s[96:97], 0, v[134:135]
	s_mov_b32 m0, s73
	s_nop 0
	global_load_lds_dwordx4 v[238:239], off
	s_mov_b32 m0, s74
	s_nop 0
	global_load_lds_dwordx4 v[240:241], off
	s_waitcnt vmcnt(8) lgkmcnt(0)
	s_barrier
; #define PG8_STAGE(bufoff, gbase, voff) do { _Pragma("unroll") for (int _i = 0; _i < 2; ++_i) \
;         __builtin_amdgcn_global_load_lds((const unsigned*)((const char*)(gbase) + (voff)[_i]), (LAS unsigned*)(lds + (bufoff) + ldsw + _i * 8192), 16, 0, 0); } while (0)
; #define PG8_LDA(dst, b, h) do { _Pragma("unroll") for (int m = 0; m < 4; ++m) _Pragma("unroll") for (int k = 0; k < 2; ++k) dst[m][k] = *(const LAS bf16x8*)(lds + PG8_SA(b, h) + aoff + m * 2048 + k * 1024); } while (0)
; #define PG8_LDB(dst, b, h) do { _Pragma("unroll") for (int n = 0; n < 2; ++n) _Pragma("unroll") for (int k = 0; k < 2; ++k) dst[n][k] = *(const LAS bf16x8*)(lds + PG8_SB(b, h) + boff + n * 2048 + k * 1024); } while (0)
; #define PG8_MMA(ai, bj, At, Bt) do { __builtin_amdgcn_s_setprio(1); _Pragma("unroll") for (int m = 0; m < 4; ++m) _Pragma("unroll") for (int n = 0; n < 2; ++n) _Pragma("unroll") for (int k = 0; k < 2; ++k) \
;         acc[ai][bj][m][n] = __builtin_amdgcn_mfma_f32_16x16x32_bf16(Bt[n][k], At[m][k], acc[ai][bj][m][n], 0, 0, 0); __builtin_amdgcn_s_setprio(0); } while (0)
; #define PG8_WAIT_V(n) asm volatile("s_waitcnt vmcnt(" #n ")" ::: "memory")
; #define PG8_WAIT_L(n) asm volatile("s_waitcnt lgkmcnt(" #n ")" ::: "memory")
; #define PG8_BAR __builtin_amdgcn_s_barrier()
; #define PG8_SCHED __builtin_amdgcn_sched_barrier(0)
; template <class Epi, bool SP2, class Sched>
; __device__ __forceinline__ void gemm_phase(LAS unsigned char* lds, const Gemm g, const Sched& S, const Epi& E) {
;     ...
;             PG8_WAIT_V(8); PG8_WAIT_L(0); PG8_BAR; PG8_MMA(1, 0, At, B0); PG8_MMA(1, 1, At, B1); PG8_BAR; PG8_SCHED;
;             PG8_LDB(B0, 1, 0); PG8_LDB(B1, 1, 1); PG8_SCHED; PG8_LDA(At, 1, 0); PG8_STAGE(PG8_SA(0, 1), a2 + hstep, voffA);
;             PG8_WAIT_V(8); PG8_WAIT_L(0); PG8_BAR; PG8_MMA(0, 0, At, B0); PG8_MMA(0, 1, At, B1); PG8_BAR; PG8_SCHED;
	s_setprio 1
	v_mfma_f32_16x16x32_bf16 v[60:63], v[130:133], v[184:187], v[60:63]
	v_mfma_f32_16x16x32_bf16 v[56:59], v[156:159], v[184:187], v[56:59]
	v_mfma_f32_16x16x32_bf16 v[44:47], v[130:133], v[214:217], v[44:47]
	v_mfma_f32_16x16x32_bf16 v[40:43], v[156:159], v[214:217], v[40:43]
	v_mfma_f32_16x16x32_bf16 v[28:31], v[130:133], v[222:225], v[28:31]
	v_mfma_f32_16x16x32_bf16 v[24:27], v[156:159], v[222:225], v[24:27]
	v_mfma_f32_16x16x32_bf16 v[12:15], v[130:133], v[230:233], v[12:15]
	v_mfma_f32_16x16x32_bf16 v[8:11], v[156:159], v[230:233], v[8:11]
	v_mfma_f32_16x16x32_bf16 v[60:63], v[148:151], v[188:191], v[60:63]
	v_mfma_f32_16x16x32_bf16 v[56:59], v[164:167], v[188:191], v[56:59]
	v_mfma_f32_16x16x32_bf16 v[44:47], v[148:151], v[218:221], v[44:47]
	v_mfma_f32_16x16x32_bf16 v[40:43], v[164:167], v[218:221], v[40:43]
	v_mfma_f32_16x16x32_bf16 v[28:31], v[148:151], v[226:229], v[28:31]
	v_mfma_f32_16x16x32_bf16 v[24:27], v[164:167], v[226:229], v[24:27]
	v_mfma_f32_16x16x32_bf16 v[12:15], v[148:151], v[234:237], v[12:15]
	v_mfma_f32_16x16x32_bf16 v[8:11], v[164:167], v[234:237], v[8:11]
	v_mfma_f32_16x16x32_bf16 v[52:55], v[168:171], v[184:187], v[52:55]
	v_mfma_f32_16x16x32_bf16 v[48:51], v[176:179], v[184:187], v[48:51]
	v_mfma_f32_16x16x32_bf16 v[36:39], v[168:171], v[214:217], v[36:39]
	v_mfma_f32_16x16x32_bf16 v[32:35], v[176:179], v[214:217], v[32:35]
	v_mfma_f32_16x16x32_bf16 v[20:23], v[168:171], v[222:225], v[20:23]
	v_mfma_f32_16x16x32_bf16 v[16:19], v[176:179], v[222:225], v[16:19]
	v_mfma_f32_16x16x32_bf16 v[4:7], v[168:171], v[230:233], v[4:7]
	v_mfma_f32_16x16x32_bf16 v[0:3], v[176:179], v[230:233], v[0:3]
	v_mfma_f32_16x16x32_bf16 v[52:55], v[172:175], v[188:191], v[52:55]
	v_mfma_f32_16x16x32_bf16 v[48:51], v[180:183], v[188:191], v[48:51]
	v_mfma_f32_16x16x32_bf16 v[36:39], v[172:175], v[218:221], v[36:39]
	v_mfma_f32_16x16x32_bf16 v[32:35], v[180:183], v[218:221], v[32:35]
	v_mfma_f32_16x16x32_bf16 v[20:23], v[172:175], v[226:229], v[20:23]
	v_mfma_f32_16x16x32_bf16 v[16:19], v[180:183], v[226:229], v[16:19]
	v_mfma_f32_16x16x32_bf16 v[4:7], v[172:175], v[234:237], v[4:7]
	v_mfma_f32_16x16x32_bf16 v[0:3], v[180:183], v[234:237], v[0:3]
	s_setprio 0
	s_barrier
	s_add_i32 s24, 0, 0x18000
	v_add_u32_e32 v64, s24, v155
	s_add_i32 s25, 0, 0x1c000
	ds_read_b128 v[130:133], v64
	ds_read_b128 v[148:151], v64 offset:1024
	ds_read_b128 v[156:159], v64 offset:2048
	ds_read_b128 v[164:167], v64 offset:3072
	v_add_u32_e32 v64, s25, v155
	ds_read_b128 v[168:171], v64
	ds_read_b128 v[172:175], v64 offset:1024
	ds_read_b128 v[176:179], v64 offset:2048
	ds_read_b128 v[180:183], v64 offset:3072
	s_add_u32 s22, s96, 0x40000
	s_addc_u32 s23, s97, 0
	s_mov_b32 m0, s75
	v_lshl_add_u64 v[248:249], s[22:23], 0, v[134:135]
	ds_read_b128 v[184:187], v162 offset:32768
	ds_read_b128 v[188:191], v162 offset:33792
	ds_read_b128 v[214:217], v162 offset:34816
	ds_read_b128 v[218:221], v162 offset:35840
	ds_read_b128 v[222:225], v162 offset:36864
	ds_read_b128 v[226:229], v162 offset:37888
	ds_read_b128 v[230:233], v162 offset:38912
	ds_read_b128 v[234:237], v162 offset:39936
	global_load_lds_dwordx4 v[248:249], off
	v_lshl_add_u64 v[248:249], s[22:23], 0, v[138:139]
	s_mov_b32 m0, s76
	s_nop 0
	global_load_lds_dwordx4 v[248:249], off
	s_waitcnt vmcnt(8) lgkmcnt(0)
	s_barrier
	s_setprio 1
	v_mfma_f32_16x16x32_bf16 v[126:129], v[130:133], v[184:187], v[126:129]
	v_mfma_f32_16x16x32_bf16 v[122:125], v[156:159], v[184:187], v[122:125]
	v_mfma_f32_16x16x32_bf16 v[110:113], v[130:133], v[214:217], v[110:113]
	v_mfma_f32_16x16x32_bf16 v[106:109], v[156:159], v[214:217], v[106:109]
	v_mfma_f32_16x16x32_bf16 v[94:97], v[130:133], v[222:225], v[94:97]
	v_mfma_f32_16x16x32_bf16 v[90:93], v[156:159], v[222:225], v[90:93]
	v_mfma_f32_16x16x32_bf16 v[78:81], v[130:133], v[230:233], v[78:81]
	v_mfma_f32_16x16x32_bf16 v[74:77], v[156:159], v[230:233], v[74:77]
	v_mfma_f32_16x16x32_bf16 v[126:129], v[148:151], v[188:191], v[126:129]
	v_mfma_f32_16x16x32_bf16 v[122:125], v[164:167], v[188:191], v[122:125]
	v_mfma_f32_16x16x32_bf16 v[110:113], v[148:151], v[218:221], v[110:113]
	v_mfma_f32_16x16x32_bf16 v[106:109], v[164:167], v[218:221], v[106:109]
	v_mfma_f32_16x16x32_bf16 v[94:97], v[148:151], v[226:229], v[94:97]
	v_mfma_f32_16x16x32_bf16 v[90:93], v[164:167], v[226:229], v[90:93]
	v_mfma_f32_16x16x32_bf16 v[78:81], v[148:151], v[234:237], v[78:81]
	v_mfma_f32_16x16x32_bf16 v[74:77], v[164:167], v[234:237], v[74:77]
	v_mfma_f32_16x16x32_bf16 v[118:121], v[168:171], v[184:187], v[118:121]
	v_mfma_f32_16x16x32_bf16 v[114:117], v[176:179], v[184:187], v[114:117]
	v_mfma_f32_16x16x32_bf16 v[102:105], v[168:171], v[214:217], v[102:105]
	v_mfma_f32_16x16x32_bf16 v[98:101], v[176:179], v[214:217], v[98:101]
	v_mfma_f32_16x16x32_bf16 v[86:89], v[168:171], v[222:225], v[86:89]
	v_mfma_f32_16x16x32_bf16 v[82:85], v[176:179], v[222:225], v[82:85]
	v_mfma_f32_16x16x32_bf16 v[70:73], v[168:171], v[230:233], v[70:73]
	v_mfma_f32_16x16x32_bf16 v[66:69], v[176:179], v[230:233], v[66:69]
	v_mfma_f32_16x16x32_bf16 v[118:121], v[172:175], v[188:191], v[118:121]
	v_mfma_f32_16x16x32_bf16 v[114:117], v[180:183], v[188:191], v[114:117]
	v_mfma_f32_16x16x32_bf16 v[102:105], v[172:175], v[218:221], v[102:105]
	v_mfma_f32_16x16x32_bf16 v[98:101], v[180:183], v[218:221], v[98:101]
	v_mfma_f32_16x16x32_bf16 v[86:89], v[172:175], v[226:229], v[86:89]
	v_mfma_f32_16x16x32_bf16 v[82:85], v[180:183], v[226:229], v[82:85]
	v_mfma_f32_16x16x32_bf16 v[70:73], v[172:175], v[234:237], v[70:73]
	v_mfma_f32_16x16x32_bf16 v[66:69], v[180:183], v[234:237], v[66:69]
	s_setprio 0
	s_barrier
; #define PG8_STAGE(bufoff, gbase, voff) do { _Pragma("unroll") for (int _i = 0; _i < 2; ++_i) \
;         __builtin_amdgcn_global_load_lds((const unsigned*)((const char*)(gbase) + (voff)[_i]), (LAS unsigned*)(lds + (bufoff) + ldsw + _i * 8192), 16, 0, 0); } while (0)
; #define PG8_LDA(dst, b, h) do { _Pragma("unroll") for (int m = 0; m < 4; ++m) _Pragma("unroll") for (int k = 0; k < 2; ++k) dst[m][k] = *(const LAS bf16x8*)(lds + PG8_SA(b, h) + aoff + m * 2048 + k * 1024); } while (0)
; #define PG8_MMA(ai, bj, At, Bt) do { __builtin_amdgcn_s_setprio(1); _Pragma("unroll") for (int m = 0; m < 4; ++m) _Pragma("unroll") for (int n = 0; n < 2; ++n) _Pragma("unroll") for (int k = 0; k < 2; ++k) \
;         acc[ai][bj][m][n] = __builtin_amdgcn_mfma_f32_16x16x32_bf16(Bt[n][k], At[m][k], acc[ai][bj][m][n], 0, 0, 0); __builtin_amdgcn_s_setprio(0); } while (0)
; #define PG8_WAIT_V(n) asm volatile("s_waitcnt vmcnt(" #n ")" ::: "memory")
; #define PG8_WAIT_L(n) asm volatile("s_waitcnt lgkmcnt(" #n ")" ::: "memory")
; #define PG8_BAR __builtin_amdgcn_s_barrier()
; #define PG8_SCHED __builtin_amdgcn_sched_barrier(0)
; template <class Epi, bool SP2, class Sched>
; __device__ __forceinline__ void gemm_phase(LAS unsigned char* lds, const Gemm g, const Sched& S, const Epi& E) {
;     ...
;             PG8_LDA(At, 1, 1); PG8_STAGE(PG8_SB(1, 0), b3, voffB); PG8_STAGE(PG8_SB(1, 1), b3 + hstepB, voffB); PG8_STAGE(PG8_SA(1, 0), a3, voffA);
;             PG8_WAIT_V(8); PG8_WAIT_L(0); PG8_BAR; PG8_MMA(1, 0, At, B0); PG8_MMA(1, 1, At, B1); PG8_BAR; PG8_SCHED;
;     ...
;         if (wr == 0) PG8_BAR;
	s_add_i32 s22, s24, s72
	v_lshl_add_u64 v[152:153], v[152:153], 0, s[66:67]
	s_mov_b32 m0, s22
	ds_read_b128 v[184:187], v162 offset:49152
	ds_read_b128 v[188:191], v162 offset:50176
	ds_read_b128 v[214:217], v162 offset:51200
	ds_read_b128 v[218:221], v162 offset:52224
	ds_read_b128 v[222:225], v162 offset:53248
	ds_read_b128 v[226:229], v162 offset:54272
	ds_read_b128 v[230:233], v162 offset:55296
	ds_read_b128 v[234:237], v162 offset:56320
	global_load_lds_dwordx4 v[152:153], off
	s_add_i32 m0, s22, 0x2000
	s_add_u32 s10, s10, 0x40080
	v_lshl_add_u64 v[152:153], v[192:193], 0, s[66:67]
	s_addc_u32 s11, s11, 0
	s_add_i32 s22, s25, s72
	global_load_lds_dwordx4 v[152:153], off
	v_lshl_add_u64 v[152:153], s[10:11], 0, v[136:137]
	s_mov_b32 m0, s22
	s_nop 0
	global_load_lds_dwordx4 v[152:153], off
	v_lshl_add_u64 v[152:153], s[10:11], 0, v[140:141]
	s_add_i32 m0, s22, 0x2000
	s_nop 0
	global_load_lds_dwordx4 v[152:153], off
	v_lshl_add_u64 v[152:153], v[238:239], 0, s[66:67]
	s_mov_b32 m0, s14
	s_nop 0
	global_load_lds_dwordx4 v[152:153], off
	v_lshl_add_u64 v[152:153], v[240:241], 0, s[66:67]
	s_mov_b32 m0, s15
	s_nop 0
	global_load_lds_dwordx4 v[152:153], off
	s_waitcnt vmcnt(8) lgkmcnt(0)
	s_barrier
	s_setprio 1
	v_mfma_f32_16x16x32_bf16 v[60:63], v[130:133], v[184:187], v[60:63]
	v_mfma_f32_16x16x32_bf16 v[56:59], v[156:159], v[184:187], v[56:59]
	v_mfma_f32_16x16x32_bf16 v[44:47], v[130:133], v[214:217], v[44:47]
	v_mfma_f32_16x16x32_bf16 v[40:43], v[156:159], v[214:217], v[40:43]
	v_mfma_f32_16x16x32_bf16 v[28:31], v[130:133], v[222:225], v[28:31]
	v_mfma_f32_16x16x32_bf16 v[24:27], v[156:159], v[222:225], v[24:27]
	v_mfma_f32_16x16x32_bf16 v[12:15], v[130:133], v[230:233], v[12:15]
	v_mfma_f32_16x16x32_bf16 v[8:11], v[156:159], v[230:233], v[8:11]
	v_mfma_f32_16x16x32_bf16 v[60:63], v[148:151], v[188:191], v[60:63]
	v_mfma_f32_16x16x32_bf16 v[56:59], v[164:167], v[188:191], v[56:59]
	v_mfma_f32_16x16x32_bf16 v[44:47], v[148:151], v[218:221], v[44:47]
	v_mfma_f32_16x16x32_bf16 v[40:43], v[164:167], v[218:221], v[40:43]
	v_mfma_f32_16x16x32_bf16 v[28:31], v[148:151], v[226:229], v[28:31]
	v_mfma_f32_16x16x32_bf16 v[24:27], v[164:167], v[226:229], v[24:27]
	v_mfma_f32_16x16x32_bf16 v[12:15], v[148:151], v[234:237], v[12:15]
	v_mfma_f32_16x16x32_bf16 v[8:11], v[164:167], v[234:237], v[8:11]
	v_mfma_f32_16x16x32_bf16 v[52:55], v[168:171], v[184:187], v[52:55]
	v_mfma_f32_16x16x32_bf16 v[48:51], v[176:179], v[184:187], v[48:51]
	v_mfma_f32_16x16x32_bf16 v[36:39], v[168:171], v[214:217], v[36:39]
	v_mfma_f32_16x16x32_bf16 v[32:35], v[176:179], v[214:217], v[32:35]
	v_mfma_f32_16x16x32_bf16 v[20:23], v[168:171], v[222:225], v[20:23]
	v_mfma_f32_16x16x32_bf16 v[16:19], v[176:179], v[222:225], v[16:19]
	v_mfma_f32_16x16x32_bf16 v[4:7], v[168:171], v[230:233], v[4:7]
	v_mfma_f32_16x16x32_bf16 v[0:3], v[176:179], v[230:233], v[0:3]
	v_mfma_f32_16x16x32_bf16 v[52:55], v[172:175], v[188:191], v[52:55]
	v_mfma_f32_16x16x32_bf16 v[48:51], v[180:183], v[188:191], v[48:51]
	v_mfma_f32_16x16x32_bf16 v[36:39], v[172:175], v[218:221], v[36:39]
	v_mfma_f32_16x16x32_bf16 v[32:35], v[180:183], v[218:221], v[32:35]
	v_mfma_f32_16x16x32_bf16 v[20:23], v[172:175], v[226:229], v[20:23]
	v_mfma_f32_16x16x32_bf16 v[16:19], v[180:183], v[226:229], v[16:19]
	v_mfma_f32_16x16x32_bf16 v[4:7], v[172:175], v[234:237], v[4:7]
	v_mfma_f32_16x16x32_bf16 v[0:3], v[180:183], v[234:237], v[0:3]
	s_setprio 0
	s_barrier
	s_add_i32 s21, s21, 2
	s_add_u32 s95, s95, 0x100
	s_addc_u32 s20, s20, 0
	s_add_u32 vcc_lo, vcc_lo, 0x100
	s_addc_u32 vcc_hi, vcc_hi, 0
	s_cmp_gt_u32 s21, 13
	s_cbranch_scc0 .LBB0_313
	s_and_b64 vcc, exec, s[88:89]
	s_cbranch_vccz .LBB0_316
	s_barrier

; #define PG8_STAGE(bufoff, gbase, voff) do { _Pragma("unroll") for (int _i = 0; _i < 2; ++_i) \
;         __builtin_amdgcn_global_load_lds((const unsigned*)((const char*)(gbase) + (voff)[_i]), (LAS unsigned*)(lds + (bufoff) + ldsw + _i * 8192), 16, 0, 0); } while (0)
; #define PG8_LDA(dst, b, h) do { _Pragma("unroll") for (int m = 0; m < 4; ++m) _Pragma("unroll") for (int k = 0; k < 2; ++k) dst[m][k] = *(const LAS bf16x8*)(lds + PG8_SA(b, h) + aoff + m * 2048 + k * 1024); } while (0)
; #define PG8_LDB(dst, b, h) do { _Pragma("unroll") for (int n = 0; n < 2; ++n) _Pragma("unroll") for (int k = 0; k < 2; ++k) dst[n][k] = *(const LAS bf16x8*)(lds + PG8_SB(b, h) + boff + n * 2048 + k * 1024); } while (0)
; #define PG8_WAIT_V(n) asm volatile("s_waitcnt vmcnt(" #n ")" ::: "memory")
; #define PG8_WAIT_L(n) asm volatile("s_waitcnt lgkmcnt(" #n ")" ::: "memory")
; #define PG8_BAR __builtin_amdgcn_s_barrier()
; #define PG8_SCHED __builtin_amdgcn_sched_barrier(0)
; template <class Epi, bool SP2, class Sched>
; __device__ __forceinline__ void gemm_phase(LAS unsigned char* lds, const Gemm g, const Sched& S, const Epi& E) {
;     ...
;         const bool has_next = S.next(ui + 1, nxt);
;         const char* nA = has_next ? (const char*)g.A + (size_t)nxt.pm * tstep + nxt.ko : cA; const char* nB = has_next ? (const char*)g.Bt + (size_t)nxt.pn * tstepB + nxt.ko : cB;
;         for (int t = 0; t < nt; t += 2) {
;             const bool last = (t == nt - 2);
;             const char* a1 = cA + (size_t)(t + 1) * kstep;
;             const char* a2 = last ? nA : cA + (size_t)(t + 2) * kstep; const char* b2 = last ? nB : cB + (size_t)(t + 2) * kstep;
;             const char* a3 = a2 + kstep; const char* b3 = b2 + kstep;
;             if constexpr (Epi::MID) { if (t == (nt >> 1)) E.mid(acc, cur, wr, fr); }
;             if constexpr (SP2) {
;             PG8_LDB(B0, 0, 0); PG8_LDB(B1, 0, 1); PG8_SCHED; PG8_LDA(At, 0, 0); PG8_STAGE(PG8_SA(1, 1), a1 + hstep, voffA);
;             PG8_WAIT_V(8); PG8_WAIT_L(0); PG8_BAR; PG8_MMA(0, 0, At, B0); PG8_MMA(0, 1, At, B1); PG8_BAR; PG8_SCHED;
;             PG8_LDA(At, 0, 1); PG8_STAGE(PG8_SB(0, 0), b2, voffB); PG8_STAGE(PG8_SB(0, 1), b2 + hstepB, voffB); PG8_STAGE(PG8_SA(0, 0), a2, voffA);
;             PG8_WAIT_V(8); PG8_WAIT_L(0); PG8_BAR; PG8_MMA(1, 0, At, B0); PG8_MMA(1, 1, At, B1); PG8_BAR; PG8_SCHED;
.LBB0_381:
	s_add_u32 s6, s90, 0xfffc0080
	s_addc_u32 s7, s91, -1
	s_add_i32 s22, 0, 0x10000
	s_cmp_eq_u32 s21, 12
	s_cselect_b32 s11, s74, s7
	s_cselect_b32 s10, s75, s6
	s_cselect_b32 s7, s61, s20
	s_cselect_b32 s6, s76, s77
	s_add_i32 s24, 0, 0x14000
	v_add_u32_e32 v110, s22, v163
	v_add_u32_e32 v160, s24, v163
	ds_read_b128 v[98:101], v110
	ds_read_b128 v[102:105], v110 offset:1024
	ds_read_b128 v[106:109], v110 offset:2048
	ds_read_b128 v[110:113], v110 offset:3072
	ds_read_b128 v[156:159], v160
	ds_read_b128 v[166:169], v160 offset:1024
	ds_read_b128 v[170:173], v160 offset:2048
	ds_read_b128 v[174:177], v160 offset:3072
	v_lshl_add_u64 v[160:161], s[90:91], 0, v[154:155]
	s_add_i32 m0, s17, 0xc000
	ds_read_b128 v[178:181], v165
	ds_read_b128 v[182:185], v165 offset:1024
	ds_read_b128 v[186:189], v165 offset:2048
	ds_read_b128 v[190:193], v165 offset:3072
	ds_read_b128 v[214:217], v165 offset:4096
	ds_read_b128 v[218:221], v165 offset:5120
	ds_read_b128 v[222:225], v165 offset:6144
	ds_read_b128 v[226:229], v165 offset:7168
	global_load_lds_dwordx4 v[160:161], off
	v_lshl_add_u64 v[160:161], s[90:91], 0, v[152:153]
	s_add_i32 m0, s17, 0xe000
	s_nop 0
	global_load_lds_dwordx4 v[160:161], off
	s_waitcnt vmcnt(8) lgkmcnt(0)
	s_barrier
	s_setprio 1
	v_mfma_f32_16x16x32_bf16 v[142:145], v[98:101], v[178:181], v[142:145]
	v_mfma_f32_16x16x32_bf16 v[138:141], v[106:109], v[178:181], v[138:141]
	v_mfma_f32_16x16x32_bf16 v[126:129], v[98:101], v[186:189], v[126:129]
	v_mfma_f32_16x16x32_bf16 v[122:125], v[106:109], v[186:189], v[122:125]
	v_mfma_f32_16x16x32_bf16 v[94:97], v[98:101], v[214:217], v[94:97]
	v_mfma_f32_16x16x32_bf16 v[90:93], v[106:109], v[214:217], v[90:93]
	v_mfma_f32_16x16x32_bf16 v[78:81], v[98:101], v[222:225], v[78:81]
	v_mfma_f32_16x16x32_bf16 v[74:77], v[106:109], v[222:225], v[74:77]
	v_mfma_f32_16x16x32_bf16 v[142:145], v[102:105], v[182:185], v[142:145]
	v_mfma_f32_16x16x32_bf16 v[138:141], v[110:113], v[182:185], v[138:141]
	v_mfma_f32_16x16x32_bf16 v[126:129], v[102:105], v[190:193], v[126:129]
	v_mfma_f32_16x16x32_bf16 v[122:125], v[110:113], v[190:193], v[122:125]
	v_mfma_f32_16x16x32_bf16 v[94:97], v[102:105], v[218:221], v[94:97]
	v_mfma_f32_16x16x32_bf16 v[90:93], v[110:113], v[218:221], v[90:93]
	v_mfma_f32_16x16x32_bf16 v[78:81], v[102:105], v[226:229], v[78:81]
	v_mfma_f32_16x16x32_bf16 v[74:77], v[110:113], v[226:229], v[74:77]
	v_mfma_f32_16x16x32_bf16 v[134:137], v[156:159], v[178:181], v[134:137]
	v_mfma_f32_16x16x32_bf16 v[130:133], v[170:173], v[178:181], v[130:133]
	v_mfma_f32_16x16x32_bf16 v[118:121], v[156:159], v[186:189], v[118:121]
	v_mfma_f32_16x16x32_bf16 v[114:117], v[170:173], v[186:189], v[114:117]
	v_mfma_f32_16x16x32_bf16 v[86:89], v[156:159], v[214:217], v[86:89]
	v_mfma_f32_16x16x32_bf16 v[82:85], v[170:173], v[214:217], v[82:85]
	v_mfma_f32_16x16x32_bf16 v[70:73], v[156:159], v[222:225], v[70:73]
	v_mfma_f32_16x16x32_bf16 v[66:69], v[170:173], v[222:225], v[66:69]
	v_mfma_f32_16x16x32_bf16 v[134:137], v[166:169], v[182:185], v[134:137]
	v_mfma_f32_16x16x32_bf16 v[130:133], v[174:177], v[182:185], v[130:133]
	v_mfma_f32_16x16x32_bf16 v[118:121], v[166:169], v[190:193], v[118:121]
	v_mfma_f32_16x16x32_bf16 v[114:117], v[174:177], v[190:193], v[114:117]
	v_mfma_f32_16x16x32_bf16 v[86:89], v[166:169], v[218:221], v[86:89]
	v_mfma_f32_16x16x32_bf16 v[82:85], v[174:177], v[218:221], v[82:85]
	v_mfma_f32_16x16x32_bf16 v[70:73], v[166:169], v[226:229], v[70:73]
	v_mfma_f32_16x16x32_bf16 v[66:69], v[174:177], v[226:229], v[66:69]
	s_setprio 0
	s_barrier
	s_add_i32 s22, s22, s19
	v_lshl_add_u64 v[160:161], s[6:7], 0, v[64:65]
	s_mov_b32 m0, s22
	ds_read_b128 v[178:181], v165 offset:16384
	ds_read_b128 v[182:185], v165 offset:17408
	ds_read_b128 v[186:189], v165 offset:18432
	ds_read_b128 v[190:193], v165 offset:19456
	ds_read_b128 v[214:217], v165 offset:20480
	ds_read_b128 v[218:221], v165 offset:21504
	ds_read_b128 v[222:225], v165 offset:22528
	ds_read_b128 v[226:229], v165 offset:23552
	global_load_lds_dwordx4 v[160:161], off
	s_add_i32 m0, s22, 0x2000
	s_add_u32 s22, s6, 0x40000
	v_lshl_add_u64 v[230:231], s[6:7], 0, v[150:151]
	s_addc_u32 s23, s7, 0
	s_add_i32 s24, s24, s19
	global_load_lds_dwordx4 v[230:231], off
	v_lshl_add_u64 v[232:233], s[22:23], 0, v[64:65]
	s_mov_b32 m0, s24
	v_lshl_add_u64 v[234:235], s[10:11], 0, v[148:149]
	global_load_lds_dwordx4 v[232:233], off
	v_lshl_add_u64 v[232:233], s[22:23], 0, v[150:151]
	s_add_i32 m0, s24, 0x2000
	s_nop 0
	global_load_lds_dwordx4 v[232:233], off
	v_lshl_add_u64 v[232:233], s[10:11], 0, v[146:147]
	s_mov_b32 m0, s17
	s_nop 0
	global_load_lds_dwordx4 v[232:233], off
	s_mov_b32 m0, s33
	s_nop 0
	global_load_lds_dwordx4 v[234:235], off
	s_waitcnt vmcnt(8) lgkmcnt(0)
	s_barrier
; #define PG8_STAGE(bufoff, gbase, voff) do { _Pragma("unroll") for (int _i = 0; _i < 2; ++_i) \
;         __builtin_amdgcn_global_load_lds((const unsigned*)((const char*)(gbase) + (voff)[_i]), (LAS unsigned*)(lds + (bufoff) + ldsw + _i * 8192), 16, 0, 0); } while (0)
; #define PG8_LDA(dst, b, h) do { _Pragma("unroll") for (int m = 0; m < 4; ++m) _Pragma("unroll") for (int k = 0; k < 2; ++k) dst[m][k] = *(const LAS bf16x8*)(lds + PG8_SA(b, h) + aoff + m * 2048 + k * 1024); } while (0)
; #define PG8_LDB(dst, b, h) do { _Pragma("unroll") for (int n = 0; n < 2; ++n) _Pragma("unroll") for (int k = 0; k < 2; ++k) dst[n][k] = *(const LAS bf16x8*)(lds + PG8_SB(b, h) + boff + n * 2048 + k * 1024); } while (0)
; #define PG8_MMA(ai, bj, At, Bt) do { __builtin_amdgcn_s_setprio(1); _Pragma("unroll") for (int m = 0; m < 4; ++m) _Pragma("unroll") for (int n = 0; n < 2; ++n) _Pragma("unroll") for (int k = 0; k < 2; ++k) \
;         acc[ai][bj][m][n] = __builtin_amdgcn_mfma_f32_16x16x32_bf16(Bt[n][k], At[m][k], acc[ai][bj][m][n], 0, 0, 0); __builtin_amdgcn_s_setprio(0); } while (0)
; #define PG8_WAIT_V(n) asm volatile("s_waitcnt vmcnt(" #n ")" ::: "memory")
; #define PG8_WAIT_L(n) asm volatile("s_waitcnt lgkmcnt(" #n ")" ::: "memory")
; #define PG8_BAR __builtin_amdgcn_s_barrier()
; #define PG8_SCHED __builtin_amdgcn_sched_barrier(0)
; template <class Epi, bool SP2, class Sched>
; __device__ __forceinline__ void gemm_phase(LAS unsigned char* lds, const Gemm g, const Sched& S, const Epi& E) {
;     ...
;             PG8_WAIT_V(8); PG8_WAIT_L(0); PG8_BAR; PG8_MMA(1, 0, At, B0); PG8_MMA(1, 1, At, B1); PG8_BAR; PG8_SCHED;
;             PG8_LDB(B0, 1, 0); PG8_LDB(B1, 1, 1); PG8_SCHED; PG8_LDA(At, 1, 0); PG8_STAGE(PG8_SA(0, 1), a2 + hstep, voffA);
;             PG8_WAIT_V(8); PG8_WAIT_L(0); PG8_BAR; PG8_MMA(0, 0, At, B0); PG8_MMA(0, 1, At, B1); PG8_BAR; PG8_SCHED;
	s_setprio 1
	v_mfma_f32_16x16x32_bf16 v[60:63], v[98:101], v[178:181], v[60:63]
	v_mfma_f32_16x16x32_bf16 v[56:59], v[106:109], v[178:181], v[56:59]
	v_mfma_f32_16x16x32_bf16 v[48:51], v[98:101], v[186:189], v[48:51]
	v_mfma_f32_16x16x32_bf16 v[40:43], v[106:109], v[186:189], v[40:43]
	v_mfma_f32_16x16x32_bf16 v[32:35], v[98:101], v[214:217], v[32:35]
	v_mfma_f32_16x16x32_bf16 v[24:27], v[106:109], v[214:217], v[24:27]
	v_mfma_f32_16x16x32_bf16 v[16:19], v[98:101], v[222:225], v[16:19]
	v_mfma_f32_16x16x32_bf16 v[8:11], v[106:109], v[222:225], v[8:11]
	v_mfma_f32_16x16x32_bf16 v[60:63], v[102:105], v[182:185], v[60:63]
	v_mfma_f32_16x16x32_bf16 v[56:59], v[110:113], v[182:185], v[56:59]
	v_mfma_f32_16x16x32_bf16 v[48:51], v[102:105], v[190:193], v[48:51]
	v_mfma_f32_16x16x32_bf16 v[40:43], v[110:113], v[190:193], v[40:43]
	v_mfma_f32_16x16x32_bf16 v[32:35], v[102:105], v[218:221], v[32:35]
	v_mfma_f32_16x16x32_bf16 v[24:27], v[110:113], v[218:221], v[24:27]
	v_mfma_f32_16x16x32_bf16 v[16:19], v[102:105], v[226:229], v[16:19]
	v_mfma_f32_16x16x32_bf16 v[8:11], v[110:113], v[226:229], v[8:11]
	v_mfma_f32_16x16x32_bf16 v[52:55], v[156:159], v[178:181], v[52:55]
	v_mfma_f32_16x16x32_bf16 v[44:47], v[170:173], v[178:181], v[44:47]
	v_mfma_f32_16x16x32_bf16 v[36:39], v[156:159], v[186:189], v[36:39]
	v_mfma_f32_16x16x32_bf16 v[28:31], v[170:173], v[186:189], v[28:31]
	v_mfma_f32_16x16x32_bf16 v[20:23], v[156:159], v[214:217], v[20:23]
	v_mfma_f32_16x16x32_bf16 v[12:15], v[170:173], v[214:217], v[12:15]
	v_mfma_f32_16x16x32_bf16 v[4:7], v[156:159], v[222:225], v[4:7]
	v_mfma_f32_16x16x32_bf16 v[0:3], v[170:173], v[222:225], v[0:3]
	v_mfma_f32_16x16x32_bf16 v[52:55], v[166:169], v[182:185], v[52:55]
	v_mfma_f32_16x16x32_bf16 v[44:47], v[174:177], v[182:185], v[44:47]
	v_mfma_f32_16x16x32_bf16 v[36:39], v[166:169], v[190:193], v[36:39]
	v_mfma_f32_16x16x32_bf16 v[28:31], v[174:177], v[190:193], v[28:31]
	v_mfma_f32_16x16x32_bf16 v[20:23], v[166:169], v[218:221], v[20:23]
	v_mfma_f32_16x16x32_bf16 v[12:15], v[174:177], v[218:221], v[12:15]
	v_mfma_f32_16x16x32_bf16 v[4:7], v[166:169], v[226:229], v[4:7]
	v_mfma_f32_16x16x32_bf16 v[0:3], v[174:177], v[226:229], v[0:3]
	s_setprio 0
	s_barrier
	s_add_i32 s22, 0, 0x18000
	s_add_i32 s23, 0, 0x1c000
	v_add_u32_e32 v110, s22, v163
	v_add_u32_e32 v174, s23, v163
	ds_read_b128 v[98:101], v110
	ds_read_b128 v[102:105], v110 offset:1024
	ds_read_b128 v[106:109], v110 offset:2048
	ds_read_b128 v[110:113], v110 offset:3072
	ds_read_b128 v[156:159], v174
	ds_read_b128 v[166:169], v174 offset:1024
	ds_read_b128 v[170:173], v174 offset:2048
	ds_read_b128 v[174:177], v174 offset:3072
	s_add_u32 s10, s10, 0x40000
	s_addc_u32 s11, s11, 0
	s_mov_b32 m0, s62
	v_lshl_add_u64 v[236:237], s[10:11], 0, v[146:147]
	ds_read_b128 v[178:181], v165 offset:32768
	ds_read_b128 v[182:185], v165 offset:33792
	ds_read_b128 v[186:189], v165 offset:34816
	ds_read_b128 v[190:193], v165 offset:35840
	ds_read_b128 v[214:217], v165 offset:36864
	ds_read_b128 v[218:221], v165 offset:37888
	ds_read_b128 v[222:225], v165 offset:38912
	ds_read_b128 v[226:229], v165 offset:39936
	global_load_lds_dwordx4 v[236:237], off
	v_lshl_add_u64 v[236:237], s[10:11], 0, v[148:149]
	s_mov_b32 m0, s64
	s_nop 0
	global_load_lds_dwordx4 v[236:237], off
	s_waitcnt vmcnt(8) lgkmcnt(0)
	s_barrier
	s_setprio 1
	v_mfma_f32_16x16x32_bf16 v[142:145], v[98:101], v[178:181], v[142:145]
	v_mfma_f32_16x16x32_bf16 v[138:141], v[106:109], v[178:181], v[138:141]
	v_mfma_f32_16x16x32_bf16 v[126:129], v[98:101], v[186:189], v[126:129]
	v_mfma_f32_16x16x32_bf16 v[122:125], v[106:109], v[186:189], v[122:125]
	v_mfma_f32_16x16x32_bf16 v[94:97], v[98:101], v[214:217], v[94:97]
	v_mfma_f32_16x16x32_bf16 v[90:93], v[106:109], v[214:217], v[90:93]
	v_mfma_f32_16x16x32_bf16 v[78:81], v[98:101], v[222:225], v[78:81]
	v_mfma_f32_16x16x32_bf16 v[74:77], v[106:109], v[222:225], v[74:77]
	v_mfma_f32_16x16x32_bf16 v[142:145], v[102:105], v[182:185], v[142:145]
	v_mfma_f32_16x16x32_bf16 v[138:141], v[110:113], v[182:185], v[138:141]
	v_mfma_f32_16x16x32_bf16 v[126:129], v[102:105], v[190:193], v[126:129]
	v_mfma_f32_16x16x32_bf16 v[122:125], v[110:113], v[190:193], v[122:125]
	v_mfma_f32_16x16x32_bf16 v[94:97], v[102:105], v[218:221], v[94:97]
	v_mfma_f32_16x16x32_bf16 v[90:93], v[110:113], v[218:221], v[90:93]
	v_mfma_f32_16x16x32_bf16 v[78:81], v[102:105], v[226:229], v[78:81]
	v_mfma_f32_16x16x32_bf16 v[74:77], v[110:113], v[226:229], v[74:77]
	v_mfma_f32_16x16x32_bf16 v[134:137], v[156:159], v[178:181], v[134:137]
	v_mfma_f32_16x16x32_bf16 v[130:133], v[170:173], v[178:181], v[130:133]
	v_mfma_f32_16x16x32_bf16 v[118:121], v[156:159], v[186:189], v[118:121]
	v_mfma_f32_16x16x32_bf16 v[114:117], v[170:173], v[186:189], v[114:117]
	v_mfma_f32_16x16x32_bf16 v[86:89], v[156:159], v[214:217], v[86:89]
	v_mfma_f32_16x16x32_bf16 v[82:85], v[170:173], v[214:217], v[82:85]
	v_mfma_f32_16x16x32_bf16 v[70:73], v[156:159], v[222:225], v[70:73]
	v_mfma_f32_16x16x32_bf16 v[66:69], v[170:173], v[222:225], v[66:69]
	v_mfma_f32_16x16x32_bf16 v[134:137], v[166:169], v[182:185], v[134:137]
	v_mfma_f32_16x16x32_bf16 v[130:133], v[174:177], v[182:185], v[130:133]
	v_mfma_f32_16x16x32_bf16 v[118:121], v[166:169], v[190:193], v[118:121]
	v_mfma_f32_16x16x32_bf16 v[114:117], v[174:177], v[190:193], v[114:117]
	v_mfma_f32_16x16x32_bf16 v[86:89], v[166:169], v[218:221], v[86:89]
	v_mfma_f32_16x16x32_bf16 v[82:85], v[174:177], v[218:221], v[82:85]
	v_mfma_f32_16x16x32_bf16 v[70:73], v[166:169], v[226:229], v[70:73]
	v_mfma_f32_16x16x32_bf16 v[66:69], v[174:177], v[226:229], v[66:69]
	s_setprio 0
	s_barrier
; #define PG8_STAGE(bufoff, gbase, voff) do { _Pragma("unroll") for (int _i = 0; _i < 2; ++_i) \
;         __builtin_amdgcn_global_load_lds((const unsigned*)((const char*)(gbase) + (voff)[_i]), (LAS unsigned*)(lds + (bufoff) + ldsw + _i * 8192), 16, 0, 0); } while (0)
; #define PG8_LDA(dst, b, h) do { _Pragma("unroll") for (int m = 0; m < 4; ++m) _Pragma("unroll") for (int k = 0; k < 2; ++k) dst[m][k] = *(const LAS bf16x8*)(lds + PG8_SA(b, h) + aoff + m * 2048 + k * 1024); } while (0)
; #define PG8_MMA(ai, bj, At, Bt) do { __builtin_amdgcn_s_setprio(1); _Pragma("unroll") for (int m = 0; m < 4; ++m) _Pragma("unroll") for (int n = 0; n < 2; ++n) _Pragma("unroll") for (int k = 0; k < 2; ++k) \
;         acc[ai][bj][m][n] = __builtin_amdgcn_mfma_f32_16x16x32_bf16(Bt[n][k], At[m][k], acc[ai][bj][m][n], 0, 0, 0); __builtin_amdgcn_s_setprio(0); } while (0)
; #define PG8_WAIT_V(n) asm volatile("s_waitcnt vmcnt(" #n ")" ::: "memory")
; #define PG8_WAIT_L(n) asm volatile("s_waitcnt lgkmcnt(" #n ")" ::: "memory")
; #define PG8_BAR __builtin_amdgcn_s_barrier()
; #define PG8_SCHED __builtin_amdgcn_sched_barrier(0)
; template <class Epi, bool SP2, class Sched>
; __device__ __forceinline__ void gemm_phase(LAS unsigned char* lds, const Gemm g, const Sched& S, const Epi& E) {
;     ...
;             PG8_LDA(At, 1, 1); PG8_STAGE(PG8_SB(1, 0), b3, voffB); PG8_STAGE(PG8_SB(1, 1), b3 + hstepB, voffB); PG8_STAGE(PG8_SA(1, 0), a3, voffA);
;             PG8_WAIT_V(8); PG8_WAIT_L(0); PG8_BAR; PG8_MMA(1, 0, At, B0); PG8_MMA(1, 1, At, B1); PG8_BAR; PG8_SCHED;
;     ...
;         if (wr == 0) PG8_BAR;
	s_add_i32 s10, s22, s19
	v_lshl_add_u64 v[160:161], v[160:161], 0, s[66:67]
	s_mov_b32 m0, s10
	ds_read_b128 v[178:181], v165 offset:49152
	ds_read_b128 v[182:185], v165 offset:50176
	ds_read_b128 v[186:189], v165 offset:51200
	ds_read_b128 v[190:193], v165 offset:52224
	ds_read_b128 v[214:217], v165 offset:53248
	ds_read_b128 v[218:221], v165 offset:54272
	ds_read_b128 v[222:225], v165 offset:55296
	ds_read_b128 v[226:229], v165 offset:56320
	global_load_lds_dwordx4 v[160:161], off
	s_add_i32 m0, s10, 0x2000
	s_add_u32 s6, s6, 0x40080
	v_lshl_add_u64 v[160:161], v[230:231], 0, s[66:67]
	s_addc_u32 s7, s7, 0
	s_add_i32 s10, s23, s19
	global_load_lds_dwordx4 v[160:161], off
	v_lshl_add_u64 v[160:161], s[6:7], 0, v[64:65]
	s_mov_b32 m0, s10
	s_nop 0
	global_load_lds_dwordx4 v[160:161], off
	v_lshl_add_u64 v[160:161], s[6:7], 0, v[150:151]
	s_add_i32 m0, s10, 0x2000
	s_nop 0
	global_load_lds_dwordx4 v[160:161], off
	v_lshl_add_u64 v[160:161], v[232:233], 0, s[66:67]
	s_mov_b32 m0, s65
	s_nop 0
	global_load_lds_dwordx4 v[160:161], off
	v_lshl_add_u64 v[160:161], v[234:235], 0, s[66:67]
	s_mov_b32 m0, s68
	s_nop 0
	global_load_lds_dwordx4 v[160:161], off
	s_waitcnt vmcnt(8) lgkmcnt(0)
	s_barrier
	s_setprio 1
	v_mfma_f32_16x16x32_bf16 v[60:63], v[98:101], v[178:181], v[60:63]
	v_mfma_f32_16x16x32_bf16 v[56:59], v[106:109], v[178:181], v[56:59]
	v_mfma_f32_16x16x32_bf16 v[48:51], v[98:101], v[186:189], v[48:51]
	v_mfma_f32_16x16x32_bf16 v[40:43], v[106:109], v[186:189], v[40:43]
	v_mfma_f32_16x16x32_bf16 v[32:35], v[98:101], v[214:217], v[32:35]
	v_mfma_f32_16x16x32_bf16 v[24:27], v[106:109], v[214:217], v[24:27]
	v_mfma_f32_16x16x32_bf16 v[16:19], v[98:101], v[222:225], v[16:19]
	v_mfma_f32_16x16x32_bf16 v[8:11], v[106:109], v[222:225], v[8:11]
	v_mfma_f32_16x16x32_bf16 v[60:63], v[102:105], v[182:185], v[60:63]
	v_mfma_f32_16x16x32_bf16 v[56:59], v[110:113], v[182:185], v[56:59]
	v_mfma_f32_16x16x32_bf16 v[48:51], v[102:105], v[190:193], v[48:51]
	v_mfma_f32_16x16x32_bf16 v[40:43], v[110:113], v[190:193], v[40:43]
	v_mfma_f32_16x16x32_bf16 v[32:35], v[102:105], v[218:221], v[32:35]
	v_mfma_f32_16x16x32_bf16 v[24:27], v[110:113], v[218:221], v[24:27]
	v_mfma_f32_16x16x32_bf16 v[16:19], v[102:105], v[226:229], v[16:19]
	v_mfma_f32_16x16x32_bf16 v[8:11], v[110:113], v[226:229], v[8:11]
	v_mfma_f32_16x16x32_bf16 v[52:55], v[156:159], v[178:181], v[52:55]
	v_mfma_f32_16x16x32_bf16 v[44:47], v[170:173], v[178:181], v[44:47]
	v_mfma_f32_16x16x32_bf16 v[36:39], v[156:159], v[186:189], v[36:39]
	v_mfma_f32_16x16x32_bf16 v[28:31], v[170:173], v[186:189], v[28:31]
	v_mfma_f32_16x16x32_bf16 v[20:23], v[156:159], v[214:217], v[20:23]
	v_mfma_f32_16x16x32_bf16 v[12:15], v[170:173], v[214:217], v[12:15]
	v_mfma_f32_16x16x32_bf16 v[4:7], v[156:159], v[222:225], v[4:7]
	v_mfma_f32_16x16x32_bf16 v[0:3], v[170:173], v[222:225], v[0:3]
	v_mfma_f32_16x16x32_bf16 v[52:55], v[166:169], v[182:185], v[52:55]
	v_mfma_f32_16x16x32_bf16 v[44:47], v[174:177], v[182:185], v[44:47]
	v_mfma_f32_16x16x32_bf16 v[36:39], v[166:169], v[190:193], v[36:39]
	v_mfma_f32_16x16x32_bf16 v[28:31], v[174:177], v[190:193], v[28:31]
	v_mfma_f32_16x16x32_bf16 v[20:23], v[166:169], v[218:221], v[20:23]
	v_mfma_f32_16x16x32_bf16 v[12:15], v[174:177], v[218:221], v[12:15]
	v_mfma_f32_16x16x32_bf16 v[4:7], v[166:169], v[226:229], v[4:7]
	v_mfma_f32_16x16x32_bf16 v[0:3], v[174:177], v[226:229], v[0:3]
	s_setprio 0
	s_barrier
	s_add_i32 s21, s21, 2
	s_add_u32 s77, s77, 0x100
	s_addc_u32 s20, s20, 0
	s_add_u32 s90, s90, 0x100
	s_addc_u32 s91, s91, 0
	s_cmp_gt_u32 s21, 13
	s_cbranch_scc0 .LBB0_381
	s_and_b64 vcc, exec, s[58:59]
	s_cbranch_vccz .LBB0_384
	s_barrier

; #define PG8_STAGE(bufoff, gbase, voff) do { _Pragma("unroll") for (int _i = 0; _i < 2; ++_i) \
;         __builtin_amdgcn_global_load_lds((const unsigned*)((const char*)(gbase) + (voff)[_i]), (LAS unsigned*)(lds + (bufoff) + ldsw + _i * 8192), 16, 0, 0); } while (0)
; #define PG8_LDA(dst, b, h) do { _Pragma("unroll") for (int m = 0; m < 4; ++m) _Pragma("unroll") for (int k = 0; k < 2; ++k) dst[m][k] = *(const LAS bf16x8*)(lds + PG8_SA(b, h) + aoff + m * 2048 + k * 1024); } while (0)
; #define PG8_LDB(dst, b, h) do { _Pragma("unroll") for (int n = 0; n < 2; ++n) _Pragma("unroll") for (int k = 0; k < 2; ++k) dst[n][k] = *(const LAS bf16x8*)(lds + PG8_SB(b, h) + boff + n * 2048 + k * 1024); } while (0)
; #define PG8_WAIT_V(n) asm volatile("s_waitcnt vmcnt(" #n ")" ::: "memory")
; #define PG8_WAIT_L(n) asm volatile("s_waitcnt lgkmcnt(" #n ")" ::: "memory")
; #define PG8_BAR __builtin_amdgcn_s_barrier()
; #define PG8_SCHED __builtin_amdgcn_sched_barrier(0)
; template <class Epi, bool SP2, class Sched>
; __device__ __forceinline__ void gemm_phase(LAS unsigned char* lds, const Gemm g, const Sched& S, const Epi& E) {
;     ...
;         const bool has_next = S.next(ui + 1, nxt);
;         const char* nA = has_next ? (const char*)g.A + (size_t)nxt.pm * tstep + nxt.ko : cA; const char* nB = has_next ? (const char*)g.Bt + (size_t)nxt.pn * tstepB + nxt.ko : cB;
;         for (int t = 0; t < nt; t += 2) {
;             const bool last = (t == nt - 2);
;             const char* a1 = cA + (size_t)(t + 1) * kstep;
;             const char* a2 = last ? nA : cA + (size_t)(t + 2) * kstep; const char* b2 = last ? nB : cB + (size_t)(t + 2) * kstep;
;             const char* a3 = a2 + kstep; const char* b3 = b2 + kstep;
;             if constexpr (Epi::MID) { if (t == (nt >> 1)) E.mid(acc, cur, wr, fr); }
;             if constexpr (SP2) {
;             PG8_LDB(B0, 0, 0); PG8_LDB(B1, 0, 1); PG8_SCHED; PG8_LDA(At, 0, 0); PG8_STAGE(PG8_SA(1, 1), a1 + hstep, voffA);
;             PG8_WAIT_V(8); PG8_WAIT_L(0); PG8_BAR; PG8_MMA(0, 0, At, B0); PG8_MMA(0, 1, At, B1); PG8_BAR; PG8_SCHED;
;             PG8_LDA(At, 0, 1); PG8_STAGE(PG8_SB(0, 0), b2, voffB); PG8_STAGE(PG8_SB(0, 1), b2 + hstepB, voffB); PG8_STAGE(PG8_SA(0, 0), a2, voffA);
;             PG8_WAIT_V(8); PG8_WAIT_L(0); PG8_BAR; PG8_MMA(1, 0, At, B0); PG8_MMA(1, 1, At, B1); PG8_BAR; PG8_SCHED;
.LBB0_587:
	s_add_u32 s6, s94, 0xfffe0080
	s_addc_u32 s7, s95, -1
	s_add_i32 s20, 0, 0x10000
	s_cmp_eq_u32 s19, 4
	s_cselect_b32 s11, s5, s7
	s_cselect_b32 s10, s12, s6
	s_cselect_b32 s7, s13, s18
	s_cselect_b32 s6, s14, s15
	s_add_i32 s22, 0, 0x14000
	v_add_u32_e32 v156, s20, v145
	v_add_u32_e32 v172, s22, v145
	ds_read_b128 v[140:143], v156
	ds_read_b128 v[148:151], v156 offset:1024
	ds_read_b128 v[152:155], v156 offset:2048
	ds_read_b128 v[156:159], v156 offset:3072
	ds_read_b128 v[160:163], v172
	ds_read_b128 v[164:167], v172 offset:1024
	ds_read_b128 v[168:171], v172 offset:2048
	ds_read_b128 v[172:175], v172 offset:3072
	v_lshl_add_u64 v[192:193], s[94:95], 0, v[138:139]
	s_add_i32 m0, s17, 0xc000
	ds_read_b128 v[176:179], v147
	ds_read_b128 v[180:183], v147 offset:1024
	ds_read_b128 v[184:187], v147 offset:2048
	ds_read_b128 v[188:191], v147 offset:3072
	ds_read_b128 v[214:217], v147 offset:4096
	ds_read_b128 v[218:221], v147 offset:5120
	ds_read_b128 v[222:225], v147 offset:6144
	ds_read_b128 v[226:229], v147 offset:7168
	global_load_lds_dwordx4 v[192:193], off
	v_lshl_add_u64 v[192:193], s[94:95], 0, v[136:137]
	s_add_i32 m0, s17, 0xe000
	s_nop 0
	global_load_lds_dwordx4 v[192:193], off
	s_waitcnt vmcnt(8) lgkmcnt(0)
	s_barrier
	s_setprio 1
	v_mfma_f32_16x16x32_bf16 v[126:129], v[140:143], v[176:179], v[126:129]
	v_mfma_f32_16x16x32_bf16 v[122:125], v[152:155], v[176:179], v[122:125]
	v_mfma_f32_16x16x32_bf16 v[110:113], v[140:143], v[184:187], v[110:113]
	v_mfma_f32_16x16x32_bf16 v[106:109], v[152:155], v[184:187], v[106:109]
	v_mfma_f32_16x16x32_bf16 v[94:97], v[140:143], v[214:217], v[94:97]
	v_mfma_f32_16x16x32_bf16 v[90:93], v[152:155], v[214:217], v[90:93]
	v_mfma_f32_16x16x32_bf16 v[78:81], v[140:143], v[222:225], v[78:81]
	v_mfma_f32_16x16x32_bf16 v[74:77], v[152:155], v[222:225], v[74:77]
	v_mfma_f32_16x16x32_bf16 v[126:129], v[148:151], v[180:183], v[126:129]
	v_mfma_f32_16x16x32_bf16 v[122:125], v[156:159], v[180:183], v[122:125]
	v_mfma_f32_16x16x32_bf16 v[110:113], v[148:151], v[188:191], v[110:113]
	v_mfma_f32_16x16x32_bf16 v[106:109], v[156:159], v[188:191], v[106:109]
	v_mfma_f32_16x16x32_bf16 v[94:97], v[148:151], v[218:221], v[94:97]
	v_mfma_f32_16x16x32_bf16 v[90:93], v[156:159], v[218:221], v[90:93]
	v_mfma_f32_16x16x32_bf16 v[78:81], v[148:151], v[226:229], v[78:81]
	v_mfma_f32_16x16x32_bf16 v[74:77], v[156:159], v[226:229], v[74:77]
	v_mfma_f32_16x16x32_bf16 v[118:121], v[160:163], v[176:179], v[118:121]
	v_mfma_f32_16x16x32_bf16 v[114:117], v[168:171], v[176:179], v[114:117]
	v_mfma_f32_16x16x32_bf16 v[102:105], v[160:163], v[184:187], v[102:105]
	v_mfma_f32_16x16x32_bf16 v[98:101], v[168:171], v[184:187], v[98:101]
	v_mfma_f32_16x16x32_bf16 v[86:89], v[160:163], v[214:217], v[86:89]
	v_mfma_f32_16x16x32_bf16 v[82:85], v[168:171], v[214:217], v[82:85]
	v_mfma_f32_16x16x32_bf16 v[70:73], v[160:163], v[222:225], v[70:73]
	v_mfma_f32_16x16x32_bf16 v[66:69], v[168:171], v[222:225], v[66:69]
	v_mfma_f32_16x16x32_bf16 v[118:121], v[164:167], v[180:183], v[118:121]
	v_mfma_f32_16x16x32_bf16 v[114:117], v[172:175], v[180:183], v[114:117]
	v_mfma_f32_16x16x32_bf16 v[102:105], v[164:167], v[188:191], v[102:105]
	v_mfma_f32_16x16x32_bf16 v[98:101], v[172:175], v[188:191], v[98:101]
	v_mfma_f32_16x16x32_bf16 v[86:89], v[164:167], v[218:221], v[86:89]
	v_mfma_f32_16x16x32_bf16 v[82:85], v[172:175], v[218:221], v[82:85]
	v_mfma_f32_16x16x32_bf16 v[70:73], v[164:167], v[226:229], v[70:73]
	v_mfma_f32_16x16x32_bf16 v[66:69], v[172:175], v[226:229], v[66:69]
	s_setprio 0
	s_barrier
	s_add_i32 s20, s20, s65
	v_lshl_add_u64 v[192:193], s[6:7], 0, v[64:65]
	s_mov_b32 m0, s20
	ds_read_b128 v[176:179], v147 offset:16384
	ds_read_b128 v[180:183], v147 offset:17408
	ds_read_b128 v[184:187], v147 offset:18432
	ds_read_b128 v[188:191], v147 offset:19456
	ds_read_b128 v[214:217], v147 offset:20480
	ds_read_b128 v[218:221], v147 offset:21504
	ds_read_b128 v[222:225], v147 offset:22528
	ds_read_b128 v[226:229], v147 offset:23552
	global_load_lds_dwordx4 v[192:193], off
	s_add_i32 m0, s20, 0x2000
	s_add_u32 s20, s6, 0x20000
	v_lshl_add_u64 v[230:231], s[6:7], 0, v[134:135]
	s_addc_u32 s21, s7, 0
	s_add_i32 s22, s22, s65
	global_load_lds_dwordx4 v[230:231], off
	v_lshl_add_u64 v[232:233], s[20:21], 0, v[64:65]
	s_mov_b32 m0, s22
	v_lshl_add_u64 v[234:235], s[10:11], 0, v[132:133]
	global_load_lds_dwordx4 v[232:233], off
	v_lshl_add_u64 v[232:233], s[20:21], 0, v[134:135]
	s_add_i32 m0, s22, 0x2000
	s_nop 0
	global_load_lds_dwordx4 v[232:233], off
	v_lshl_add_u64 v[232:233], s[10:11], 0, v[130:131]
	s_mov_b32 m0, s17
	s_nop 0
	global_load_lds_dwordx4 v[232:233], off
	s_mov_b32 m0, s68
	s_nop 0
	global_load_lds_dwordx4 v[234:235], off
	s_waitcnt vmcnt(8) lgkmcnt(0)
	s_barrier
; #define PG8_STAGE(bufoff, gbase, voff) do { _Pragma("unroll") for (int _i = 0; _i < 2; ++_i) \
;         __builtin_amdgcn_global_load_lds((const unsigned*)((const char*)(gbase) + (voff)[_i]), (LAS unsigned*)(lds + (bufoff) + ldsw + _i * 8192), 16, 0, 0); } while (0)
; #define PG8_LDA(dst, b, h) do { _Pragma("unroll") for (int m = 0; m < 4; ++m) _Pragma("unroll") for (int k = 0; k < 2; ++k) dst[m][k] = *(const LAS bf16x8*)(lds + PG8_SA(b, h) + aoff + m * 2048 + k * 1024); } while (0)
; #define PG8_LDB(dst, b, h) do { _Pragma("unroll") for (int n = 0; n < 2; ++n) _Pragma("unroll") for (int k = 0; k < 2; ++k) dst[n][k] = *(const LAS bf16x8*)(lds + PG8_SB(b, h) + boff + n * 2048 + k * 1024); } while (0)
; #define PG8_MMA(ai, bj, At, Bt) do { __builtin_amdgcn_s_setprio(1); _Pragma("unroll") for (int m = 0; m < 4; ++m) _Pragma("unroll") for (int n = 0; n < 2; ++n) _Pragma("unroll") for (int k = 0; k < 2; ++k) \
;         acc[ai][bj][m][n] = __builtin_amdgcn_mfma_f32_16x16x32_bf16(Bt[n][k], At[m][k], acc[ai][bj][m][n], 0, 0, 0); __builtin_amdgcn_s_setprio(0); } while (0)
; #define PG8_WAIT_V(n) asm volatile("s_waitcnt vmcnt(" #n ")" ::: "memory")
; #define PG8_WAIT_L(n) asm volatile("s_waitcnt lgkmcnt(" #n ")" ::: "memory")
; #define PG8_BAR __builtin_amdgcn_s_barrier()
; #define PG8_SCHED __builtin_amdgcn_sched_barrier(0)
; template <class Epi, bool SP2, class Sched>
; __device__ __forceinline__ void gemm_phase(LAS unsigned char* lds, const Gemm g, const Sched& S, const Epi& E) {
;     ...
;             PG8_WAIT_V(8); PG8_WAIT_L(0); PG8_BAR; PG8_MMA(1, 0, At, B0); PG8_MMA(1, 1, At, B1); PG8_BAR; PG8_SCHED;
;             PG8_LDB(B0, 1, 0); PG8_LDB(B1, 1, 1); PG8_SCHED; PG8_LDA(At, 1, 0); PG8_STAGE(PG8_SA(0, 1), a2 + hstep, voffA);
;             PG8_WAIT_V(8); PG8_WAIT_L(0); PG8_BAR; PG8_MMA(0, 0, At, B0); PG8_MMA(0, 1, At, B1); PG8_BAR; PG8_SCHED;
	s_setprio 1
	v_mfma_f32_16x16x32_bf16 v[60:63], v[140:143], v[176:179], v[60:63]
	v_mfma_f32_16x16x32_bf16 v[56:59], v[152:155], v[176:179], v[56:59]
	v_mfma_f32_16x16x32_bf16 v[44:47], v[140:143], v[184:187], v[44:47]
	v_mfma_f32_16x16x32_bf16 v[40:43], v[152:155], v[184:187], v[40:43]
	v_mfma_f32_16x16x32_bf16 v[28:31], v[140:143], v[214:217], v[28:31]
	v_mfma_f32_16x16x32_bf16 v[24:27], v[152:155], v[214:217], v[24:27]
	v_mfma_f32_16x16x32_bf16 v[12:15], v[140:143], v[222:225], v[12:15]
	v_mfma_f32_16x16x32_bf16 v[8:11], v[152:155], v[222:225], v[8:11]
	v_mfma_f32_16x16x32_bf16 v[60:63], v[148:151], v[180:183], v[60:63]
	v_mfma_f32_16x16x32_bf16 v[56:59], v[156:159], v[180:183], v[56:59]
	v_mfma_f32_16x16x32_bf16 v[44:47], v[148:151], v[188:191], v[44:47]
	v_mfma_f32_16x16x32_bf16 v[40:43], v[156:159], v[188:191], v[40:43]
	v_mfma_f32_16x16x32_bf16 v[28:31], v[148:151], v[218:221], v[28:31]
	v_mfma_f32_16x16x32_bf16 v[24:27], v[156:159], v[218:221], v[24:27]
	v_mfma_f32_16x16x32_bf16 v[12:15], v[148:151], v[226:229], v[12:15]
	v_mfma_f32_16x16x32_bf16 v[8:11], v[156:159], v[226:229], v[8:11]
	v_mfma_f32_16x16x32_bf16 v[52:55], v[160:163], v[176:179], v[52:55]
	v_mfma_f32_16x16x32_bf16 v[48:51], v[168:171], v[176:179], v[48:51]
	v_mfma_f32_16x16x32_bf16 v[36:39], v[160:163], v[184:187], v[36:39]
	v_mfma_f32_16x16x32_bf16 v[32:35], v[168:171], v[184:187], v[32:35]
	v_mfma_f32_16x16x32_bf16 v[20:23], v[160:163], v[214:217], v[20:23]
	v_mfma_f32_16x16x32_bf16 v[16:19], v[168:171], v[214:217], v[16:19]
	v_mfma_f32_16x16x32_bf16 v[4:7], v[160:163], v[222:225], v[4:7]
	v_mfma_f32_16x16x32_bf16 v[0:3], v[168:171], v[222:225], v[0:3]
	v_mfma_f32_16x16x32_bf16 v[52:55], v[164:167], v[180:183], v[52:55]
	v_mfma_f32_16x16x32_bf16 v[48:51], v[172:175], v[180:183], v[48:51]
	v_mfma_f32_16x16x32_bf16 v[36:39], v[164:167], v[188:191], v[36:39]
	v_mfma_f32_16x16x32_bf16 v[32:35], v[172:175], v[188:191], v[32:35]
	v_mfma_f32_16x16x32_bf16 v[20:23], v[164:167], v[218:221], v[20:23]
	v_mfma_f32_16x16x32_bf16 v[16:19], v[172:175], v[218:221], v[16:19]
	v_mfma_f32_16x16x32_bf16 v[4:7], v[164:167], v[226:229], v[4:7]
	v_mfma_f32_16x16x32_bf16 v[0:3], v[172:175], v[226:229], v[0:3]
	s_setprio 0
	s_barrier
	s_add_i32 s20, 0, 0x18000
	s_add_i32 s21, 0, 0x1c000
	v_add_u32_e32 v156, s20, v145
	v_add_u32_e32 v172, s21, v145
	ds_read_b128 v[140:143], v156
	ds_read_b128 v[148:151], v156 offset:1024
	ds_read_b128 v[152:155], v156 offset:2048
	ds_read_b128 v[156:159], v156 offset:3072
	ds_read_b128 v[160:163], v172
	ds_read_b128 v[164:167], v172 offset:1024
	ds_read_b128 v[168:171], v172 offset:2048
	ds_read_b128 v[172:175], v172 offset:3072
	s_add_u32 s10, s10, 0x20000
	s_addc_u32 s11, s11, 0
	s_mov_b32 m0, s69
	v_lshl_add_u64 v[236:237], s[10:11], 0, v[130:131]
	ds_read_b128 v[176:179], v147 offset:32768
	ds_read_b128 v[180:183], v147 offset:33792
	ds_read_b128 v[184:187], v147 offset:34816
	ds_read_b128 v[188:191], v147 offset:35840
	ds_read_b128 v[214:217], v147 offset:36864
	ds_read_b128 v[218:221], v147 offset:37888
	ds_read_b128 v[222:225], v147 offset:38912
	ds_read_b128 v[226:229], v147 offset:39936
	global_load_lds_dwordx4 v[236:237], off
	v_lshl_add_u64 v[236:237], s[10:11], 0, v[132:133]
	s_mov_b32 m0, s72
	s_nop 0
	global_load_lds_dwordx4 v[236:237], off
	s_waitcnt vmcnt(8) lgkmcnt(0)
	s_barrier
	s_setprio 1
	v_mfma_f32_16x16x32_bf16 v[126:129], v[140:143], v[176:179], v[126:129]
	v_mfma_f32_16x16x32_bf16 v[122:125], v[152:155], v[176:179], v[122:125]
	v_mfma_f32_16x16x32_bf16 v[110:113], v[140:143], v[184:187], v[110:113]
	v_mfma_f32_16x16x32_bf16 v[106:109], v[152:155], v[184:187], v[106:109]
	v_mfma_f32_16x16x32_bf16 v[94:97], v[140:143], v[214:217], v[94:97]
	v_mfma_f32_16x16x32_bf16 v[90:93], v[152:155], v[214:217], v[90:93]
	v_mfma_f32_16x16x32_bf16 v[78:81], v[140:143], v[222:225], v[78:81]
	v_mfma_f32_16x16x32_bf16 v[74:77], v[152:155], v[222:225], v[74:77]
	v_mfma_f32_16x16x32_bf16 v[126:129], v[148:151], v[180:183], v[126:129]
	v_mfma_f32_16x16x32_bf16 v[122:125], v[156:159], v[180:183], v[122:125]
	v_mfma_f32_16x16x32_bf16 v[110:113], v[148:151], v[188:191], v[110:113]
	v_mfma_f32_16x16x32_bf16 v[106:109], v[156:159], v[188:191], v[106:109]
	v_mfma_f32_16x16x32_bf16 v[94:97], v[148:151], v[218:221], v[94:97]
	v_mfma_f32_16x16x32_bf16 v[90:93], v[156:159], v[218:221], v[90:93]
	v_mfma_f32_16x16x32_bf16 v[78:81], v[148:151], v[226:229], v[78:81]
	v_mfma_f32_16x16x32_bf16 v[74:77], v[156:159], v[226:229], v[74:77]
	v_mfma_f32_16x16x32_bf16 v[118:121], v[160:163], v[176:179], v[118:121]
	v_mfma_f32_16x16x32_bf16 v[114:117], v[168:171], v[176:179], v[114:117]
	v_mfma_f32_16x16x32_bf16 v[102:105], v[160:163], v[184:187], v[102:105]
	v_mfma_f32_16x16x32_bf16 v[98:101], v[168:171], v[184:187], v[98:101]
	v_mfma_f32_16x16x32_bf16 v[86:89], v[160:163], v[214:217], v[86:89]
	v_mfma_f32_16x16x32_bf16 v[82:85], v[168:171], v[214:217], v[82:85]
	v_mfma_f32_16x16x32_bf16 v[70:73], v[160:163], v[222:225], v[70:73]
	v_mfma_f32_16x16x32_bf16 v[66:69], v[168:171], v[222:225], v[66:69]
	v_mfma_f32_16x16x32_bf16 v[118:121], v[164:167], v[180:183], v[118:121]
	v_mfma_f32_16x16x32_bf16 v[114:117], v[172:175], v[180:183], v[114:117]
	v_mfma_f32_16x16x32_bf16 v[102:105], v[164:167], v[188:191], v[102:105]
	v_mfma_f32_16x16x32_bf16 v[98:101], v[172:175], v[188:191], v[98:101]
	v_mfma_f32_16x16x32_bf16 v[86:89], v[164:167], v[218:221], v[86:89]
	v_mfma_f32_16x16x32_bf16 v[82:85], v[172:175], v[218:221], v[82:85]
	v_mfma_f32_16x16x32_bf16 v[70:73], v[164:167], v[226:229], v[70:73]
	v_mfma_f32_16x16x32_bf16 v[66:69], v[172:175], v[226:229], v[66:69]
	s_setprio 0
	s_barrier
; #define PG8_STAGE(bufoff, gbase, voff) do { _Pragma("unroll") for (int _i = 0; _i < 2; ++_i) \
;         __builtin_amdgcn_global_load_lds((const unsigned*)((const char*)(gbase) + (voff)[_i]), (LAS unsigned*)(lds + (bufoff) + ldsw + _i * 8192), 16, 0, 0); } while (0)
; #define PG8_LDA(dst, b, h) do { _Pragma("unroll") for (int m = 0; m < 4; ++m) _Pragma("unroll") for (int k = 0; k < 2; ++k) dst[m][k] = *(const LAS bf16x8*)(lds + PG8_SA(b, h) + aoff + m * 2048 + k * 1024); } while (0)
; #define PG8_MMA(ai, bj, At, Bt) do { __builtin_amdgcn_s_setprio(1); _Pragma("unroll") for (int m = 0; m < 4; ++m) _Pragma("unroll") for (int n = 0; n < 2; ++n) _Pragma("unroll") for (int k = 0; k < 2; ++k) \
;         acc[ai][bj][m][n] = __builtin_amdgcn_mfma_f32_16x16x32_bf16(Bt[n][k], At[m][k], acc[ai][bj][m][n], 0, 0, 0); __builtin_amdgcn_s_setprio(0); } while (0)
; #define PG8_WAIT_V(n) asm volatile("s_waitcnt vmcnt(" #n ")" ::: "memory")
; #define PG8_WAIT_L(n) asm volatile("s_waitcnt lgkmcnt(" #n ")" ::: "memory")
; #define PG8_BAR __builtin_amdgcn_s_barrier()
; #define PG8_SCHED __builtin_amdgcn_sched_barrier(0)
; template <class Epi, bool SP2, class Sched>
; __device__ __forceinline__ void gemm_phase(LAS unsigned char* lds, const Gemm g, const Sched& S, const Epi& E) {
;     ...
;             PG8_LDA(At, 1, 1); PG8_STAGE(PG8_SB(1, 0), b3, voffB); PG8_STAGE(PG8_SB(1, 1), b3 + hstepB, voffB); PG8_STAGE(PG8_SA(1, 0), a3, voffA);
;             PG8_WAIT_V(8); PG8_WAIT_L(0); PG8_BAR; PG8_MMA(1, 0, At, B0); PG8_MMA(1, 1, At, B1); PG8_BAR; PG8_SCHED;
;     ...
;         if (wr == 0) PG8_BAR;
	s_add_i32 s10, s20, s65
	v_lshl_add_u64 v[192:193], v[192:193], 0, s[66:67]
	s_mov_b32 m0, s10
	ds_read_b128 v[176:179], v147 offset:49152
	ds_read_b128 v[180:183], v147 offset:50176
	ds_read_b128 v[184:187], v147 offset:51200
	ds_read_b128 v[188:191], v147 offset:52224
	ds_read_b128 v[214:217], v147 offset:53248
	ds_read_b128 v[218:221], v147 offset:54272
	ds_read_b128 v[222:225], v147 offset:55296
	ds_read_b128 v[226:229], v147 offset:56320
	global_load_lds_dwordx4 v[192:193], off
	s_add_i32 m0, s10, 0x2000
	s_add_u32 s6, s6, 0x20080
	v_lshl_add_u64 v[192:193], v[230:231], 0, s[66:67]
	s_addc_u32 s7, s7, 0
	s_add_i32 s10, s21, s65
	global_load_lds_dwordx4 v[192:193], off
	v_lshl_add_u64 v[192:193], s[6:7], 0, v[64:65]
	s_mov_b32 m0, s10
	s_nop 0
	global_load_lds_dwordx4 v[192:193], off
	v_lshl_add_u64 v[192:193], s[6:7], 0, v[134:135]
	s_add_i32 m0, s10, 0x2000
	s_nop 0
	global_load_lds_dwordx4 v[192:193], off
	v_lshl_add_u64 v[192:193], v[232:233], 0, s[66:67]
	s_mov_b32 m0, s73
	s_nop 0
	global_load_lds_dwordx4 v[192:193], off
	v_lshl_add_u64 v[192:193], v[234:235], 0, s[66:67]
	s_mov_b32 m0, s74
	s_nop 0
	global_load_lds_dwordx4 v[192:193], off
	s_waitcnt vmcnt(8) lgkmcnt(0)
	s_barrier
	s_setprio 1
	v_mfma_f32_16x16x32_bf16 v[60:63], v[140:143], v[176:179], v[60:63]
	v_mfma_f32_16x16x32_bf16 v[56:59], v[152:155], v[176:179], v[56:59]
	v_mfma_f32_16x16x32_bf16 v[44:47], v[140:143], v[184:187], v[44:47]
	v_mfma_f32_16x16x32_bf16 v[40:43], v[152:155], v[184:187], v[40:43]
	v_mfma_f32_16x16x32_bf16 v[28:31], v[140:143], v[214:217], v[28:31]
	v_mfma_f32_16x16x32_bf16 v[24:27], v[152:155], v[214:217], v[24:27]
	v_mfma_f32_16x16x32_bf16 v[12:15], v[140:143], v[222:225], v[12:15]
	v_mfma_f32_16x16x32_bf16 v[8:11], v[152:155], v[222:225], v[8:11]
	v_mfma_f32_16x16x32_bf16 v[60:63], v[148:151], v[180:183], v[60:63]
	v_mfma_f32_16x16x32_bf16 v[56:59], v[156:159], v[180:183], v[56:59]
	v_mfma_f32_16x16x32_bf16 v[44:47], v[148:151], v[188:191], v[44:47]
	v_mfma_f32_16x16x32_bf16 v[40:43], v[156:159], v[188:191], v[40:43]
	v_mfma_f32_16x16x32_bf16 v[28:31], v[148:151], v[218:221], v[28:31]
	v_mfma_f32_16x16x32_bf16 v[24:27], v[156:159], v[218:221], v[24:27]
	v_mfma_f32_16x16x32_bf16 v[12:15], v[148:151], v[226:229], v[12:15]
	v_mfma_f32_16x16x32_bf16 v[8:11], v[156:159], v[226:229], v[8:11]
	v_mfma_f32_16x16x32_bf16 v[52:55], v[160:163], v[176:179], v[52:55]
	v_mfma_f32_16x16x32_bf16 v[48:51], v[168:171], v[176:179], v[48:51]
	v_mfma_f32_16x16x32_bf16 v[36:39], v[160:163], v[184:187], v[36:39]
	v_mfma_f32_16x16x32_bf16 v[32:35], v[168:171], v[184:187], v[32:35]
	v_mfma_f32_16x16x32_bf16 v[20:23], v[160:163], v[214:217], v[20:23]
	v_mfma_f32_16x16x32_bf16 v[16:19], v[168:171], v[214:217], v[16:19]
	v_mfma_f32_16x16x32_bf16 v[4:7], v[160:163], v[222:225], v[4:7]
	v_mfma_f32_16x16x32_bf16 v[0:3], v[168:171], v[222:225], v[0:3]
	v_mfma_f32_16x16x32_bf16 v[52:55], v[164:167], v[180:183], v[52:55]
	v_mfma_f32_16x16x32_bf16 v[48:51], v[172:175], v[180:183], v[48:51]
	v_mfma_f32_16x16x32_bf16 v[36:39], v[164:167], v[188:191], v[36:39]
	v_mfma_f32_16x16x32_bf16 v[32:35], v[172:175], v[188:191], v[32:35]
	v_mfma_f32_16x16x32_bf16 v[20:23], v[164:167], v[218:221], v[20:23]
	v_mfma_f32_16x16x32_bf16 v[16:19], v[172:175], v[218:221], v[16:19]
	v_mfma_f32_16x16x32_bf16 v[4:7], v[164:167], v[226:229], v[4:7]
	v_mfma_f32_16x16x32_bf16 v[0:3], v[172:175], v[226:229], v[0:3]
	s_setprio 0
	s_barrier
	s_add_i32 s19, s19, 2
	s_add_u32 s15, s15, 0x100
	s_addc_u32 s18, s18, 0
	s_add_u32 s94, s94, 0x100
	s_addc_u32 s95, s95, 0
	s_cmp_gt_u32 s19, 5
	s_cbranch_scc0 .LBB0_587
	s_and_b64 vcc, exec, s[84:85]
	s_cbranch_vccz .LBB0_590
	s_barrier

; #define PG8_STAGE(bufoff, gbase, voff) do { _Pragma("unroll") for (int _i = 0; _i < 2; ++_i) \
;         __builtin_amdgcn_global_load_lds((const unsigned*)((const char*)(gbase) + (voff)[_i]), (LAS unsigned*)(lds + (bufoff) + ldsw + _i * 8192), 16, 0, 0); } while (0)
; #define PG8_LDA(dst, b, h) do { _Pragma("unroll") for (int m = 0; m < 4; ++m) _Pragma("unroll") for (int k = 0; k < 2; ++k) dst[m][k] = *(const LAS bf16x8*)(lds + PG8_SA(b, h) + aoff + m * 2048 + k * 1024); } while (0)
; #define PG8_LDB(dst, b, h) do { _Pragma("unroll") for (int n = 0; n < 2; ++n) _Pragma("unroll") for (int k = 0; k < 2; ++k) dst[n][k] = *(const LAS bf16x8*)(lds + PG8_SB(b, h) + boff + n * 2048 + k * 1024); } while (0)
; #define PG8_WAIT_V(n) asm volatile("s_waitcnt vmcnt(" #n ")" ::: "memory")
; #define PG8_WAIT_L(n) asm volatile("s_waitcnt lgkmcnt(" #n ")" ::: "memory")
; #define PG8_BAR __builtin_amdgcn_s_barrier()
; #define PG8_SCHED __builtin_amdgcn_sched_barrier(0)
; template <class Epi, bool SP2, class Sched>
; __device__ __forceinline__ void gemm_phase(LAS unsigned char* lds, const Gemm g, const Sched& S, const Epi& E) {
;     ...
;         const bool has_next = S.next(ui + 1, nxt);
;         const char* nA = has_next ? (const char*)g.A + (size_t)nxt.pm * tstep + nxt.ko : cA; const char* nB = has_next ? (const char*)g.Bt + (size_t)nxt.pn * tstepB + nxt.ko : cB;
;         for (int t = 0; t < nt; t += 2) {
;             const bool last = (t == nt - 2);
;             const char* a1 = cA + (size_t)(t + 1) * kstep;
;             const char* a2 = last ? nA : cA + (size_t)(t + 2) * kstep; const char* b2 = last ? nB : cB + (size_t)(t + 2) * kstep;
;             const char* a3 = a2 + kstep; const char* b3 = b2 + kstep;
;             if constexpr (Epi::MID) { if (t == (nt >> 1)) E.mid(acc, cur, wr, fr); }
;             if constexpr (SP2) {
;             PG8_LDB(B0, 0, 0); PG8_LDB(B1, 0, 1); PG8_SCHED; PG8_LDA(At, 0, 0); PG8_STAGE(PG8_SA(1, 1), a1 + hstep, voffA);
;             PG8_WAIT_V(8); PG8_WAIT_L(0); PG8_BAR; PG8_MMA(0, 0, At, B0); PG8_MMA(0, 1, At, B1); PG8_BAR; PG8_SCHED;
;             PG8_LDA(At, 0, 1); PG8_STAGE(PG8_SB(0, 0), b2, voffB); PG8_STAGE(PG8_SB(0, 1), b2 + hstepB, voffB); PG8_STAGE(PG8_SA(0, 0), a2, voffA);
;             PG8_WAIT_V(8); PG8_WAIT_L(0); PG8_BAR; PG8_MMA(1, 0, At, B0); PG8_MMA(1, 1, At, B1); PG8_BAR; PG8_SCHED;
.LBB0_673:
	s_add_u32 s6, s94, s96
	s_addc_u32 s7, s95, s97
	s_add_u32 s6, s6, 0x100
	s_addc_u32 s7, s7, 0
	s_add_u32 s19, s15, s96
	s_addc_u32 s20, s16, s97
	s_cmpk_eq_i32 s96, 0x700
	s_cselect_b32 s11, s5, s7
	s_cselect_b32 s10, s12, s6
	s_cselect_b32 s7, s13, s20
	s_cselect_b32 s6, s14, s19
	s_add_i32 s19, 0, 0x10000
	v_add_u32_e32 v64, s19, v153
	s_add_i32 s22, 0, 0x14000
	ds_read_b128 v[156:159], v64
	ds_read_b128 v[160:163], v64 offset:1024
	ds_read_b128 v[164:167], v64 offset:2048
	ds_read_b128 v[168:171], v64 offset:3072
	v_add_u32_e32 v64, s22, v153
	ds_read_b128 v[172:175], v64
	ds_read_b128 v[176:179], v64 offset:1024
	ds_read_b128 v[180:183], v64 offset:2048
	ds_read_b128 v[184:187], v64 offset:3072
	v_lshl_add_u64 v[66:67], v[150:151], 0, s[96:97]
	s_add_i32 m0, s17, 0xc000
	ds_read_b128 v[188:191], v155
	ds_read_b128 v[214:217], v155 offset:1024
	ds_read_b128 v[218:221], v155 offset:2048
	ds_read_b128 v[222:225], v155 offset:3072
	ds_read_b128 v[226:229], v155 offset:4096
	ds_read_b128 v[230:233], v155 offset:5120
	ds_read_b128 v[234:237], v155 offset:6144
	ds_read_b128 v[238:241], v155 offset:7168
	global_load_lds_dwordx4 v[66:67], off
	v_lshl_add_u64 v[66:67], v[148:149], 0, s[96:97]
	s_add_i32 m0, s17, 0xe000
	s_nop 0
	global_load_lds_dwordx4 v[66:67], off
	s_waitcnt vmcnt(8) lgkmcnt(0)
	s_barrier
	s_setprio 1
	v_mfma_f32_16x16x32_bf16 v[128:131], v[156:159], v[188:191], v[128:131]
	v_mfma_f32_16x16x32_bf16 v[124:127], v[164:167], v[188:191], v[124:127]
	v_mfma_f32_16x16x32_bf16 v[112:115], v[156:159], v[218:221], v[112:115]
	v_mfma_f32_16x16x32_bf16 v[108:111], v[164:167], v[218:221], v[108:111]
	v_mfma_f32_16x16x32_bf16 v[96:99], v[156:159], v[226:229], v[96:99]
	v_mfma_f32_16x16x32_bf16 v[92:95], v[164:167], v[226:229], v[92:95]
	v_mfma_f32_16x16x32_bf16 v[80:83], v[156:159], v[234:237], v[80:83]
	v_mfma_f32_16x16x32_bf16 v[76:79], v[164:167], v[234:237], v[76:79]
	v_mfma_f32_16x16x32_bf16 v[128:131], v[160:163], v[214:217], v[128:131]
	v_mfma_f32_16x16x32_bf16 v[124:127], v[168:171], v[214:217], v[124:127]
	v_mfma_f32_16x16x32_bf16 v[112:115], v[160:163], v[222:225], v[112:115]
	v_mfma_f32_16x16x32_bf16 v[108:111], v[168:171], v[222:225], v[108:111]
	v_mfma_f32_16x16x32_bf16 v[96:99], v[160:163], v[230:233], v[96:99]
	v_mfma_f32_16x16x32_bf16 v[92:95], v[168:171], v[230:233], v[92:95]
	v_mfma_f32_16x16x32_bf16 v[80:83], v[160:163], v[238:241], v[80:83]
	v_mfma_f32_16x16x32_bf16 v[76:79], v[168:171], v[238:241], v[76:79]
	v_mfma_f32_16x16x32_bf16 v[120:123], v[172:175], v[188:191], v[120:123]
	v_mfma_f32_16x16x32_bf16 v[116:119], v[180:183], v[188:191], v[116:119]
	v_mfma_f32_16x16x32_bf16 v[104:107], v[172:175], v[218:221], v[104:107]
	v_mfma_f32_16x16x32_bf16 v[100:103], v[180:183], v[218:221], v[100:103]
	v_mfma_f32_16x16x32_bf16 v[88:91], v[172:175], v[226:229], v[88:91]
	v_mfma_f32_16x16x32_bf16 v[84:87], v[180:183], v[226:229], v[84:87]
	v_mfma_f32_16x16x32_bf16 v[72:75], v[172:175], v[234:237], v[72:75]
	v_mfma_f32_16x16x32_bf16 v[66:69], v[180:183], v[234:237], v[68:71]
	v_mfma_f32_16x16x32_bf16 v[120:123], v[176:179], v[214:217], v[120:123]
	v_mfma_f32_16x16x32_bf16 v[116:119], v[184:187], v[214:217], v[116:119]
	v_mfma_f32_16x16x32_bf16 v[104:107], v[176:179], v[222:225], v[104:107]
	v_mfma_f32_16x16x32_bf16 v[100:103], v[184:187], v[222:225], v[100:103]
	v_mfma_f32_16x16x32_bf16 v[88:91], v[176:179], v[230:233], v[88:91]
	v_mfma_f32_16x16x32_bf16 v[84:87], v[184:187], v[230:233], v[84:87]
	v_mfma_f32_16x16x32_bf16 v[72:75], v[176:179], v[238:241], v[72:75]
	v_mfma_f32_16x16x32_bf16 v[66:69], v[184:187], v[238:241], v[66:69]
	s_setprio 0
	s_barrier
	s_add_i32 s19, s19, s73
	v_lshl_add_u64 v[192:193], s[6:7], 0, v[134:135]
	s_mov_b32 m0, s19
	ds_read_b128 v[188:191], v155 offset:16384
	ds_read_b128 v[214:217], v155 offset:17408
	ds_read_b128 v[218:221], v155 offset:18432
	ds_read_b128 v[222:225], v155 offset:19456
	ds_read_b128 v[226:229], v155 offset:20480
	ds_read_b128 v[230:233], v155 offset:21504
	ds_read_b128 v[234:237], v155 offset:22528
	ds_read_b128 v[238:241], v155 offset:23552
	global_load_lds_dwordx4 v[192:193], off
	s_add_i32 m0, s19, 0x2000
	s_add_u32 s20, s6, 0x40000
	v_lshl_add_u64 v[248:249], s[6:7], 0, v[138:139]
	s_addc_u32 s21, s7, 0
	s_add_i32 s19, s22, s73
	global_load_lds_dwordx4 v[248:249], off
	v_lshl_add_u64 v[70:71], s[20:21], 0, v[134:135]
	s_mov_b32 m0, s19
	v_lshl_add_u64 v[250:251], s[10:11], 0, v[132:133]
	global_load_lds_dwordx4 v[70:71], off
	v_lshl_add_u64 v[70:71], s[20:21], 0, v[138:139]
	s_add_i32 m0, s19, 0x2000
	v_lshl_add_u64 v[252:253], s[10:11], 0, v[136:137]
	global_load_lds_dwordx4 v[70:71], off
	s_mov_b32 m0, s17
	s_nop 0
	global_load_lds_dwordx4 v[250:251], off
	s_mov_b32 m0, s79
	s_nop 0
	global_load_lds_dwordx4 v[252:253], off
	s_waitcnt vmcnt(8) lgkmcnt(0)
	s_barrier
; #define PG8_STAGE(bufoff, gbase, voff) do { _Pragma("unroll") for (int _i = 0; _i < 2; ++_i) \
;         __builtin_amdgcn_global_load_lds((const unsigned*)((const char*)(gbase) + (voff)[_i]), (LAS unsigned*)(lds + (bufoff) + ldsw + _i * 8192), 16, 0, 0); } while (0)
; #define PG8_LDA(dst, b, h) do { _Pragma("unroll") for (int m = 0; m < 4; ++m) _Pragma("unroll") for (int k = 0; k < 2; ++k) dst[m][k] = *(const LAS bf16x8*)(lds + PG8_SA(b, h) + aoff + m * 2048 + k * 1024); } while (0)
; #define PG8_LDB(dst, b, h) do { _Pragma("unroll") for (int n = 0; n < 2; ++n) _Pragma("unroll") for (int k = 0; k < 2; ++k) dst[n][k] = *(const LAS bf16x8*)(lds + PG8_SB(b, h) + boff + n * 2048 + k * 1024); } while (0)
; #define PG8_MMA(ai, bj, At, Bt) do { __builtin_amdgcn_s_setprio(1); _Pragma("unroll") for (int m = 0; m < 4; ++m) _Pragma("unroll") for (int n = 0; n < 2; ++n) _Pragma("unroll") for (int k = 0; k < 2; ++k) \
;         acc[ai][bj][m][n] = __builtin_amdgcn_mfma_f32_16x16x32_bf16(Bt[n][k], At[m][k], acc[ai][bj][m][n], 0, 0, 0); __builtin_amdgcn_s_setprio(0); } while (0)
; #define PG8_WAIT_V(n) asm volatile("s_waitcnt vmcnt(" #n ")" ::: "memory")
; #define PG8_WAIT_L(n) asm volatile("s_waitcnt lgkmcnt(" #n ")" ::: "memory")
; #define PG8_BAR __builtin_amdgcn_s_barrier()
; #define PG8_SCHED __builtin_amdgcn_sched_barrier(0)
; template <class Epi, bool SP2, class Sched>
; __device__ __forceinline__ void gemm_phase(LAS unsigned char* lds, const Gemm g, const Sched& S, const Epi& E) {
;     ...
;             PG8_WAIT_V(8); PG8_WAIT_L(0); PG8_BAR; PG8_MMA(1, 0, At, B0); PG8_MMA(1, 1, At, B1); PG8_BAR; PG8_SCHED;
;             PG8_LDB(B0, 1, 0); PG8_LDB(B1, 1, 1); PG8_SCHED; PG8_LDA(At, 1, 0); PG8_STAGE(PG8_SA(0, 1), a2 + hstep, voffA);
;             PG8_WAIT_V(8); PG8_WAIT_L(0); PG8_BAR; PG8_MMA(0, 0, At, B0); PG8_MMA(0, 1, At, B1); PG8_BAR; PG8_SCHED;
	s_setprio 1
	v_mfma_f32_16x16x32_bf16 v[60:63], v[156:159], v[188:191], v[60:63]
	v_mfma_f32_16x16x32_bf16 v[56:59], v[164:167], v[188:191], v[56:59]
	v_mfma_f32_16x16x32_bf16 v[44:47], v[156:159], v[218:221], v[44:47]
	v_mfma_f32_16x16x32_bf16 v[40:43], v[164:167], v[218:221], v[40:43]
	v_mfma_f32_16x16x32_bf16 v[28:31], v[156:159], v[226:229], v[28:31]
	v_mfma_f32_16x16x32_bf16 v[24:27], v[164:167], v[226:229], v[24:27]
	v_mfma_f32_16x16x32_bf16 v[12:15], v[156:159], v[234:237], v[12:15]
	v_mfma_f32_16x16x32_bf16 v[8:11], v[164:167], v[234:237], v[8:11]
	v_mfma_f32_16x16x32_bf16 v[60:63], v[160:163], v[214:217], v[60:63]
	v_mfma_f32_16x16x32_bf16 v[56:59], v[168:171], v[214:217], v[56:59]
	v_mfma_f32_16x16x32_bf16 v[44:47], v[160:163], v[222:225], v[44:47]
	v_mfma_f32_16x16x32_bf16 v[40:43], v[168:171], v[222:225], v[40:43]
	v_mfma_f32_16x16x32_bf16 v[28:31], v[160:163], v[230:233], v[28:31]
	v_mfma_f32_16x16x32_bf16 v[24:27], v[168:171], v[230:233], v[24:27]
	v_mfma_f32_16x16x32_bf16 v[12:15], v[160:163], v[238:241], v[12:15]
	v_mfma_f32_16x16x32_bf16 v[8:11], v[168:171], v[238:241], v[8:11]
	v_mfma_f32_16x16x32_bf16 v[52:55], v[172:175], v[188:191], v[52:55]
	v_mfma_f32_16x16x32_bf16 v[48:51], v[180:183], v[188:191], v[48:51]
	v_mfma_f32_16x16x32_bf16 v[36:39], v[172:175], v[218:221], v[36:39]
	v_mfma_f32_16x16x32_bf16 v[32:35], v[180:183], v[218:221], v[32:35]
	v_mfma_f32_16x16x32_bf16 v[20:23], v[172:175], v[226:229], v[20:23]
	v_mfma_f32_16x16x32_bf16 v[16:19], v[180:183], v[226:229], v[16:19]
	v_mfma_f32_16x16x32_bf16 v[4:7], v[172:175], v[234:237], v[4:7]
	v_mfma_f32_16x16x32_bf16 v[0:3], v[180:183], v[234:237], v[0:3]
	v_mfma_f32_16x16x32_bf16 v[52:55], v[176:179], v[214:217], v[52:55]
	v_mfma_f32_16x16x32_bf16 v[48:51], v[184:187], v[214:217], v[48:51]
	v_mfma_f32_16x16x32_bf16 v[36:39], v[176:179], v[222:225], v[36:39]
	v_mfma_f32_16x16x32_bf16 v[32:35], v[184:187], v[222:225], v[32:35]
	v_mfma_f32_16x16x32_bf16 v[20:23], v[176:179], v[230:233], v[20:23]
	v_mfma_f32_16x16x32_bf16 v[16:19], v[184:187], v[230:233], v[16:19]
	v_mfma_f32_16x16x32_bf16 v[4:7], v[176:179], v[238:241], v[4:7]
	v_mfma_f32_16x16x32_bf16 v[0:3], v[184:187], v[238:241], v[0:3]
	s_setprio 0
	s_barrier
	s_add_i32 s19, 0, 0x18000
	v_add_u32_e32 v64, s19, v153
	s_add_i32 s20, 0, 0x1c000
	ds_read_b128 v[156:159], v64
	ds_read_b128 v[160:163], v64 offset:1024
	ds_read_b128 v[164:167], v64 offset:2048
	ds_read_b128 v[168:171], v64 offset:3072
	v_add_u32_e32 v64, s20, v153
	ds_read_b128 v[172:175], v64
	ds_read_b128 v[176:179], v64 offset:1024
	ds_read_b128 v[180:183], v64 offset:2048
	ds_read_b128 v[184:187], v64 offset:3072
	s_add_u32 s10, s10, 0x40000
	s_addc_u32 s11, s11, 0
	s_mov_b32 m0, s83
	v_lshl_add_u64 v[70:71], s[10:11], 0, v[132:133]
	ds_read_b128 v[188:191], v155 offset:32768
	ds_read_b128 v[214:217], v155 offset:33792
	ds_read_b128 v[218:221], v155 offset:34816
	ds_read_b128 v[222:225], v155 offset:35840
	ds_read_b128 v[226:229], v155 offset:36864
	ds_read_b128 v[230:233], v155 offset:37888
	ds_read_b128 v[234:237], v155 offset:38912
	ds_read_b128 v[238:241], v155 offset:39936
	global_load_lds_dwordx4 v[70:71], off
	v_lshl_add_u64 v[70:71], s[10:11], 0, v[136:137]
	s_mov_b32 m0, s74
	s_nop 0
	global_load_lds_dwordx4 v[70:71], off
	s_waitcnt vmcnt(8) lgkmcnt(0)
	s_barrier
	s_setprio 1
	v_mfma_f32_16x16x32_bf16 v[128:131], v[156:159], v[188:191], v[128:131]
	v_mfma_f32_16x16x32_bf16 v[124:127], v[164:167], v[188:191], v[124:127]
	v_mfma_f32_16x16x32_bf16 v[112:115], v[156:159], v[218:221], v[112:115]
	v_mfma_f32_16x16x32_bf16 v[108:111], v[164:167], v[218:221], v[108:111]
	v_mfma_f32_16x16x32_bf16 v[96:99], v[156:159], v[226:229], v[96:99]
	v_mfma_f32_16x16x32_bf16 v[92:95], v[164:167], v[226:229], v[92:95]
	v_mfma_f32_16x16x32_bf16 v[80:83], v[156:159], v[234:237], v[80:83]
	v_mfma_f32_16x16x32_bf16 v[76:79], v[164:167], v[234:237], v[76:79]
	v_mfma_f32_16x16x32_bf16 v[128:131], v[160:163], v[214:217], v[128:131]
	v_mfma_f32_16x16x32_bf16 v[124:127], v[168:171], v[214:217], v[124:127]
	v_mfma_f32_16x16x32_bf16 v[112:115], v[160:163], v[222:225], v[112:115]
	v_mfma_f32_16x16x32_bf16 v[108:111], v[168:171], v[222:225], v[108:111]
	v_mfma_f32_16x16x32_bf16 v[96:99], v[160:163], v[230:233], v[96:99]
	v_mfma_f32_16x16x32_bf16 v[92:95], v[168:171], v[230:233], v[92:95]
	v_mfma_f32_16x16x32_bf16 v[80:83], v[160:163], v[238:241], v[80:83]
	v_mfma_f32_16x16x32_bf16 v[76:79], v[168:171], v[238:241], v[76:79]
	v_mfma_f32_16x16x32_bf16 v[120:123], v[172:175], v[188:191], v[120:123]
	v_mfma_f32_16x16x32_bf16 v[116:119], v[180:183], v[188:191], v[116:119]
	v_mfma_f32_16x16x32_bf16 v[104:107], v[172:175], v[218:221], v[104:107]
	v_mfma_f32_16x16x32_bf16 v[100:103], v[180:183], v[218:221], v[100:103]
	v_mfma_f32_16x16x32_bf16 v[88:91], v[172:175], v[226:229], v[88:91]
	v_mfma_f32_16x16x32_bf16 v[84:87], v[180:183], v[226:229], v[84:87]
	v_mfma_f32_16x16x32_bf16 v[70:73], v[172:175], v[234:237], v[72:75]
	v_mfma_f32_16x16x32_bf16 v[66:69], v[180:183], v[234:237], v[66:69]
	v_mfma_f32_16x16x32_bf16 v[120:123], v[176:179], v[214:217], v[120:123]
	v_mfma_f32_16x16x32_bf16 v[116:119], v[184:187], v[214:217], v[116:119]
	v_mfma_f32_16x16x32_bf16 v[104:107], v[176:179], v[222:225], v[104:107]
	v_mfma_f32_16x16x32_bf16 v[100:103], v[184:187], v[222:225], v[100:103]
	v_mfma_f32_16x16x32_bf16 v[88:91], v[176:179], v[230:233], v[88:91]
	v_mfma_f32_16x16x32_bf16 v[84:87], v[184:187], v[230:233], v[84:87]
	v_mfma_f32_16x16x32_bf16 v[72:75], v[176:179], v[238:241], v[70:73]
	v_mfma_f32_16x16x32_bf16 v[68:71], v[184:187], v[238:241], v[66:69]
	s_setprio 0
	s_barrier
; #define PG8_STAGE(bufoff, gbase, voff) do { _Pragma("unroll") for (int _i = 0; _i < 2; ++_i) \
;         __builtin_amdgcn_global_load_lds((const unsigned*)((const char*)(gbase) + (voff)[_i]), (LAS unsigned*)(lds + (bufoff) + ldsw + _i * 8192), 16, 0, 0); } while (0)
; #define PG8_LDA(dst, b, h) do { _Pragma("unroll") for (int m = 0; m < 4; ++m) _Pragma("unroll") for (int k = 0; k < 2; ++k) dst[m][k] = *(const LAS bf16x8*)(lds + PG8_SA(b, h) + aoff + m * 2048 + k * 1024); } while (0)
; #define PG8_MMA(ai, bj, At, Bt) do { __builtin_amdgcn_s_setprio(1); _Pragma("unroll") for (int m = 0; m < 4; ++m) _Pragma("unroll") for (int n = 0; n < 2; ++n) _Pragma("unroll") for (int k = 0; k < 2; ++k) \
;         acc[ai][bj][m][n] = __builtin_amdgcn_mfma_f32_16x16x32_bf16(Bt[n][k], At[m][k], acc[ai][bj][m][n], 0, 0, 0); __builtin_amdgcn_s_setprio(0); } while (0)
; #define PG8_WAIT_V(n) asm volatile("s_waitcnt vmcnt(" #n ")" ::: "memory")
; #define PG8_WAIT_L(n) asm volatile("s_waitcnt lgkmcnt(" #n ")" ::: "memory")
; #define PG8_BAR __builtin_amdgcn_s_barrier()
; #define PG8_SCHED __builtin_amdgcn_sched_barrier(0)
; template <class Epi, bool SP2, class Sched>
; __device__ __forceinline__ void gemm_phase(LAS unsigned char* lds, const Gemm g, const Sched& S, const Epi& E) {
;     ...
;             if constexpr (Epi::MID) { if (t == (nt >> 1)) E.mid(acc, cur, wr, fr); }
;     ...
;             PG8_LDA(At, 1, 1); PG8_STAGE(PG8_SB(1, 0), b3, voffB); PG8_STAGE(PG8_SB(1, 1), b3 + hstepB, voffB); PG8_STAGE(PG8_SA(1, 0), a3, voffA);
;             PG8_WAIT_V(8); PG8_WAIT_L(0); PG8_BAR; PG8_MMA(1, 0, At, B0); PG8_MMA(1, 1, At, B1); PG8_BAR; PG8_SCHED;
	s_add_i32 s10, s19, s73
	v_lshl_add_u64 v[66:67], v[192:193], 0, s[66:67]
	s_mov_b32 m0, s10
	ds_read_b128 v[188:191], v155 offset:49152
	ds_read_b128 v[214:217], v155 offset:50176
	ds_read_b128 v[218:221], v155 offset:51200
	ds_read_b128 v[222:225], v155 offset:52224
	ds_read_b128 v[226:229], v155 offset:53248
	ds_read_b128 v[230:233], v155 offset:54272
	ds_read_b128 v[234:237], v155 offset:55296
	ds_read_b128 v[238:241], v155 offset:56320
	global_load_lds_dwordx4 v[66:67], off
	s_add_i32 m0, s10, 0x2000
	s_add_u32 s6, s6, 0x40080
	v_lshl_add_u64 v[66:67], v[248:249], 0, s[66:67]
	s_addc_u32 s7, s7, 0
	s_add_i32 s10, s20, s73
	global_load_lds_dwordx4 v[66:67], off
	v_lshl_add_u64 v[66:67], s[6:7], 0, v[134:135]
	s_mov_b32 m0, s10
	s_nop 0
	global_load_lds_dwordx4 v[66:67], off
	v_lshl_add_u64 v[66:67], s[6:7], 0, v[138:139]
	s_add_i32 m0, s10, 0x2000
	s_nop 0
	global_load_lds_dwordx4 v[66:67], off
	v_lshl_add_u64 v[66:67], v[250:251], 0, s[66:67]
	s_mov_b32 m0, s75
	s_nop 0
	global_load_lds_dwordx4 v[66:67], off
	v_lshl_add_u64 v[66:67], v[252:253], 0, s[66:67]
	s_mov_b32 m0, s76
	s_nop 0
	global_load_lds_dwordx4 v[66:67], off
	s_waitcnt vmcnt(8) lgkmcnt(0)
	s_barrier
	s_setprio 1
	v_mfma_f32_16x16x32_bf16 v[60:63], v[156:159], v[188:191], v[60:63]
	v_mfma_f32_16x16x32_bf16 v[56:59], v[164:167], v[188:191], v[56:59]
	v_mfma_f32_16x16x32_bf16 v[44:47], v[156:159], v[218:221], v[44:47]
	v_mfma_f32_16x16x32_bf16 v[40:43], v[164:167], v[218:221], v[40:43]
	v_mfma_f32_16x16x32_bf16 v[28:31], v[156:159], v[226:229], v[28:31]
	v_mfma_f32_16x16x32_bf16 v[24:27], v[164:167], v[226:229], v[24:27]
	v_mfma_f32_16x16x32_bf16 v[12:15], v[156:159], v[234:237], v[12:15]
	v_mfma_f32_16x16x32_bf16 v[8:11], v[164:167], v[234:237], v[8:11]
	v_mfma_f32_16x16x32_bf16 v[60:63], v[160:163], v[214:217], v[60:63]
	v_mfma_f32_16x16x32_bf16 v[56:59], v[168:171], v[214:217], v[56:59]
	v_mfma_f32_16x16x32_bf16 v[44:47], v[160:163], v[222:225], v[44:47]
	v_mfma_f32_16x16x32_bf16 v[40:43], v[168:171], v[222:225], v[40:43]
	v_mfma_f32_16x16x32_bf16 v[28:31], v[160:163], v[230:233], v[28:31]
	v_mfma_f32_16x16x32_bf16 v[24:27], v[168:171], v[230:233], v[24:27]
	v_mfma_f32_16x16x32_bf16 v[12:15], v[160:163], v[238:241], v[12:15]
	v_mfma_f32_16x16x32_bf16 v[8:11], v[168:171], v[238:241], v[8:11]
	v_mfma_f32_16x16x32_bf16 v[52:55], v[172:175], v[188:191], v[52:55]
	v_mfma_f32_16x16x32_bf16 v[48:51], v[180:183], v[188:191], v[48:51]
	v_mfma_f32_16x16x32_bf16 v[36:39], v[172:175], v[218:221], v[36:39]
	v_mfma_f32_16x16x32_bf16 v[32:35], v[180:183], v[218:221], v[32:35]
	v_mfma_f32_16x16x32_bf16 v[20:23], v[172:175], v[226:229], v[20:23]
	v_mfma_f32_16x16x32_bf16 v[16:19], v[180:183], v[226:229], v[16:19]
	v_mfma_f32_16x16x32_bf16 v[4:7], v[172:175], v[234:237], v[4:7]
	v_mfma_f32_16x16x32_bf16 v[0:3], v[180:183], v[234:237], v[0:3]
	v_mfma_f32_16x16x32_bf16 v[52:55], v[176:179], v[214:217], v[52:55]
	v_mfma_f32_16x16x32_bf16 v[48:51], v[184:187], v[214:217], v[48:51]
	v_mfma_f32_16x16x32_bf16 v[36:39], v[176:179], v[222:225], v[36:39]
	v_mfma_f32_16x16x32_bf16 v[32:35], v[184:187], v[222:225], v[32:35]
	v_mfma_f32_16x16x32_bf16 v[20:23], v[176:179], v[230:233], v[20:23]
	v_mfma_f32_16x16x32_bf16 v[16:19], v[184:187], v[230:233], v[16:19]
	v_mfma_f32_16x16x32_bf16 v[4:7], v[176:179], v[238:241], v[4:7]
	v_mfma_f32_16x16x32_bf16 v[0:3], v[184:187], v[238:241], v[0:3]
	s_setprio 0
	s_barrier
	s_add_i32 s18, s18, 2
	s_add_u32 s96, s96, 0x100
	s_addc_u32 s97, s97, 0
	s_cmp_gt_u32 s18, 13
	s_cbranch_scc1 .LBB0_676

; #define PG8_STAGE(bufoff, gbase, voff) do { _Pragma("unroll") for (int _i = 0; _i < 2; ++_i) \
;         __builtin_amdgcn_global_load_lds((const unsigned*)((const char*)(gbase) + (voff)[_i]), (LAS unsigned*)(lds + (bufoff) + ldsw + _i * 8192), 16, 0, 0); } while (0)
; #define PG8_LDA(dst, b, h) do { _Pragma("unroll") for (int m = 0; m < 4; ++m) _Pragma("unroll") for (int k = 0; k < 2; ++k) dst[m][k] = *(const LAS bf16x8*)(lds + PG8_SA(b, h) + aoff + m * 2048 + k * 1024); } while (0)
; #define PG8_LDB(dst, b, h) do { _Pragma("unroll") for (int n = 0; n < 2; ++n) _Pragma("unroll") for (int k = 0; k < 2; ++k) dst[n][k] = *(const LAS bf16x8*)(lds + PG8_SB(b, h) + boff + n * 2048 + k * 1024); } while (0)
; #define PG8_WAIT_V(n) asm volatile("s_waitcnt vmcnt(" #n ")" ::: "memory")
; #define PG8_WAIT_L(n) asm volatile("s_waitcnt lgkmcnt(" #n ")" ::: "memory")
; #define PG8_BAR __builtin_amdgcn_s_barrier()
; #define PG8_SCHED __builtin_amdgcn_sched_barrier(0)
; template <class Epi, bool SP2, class Sched>
; __device__ __forceinline__ void gemm_phase(LAS unsigned char* lds, const Gemm g, const Sched& S, const Epi& E) {
;     ...
;         const bool has_next = S.next(ui + 1, nxt);
;         const char* nA = has_next ? (const char*)g.A + (size_t)nxt.pm * tstep + nxt.ko : cA; const char* nB = has_next ? (const char*)g.Bt + (size_t)nxt.pn * tstepB + nxt.ko : cB;
;         for (int t = 0; t < nt; t += 2) {
;             const bool last = (t == nt - 2);
;             const char* a1 = cA + (size_t)(t + 1) * kstep;
;             const char* a2 = last ? nA : cA + (size_t)(t + 2) * kstep; const char* b2 = last ? nB : cB + (size_t)(t + 2) * kstep;
;             const char* a3 = a2 + kstep; const char* b3 = b2 + kstep;
;             if constexpr (Epi::MID) { if (t == (nt >> 1)) E.mid(acc, cur, wr, fr); }
;             if constexpr (SP2) {
;             PG8_LDB(B0, 0, 0); PG8_LDB(B1, 0, 1); PG8_SCHED; PG8_LDA(At, 0, 0); PG8_STAGE(PG8_SA(1, 1), a1 + hstep, voffA);
;             PG8_WAIT_V(8); PG8_WAIT_L(0); PG8_BAR; PG8_MMA(0, 0, At, B0); PG8_MMA(0, 1, At, B1); PG8_BAR; PG8_SCHED;
;             PG8_LDA(At, 0, 1); PG8_STAGE(PG8_SB(0, 0), b2, voffB); PG8_STAGE(PG8_SB(0, 1), b2 + hstepB, voffB); PG8_STAGE(PG8_SA(0, 0), a2, voffA);
;             PG8_WAIT_V(8); PG8_WAIT_L(0); PG8_BAR; PG8_MMA(1, 0, At, B0); PG8_MMA(1, 1, At, B1); PG8_BAR; PG8_SCHED;
.LBB0_715:
	s_add_u32 s6, s90, 0xfffc0080
	s_addc_u32 s7, s91, -1
	s_add_i32 s22, 0, 0x10000
	s_cmp_eq_u32 s21, 12
	s_cselect_b32 s11, s19, s7
	s_cselect_b32 s10, s33, s6
	v_add_u32_e32 v140, s22, v143
	s_cselect_b32 s7, s76, s20
	s_cselect_b32 s6, s77, s79
	s_add_i32 s24, 0, 0x14000
	ds_read_b128 v[136:139], v140
	ds_read_b128 v[146:149], v140 offset:1024
	ds_read_b128 v[150:153], v140 offset:2048
	ds_read_b128 v[154:157], v140 offset:3072
	v_add_u32_e32 v140, s24, v143
	ds_read_b128 v[158:161], v140
	ds_read_b128 v[162:165], v140 offset:1024
	ds_read_b128 v[166:169], v140 offset:2048
	ds_read_b128 v[170:173], v140 offset:3072
	v_lshl_add_u64 v[140:141], s[90:91], 0, v[134:135]
	s_add_i32 m0, s17, 0xc000
	ds_read_b128 v[174:177], v145
	ds_read_b128 v[178:181], v145 offset:1024
	ds_read_b128 v[182:185], v145 offset:2048
	ds_read_b128 v[186:189], v145 offset:3072
	ds_read_b128 v[190:193], v145 offset:4096
	ds_read_b128 v[214:217], v145 offset:5120
	ds_read_b128 v[218:221], v145 offset:6144
	ds_read_b128 v[222:225], v145 offset:7168
	global_load_lds_dwordx4 v[140:141], off
	v_lshl_add_u64 v[140:141], s[90:91], 0, v[132:133]
	s_add_i32 m0, s17, 0xe000
	s_nop 0
	global_load_lds_dwordx4 v[140:141], off
	s_waitcnt vmcnt(8) lgkmcnt(0)
	s_barrier
	s_setprio 1
	v_mfma_f32_16x16x32_bf16 v[126:129], v[136:139], v[174:177], v[126:129]
	v_mfma_f32_16x16x32_bf16 v[122:125], v[150:153], v[174:177], v[122:125]
	v_mfma_f32_16x16x32_bf16 v[110:113], v[136:139], v[182:185], v[110:113]
	v_mfma_f32_16x16x32_bf16 v[106:109], v[150:153], v[182:185], v[106:109]
	v_mfma_f32_16x16x32_bf16 v[94:97], v[136:139], v[190:193], v[94:97]
	v_mfma_f32_16x16x32_bf16 v[90:93], v[150:153], v[190:193], v[90:93]
	v_mfma_f32_16x16x32_bf16 v[78:81], v[136:139], v[218:221], v[78:81]
	v_mfma_f32_16x16x32_bf16 v[74:77], v[150:153], v[218:221], v[74:77]
	v_mfma_f32_16x16x32_bf16 v[126:129], v[146:149], v[178:181], v[126:129]
	v_mfma_f32_16x16x32_bf16 v[122:125], v[154:157], v[178:181], v[122:125]
	v_mfma_f32_16x16x32_bf16 v[110:113], v[146:149], v[186:189], v[110:113]
	v_mfma_f32_16x16x32_bf16 v[106:109], v[154:157], v[186:189], v[106:109]
	v_mfma_f32_16x16x32_bf16 v[94:97], v[146:149], v[214:217], v[94:97]
	v_mfma_f32_16x16x32_bf16 v[90:93], v[154:157], v[214:217], v[90:93]
	v_mfma_f32_16x16x32_bf16 v[78:81], v[146:149], v[222:225], v[78:81]
	v_mfma_f32_16x16x32_bf16 v[74:77], v[154:157], v[222:225], v[74:77]
	v_mfma_f32_16x16x32_bf16 v[118:121], v[158:161], v[174:177], v[118:121]
	v_mfma_f32_16x16x32_bf16 v[114:117], v[166:169], v[174:177], v[114:117]
	v_mfma_f32_16x16x32_bf16 v[102:105], v[158:161], v[182:185], v[102:105]
	v_mfma_f32_16x16x32_bf16 v[98:101], v[166:169], v[182:185], v[98:101]
	v_mfma_f32_16x16x32_bf16 v[86:89], v[158:161], v[190:193], v[86:89]
	v_mfma_f32_16x16x32_bf16 v[82:85], v[166:169], v[190:193], v[82:85]
	v_mfma_f32_16x16x32_bf16 v[70:73], v[158:161], v[218:221], v[70:73]
	v_mfma_f32_16x16x32_bf16 v[66:69], v[166:169], v[218:221], v[66:69]
	v_mfma_f32_16x16x32_bf16 v[118:121], v[162:165], v[178:181], v[118:121]
	v_mfma_f32_16x16x32_bf16 v[114:117], v[170:173], v[178:181], v[114:117]
	v_mfma_f32_16x16x32_bf16 v[102:105], v[162:165], v[186:189], v[102:105]
	v_mfma_f32_16x16x32_bf16 v[98:101], v[170:173], v[186:189], v[98:101]
	v_mfma_f32_16x16x32_bf16 v[86:89], v[162:165], v[214:217], v[86:89]
	v_mfma_f32_16x16x32_bf16 v[82:85], v[170:173], v[214:217], v[82:85]
	v_mfma_f32_16x16x32_bf16 v[70:73], v[162:165], v[222:225], v[70:73]
	v_mfma_f32_16x16x32_bf16 v[66:69], v[170:173], v[222:225], v[66:69]
	s_setprio 0
	s_barrier
	s_add_i32 s22, s22, s72
	v_lshl_add_u64 v[140:141], s[6:7], 0, v[64:65]
	s_mov_b32 m0, s22
	ds_read_b128 v[174:177], v145 offset:16384
	ds_read_b128 v[178:181], v145 offset:17408
	ds_read_b128 v[182:185], v145 offset:18432
	ds_read_b128 v[186:189], v145 offset:19456
	ds_read_b128 v[190:193], v145 offset:20480
	ds_read_b128 v[214:217], v145 offset:21504
	ds_read_b128 v[218:221], v145 offset:22528
	ds_read_b128 v[222:225], v145 offset:23552
	global_load_lds_dwordx4 v[140:141], off
	s_add_i32 m0, s22, 0x2000
	s_add_u32 s22, s6, 0x40000
	v_lshl_add_u64 v[226:227], s[6:7], 0, v[130:131]
	s_addc_u32 s23, s7, 0
	s_add_i32 s24, s24, s72
	global_load_lds_dwordx4 v[226:227], off
	v_lshl_add_u64 v[228:229], s[22:23], 0, v[64:65]
	s_mov_b32 m0, s24
	v_lshl_add_u64 v[230:231], s[10:11], 0, v[130:131]
	global_load_lds_dwordx4 v[228:229], off
	v_lshl_add_u64 v[228:229], s[22:23], 0, v[130:131]
	s_add_i32 m0, s24, 0x2000
	s_nop 0
	global_load_lds_dwordx4 v[228:229], off
	v_lshl_add_u64 v[228:229], s[10:11], 0, v[64:65]
	s_mov_b32 m0, s17
	s_nop 0
	global_load_lds_dwordx4 v[228:229], off
	s_mov_b32 m0, s73
	s_nop 0
	global_load_lds_dwordx4 v[230:231], off
	s_waitcnt vmcnt(8) lgkmcnt(0)
	s_barrier
; #define PG8_STAGE(bufoff, gbase, voff) do { _Pragma("unroll") for (int _i = 0; _i < 2; ++_i) \
;         __builtin_amdgcn_global_load_lds((const unsigned*)((const char*)(gbase) + (voff)[_i]), (LAS unsigned*)(lds + (bufoff) + ldsw + _i * 8192), 16, 0, 0); } while (0)
; #define PG8_LDA(dst, b, h) do { _Pragma("unroll") for (int m = 0; m < 4; ++m) _Pragma("unroll") for (int k = 0; k < 2; ++k) dst[m][k] = *(const LAS bf16x8*)(lds + PG8_SA(b, h) + aoff + m * 2048 + k * 1024); } while (0)
; #define PG8_LDB(dst, b, h) do { _Pragma("unroll") for (int n = 0; n < 2; ++n) _Pragma("unroll") for (int k = 0; k < 2; ++k) dst[n][k] = *(const LAS bf16x8*)(lds + PG8_SB(b, h) + boff + n * 2048 + k * 1024); } while (0)
; #define PG8_MMA(ai, bj, At, Bt) do { __builtin_amdgcn_s_setprio(1); _Pragma("unroll") for (int m = 0; m < 4; ++m) _Pragma("unroll") for (int n = 0; n < 2; ++n) _Pragma("unroll") for (int k = 0; k < 2; ++k) \
;         acc[ai][bj][m][n] = __builtin_amdgcn_mfma_f32_16x16x32_bf16(Bt[n][k], At[m][k], acc[ai][bj][m][n], 0, 0, 0); __builtin_amdgcn_s_setprio(0); } while (0)
; #define PG8_WAIT_V(n) asm volatile("s_waitcnt vmcnt(" #n ")" ::: "memory")
; #define PG8_WAIT_L(n) asm volatile("s_waitcnt lgkmcnt(" #n ")" ::: "memory")
; #define PG8_BAR __builtin_amdgcn_s_barrier()
; #define PG8_SCHED __builtin_amdgcn_sched_barrier(0)
; template <class Epi, bool SP2, class Sched>
; __device__ __forceinline__ void gemm_phase(LAS unsigned char* lds, const Gemm g, const Sched& S, const Epi& E) {
;     ...
;             PG8_WAIT_V(8); PG8_WAIT_L(0); PG8_BAR; PG8_MMA(1, 0, At, B0); PG8_MMA(1, 1, At, B1); PG8_BAR; PG8_SCHED;
;             PG8_LDB(B0, 1, 0); PG8_LDB(B1, 1, 1); PG8_SCHED; PG8_LDA(At, 1, 0); PG8_STAGE(PG8_SA(0, 1), a2 + hstep, voffA);
;             PG8_WAIT_V(8); PG8_WAIT_L(0); PG8_BAR; PG8_MMA(0, 0, At, B0); PG8_MMA(0, 1, At, B1); PG8_BAR; PG8_SCHED;
	s_setprio 1
	v_mfma_f32_16x16x32_bf16 v[60:63], v[136:139], v[174:177], v[60:63]
	v_mfma_f32_16x16x32_bf16 v[56:59], v[150:153], v[174:177], v[56:59]
	v_mfma_f32_16x16x32_bf16 v[44:47], v[136:139], v[182:185], v[44:47]
	v_mfma_f32_16x16x32_bf16 v[40:43], v[150:153], v[182:185], v[40:43]
	v_mfma_f32_16x16x32_bf16 v[28:31], v[136:139], v[190:193], v[28:31]
	v_mfma_f32_16x16x32_bf16 v[24:27], v[150:153], v[190:193], v[24:27]
	v_mfma_f32_16x16x32_bf16 v[12:15], v[136:139], v[218:221], v[12:15]
	v_mfma_f32_16x16x32_bf16 v[8:11], v[150:153], v[218:221], v[8:11]
	v_mfma_f32_16x16x32_bf16 v[60:63], v[146:149], v[178:181], v[60:63]
	v_mfma_f32_16x16x32_bf16 v[56:59], v[154:157], v[178:181], v[56:59]
	v_mfma_f32_16x16x32_bf16 v[44:47], v[146:149], v[186:189], v[44:47]
	v_mfma_f32_16x16x32_bf16 v[40:43], v[154:157], v[186:189], v[40:43]
	v_mfma_f32_16x16x32_bf16 v[28:31], v[146:149], v[214:217], v[28:31]
	v_mfma_f32_16x16x32_bf16 v[24:27], v[154:157], v[214:217], v[24:27]
	v_mfma_f32_16x16x32_bf16 v[12:15], v[146:149], v[222:225], v[12:15]
	v_mfma_f32_16x16x32_bf16 v[8:11], v[154:157], v[222:225], v[8:11]
	v_mfma_f32_16x16x32_bf16 v[52:55], v[158:161], v[174:177], v[52:55]
	v_mfma_f32_16x16x32_bf16 v[48:51], v[166:169], v[174:177], v[48:51]
	v_mfma_f32_16x16x32_bf16 v[36:39], v[158:161], v[182:185], v[36:39]
	v_mfma_f32_16x16x32_bf16 v[32:35], v[166:169], v[182:185], v[32:35]
	v_mfma_f32_16x16x32_bf16 v[20:23], v[158:161], v[190:193], v[20:23]
	v_mfma_f32_16x16x32_bf16 v[16:19], v[166:169], v[190:193], v[16:19]
	v_mfma_f32_16x16x32_bf16 v[4:7], v[158:161], v[218:221], v[4:7]
	v_mfma_f32_16x16x32_bf16 v[0:3], v[166:169], v[218:221], v[0:3]
	v_mfma_f32_16x16x32_bf16 v[52:55], v[162:165], v[178:181], v[52:55]
	v_mfma_f32_16x16x32_bf16 v[48:51], v[170:173], v[178:181], v[48:51]
	v_mfma_f32_16x16x32_bf16 v[36:39], v[162:165], v[186:189], v[36:39]
	v_mfma_f32_16x16x32_bf16 v[32:35], v[170:173], v[186:189], v[32:35]
	v_mfma_f32_16x16x32_bf16 v[20:23], v[162:165], v[214:217], v[20:23]
	v_mfma_f32_16x16x32_bf16 v[16:19], v[170:173], v[214:217], v[16:19]
	v_mfma_f32_16x16x32_bf16 v[4:7], v[162:165], v[222:225], v[4:7]
	v_mfma_f32_16x16x32_bf16 v[0:3], v[170:173], v[222:225], v[0:3]
	s_setprio 0
	s_barrier
	s_add_i32 s22, 0, 0x18000
	s_add_i32 s23, 0, 0x1c000
	v_add_u32_e32 v154, s22, v143
	v_add_u32_e32 v170, s23, v143
	ds_read_b128 v[136:139], v154
	ds_read_b128 v[146:149], v154 offset:1024
	ds_read_b128 v[150:153], v154 offset:2048
	ds_read_b128 v[154:157], v154 offset:3072
	ds_read_b128 v[158:161], v170
	ds_read_b128 v[162:165], v170 offset:1024
	ds_read_b128 v[166:169], v170 offset:2048
	ds_read_b128 v[170:173], v170 offset:3072
	s_add_u32 s10, s10, 0x40000
	s_addc_u32 s11, s11, 0
	s_mov_b32 m0, s74
	v_lshl_add_u64 v[232:233], s[10:11], 0, v[64:65]
	ds_read_b128 v[174:177], v145 offset:32768
	ds_read_b128 v[178:181], v145 offset:33792
	ds_read_b128 v[182:185], v145 offset:34816
	ds_read_b128 v[186:189], v145 offset:35840
	ds_read_b128 v[190:193], v145 offset:36864
	ds_read_b128 v[214:217], v145 offset:37888
	ds_read_b128 v[218:221], v145 offset:38912
	ds_read_b128 v[222:225], v145 offset:39936
	global_load_lds_dwordx4 v[232:233], off
	v_lshl_add_u64 v[232:233], s[10:11], 0, v[130:131]
	s_mov_b32 m0, s75
	s_nop 0
	global_load_lds_dwordx4 v[232:233], off
	s_waitcnt vmcnt(8) lgkmcnt(0)
	s_barrier
	s_setprio 1
	v_mfma_f32_16x16x32_bf16 v[126:129], v[136:139], v[174:177], v[126:129]
	v_mfma_f32_16x16x32_bf16 v[122:125], v[150:153], v[174:177], v[122:125]
	v_mfma_f32_16x16x32_bf16 v[110:113], v[136:139], v[182:185], v[110:113]
	v_mfma_f32_16x16x32_bf16 v[106:109], v[150:153], v[182:185], v[106:109]
	v_mfma_f32_16x16x32_bf16 v[94:97], v[136:139], v[190:193], v[94:97]
	v_mfma_f32_16x16x32_bf16 v[90:93], v[150:153], v[190:193], v[90:93]
	v_mfma_f32_16x16x32_bf16 v[78:81], v[136:139], v[218:221], v[78:81]
	v_mfma_f32_16x16x32_bf16 v[74:77], v[150:153], v[218:221], v[74:77]
	v_mfma_f32_16x16x32_bf16 v[126:129], v[146:149], v[178:181], v[126:129]
	v_mfma_f32_16x16x32_bf16 v[122:125], v[154:157], v[178:181], v[122:125]
	v_mfma_f32_16x16x32_bf16 v[110:113], v[146:149], v[186:189], v[110:113]
	v_mfma_f32_16x16x32_bf16 v[106:109], v[154:157], v[186:189], v[106:109]
	v_mfma_f32_16x16x32_bf16 v[94:97], v[146:149], v[214:217], v[94:97]
	v_mfma_f32_16x16x32_bf16 v[90:93], v[154:157], v[214:217], v[90:93]
	v_mfma_f32_16x16x32_bf16 v[78:81], v[146:149], v[222:225], v[78:81]
	v_mfma_f32_16x16x32_bf16 v[74:77], v[154:157], v[222:225], v[74:77]
	v_mfma_f32_16x16x32_bf16 v[118:121], v[158:161], v[174:177], v[118:121]
	v_mfma_f32_16x16x32_bf16 v[114:117], v[166:169], v[174:177], v[114:117]
	v_mfma_f32_16x16x32_bf16 v[102:105], v[158:161], v[182:185], v[102:105]
	v_mfma_f32_16x16x32_bf16 v[98:101], v[166:169], v[182:185], v[98:101]
	v_mfma_f32_16x16x32_bf16 v[86:89], v[158:161], v[190:193], v[86:89]
	v_mfma_f32_16x16x32_bf16 v[82:85], v[166:169], v[190:193], v[82:85]
	v_mfma_f32_16x16x32_bf16 v[70:73], v[158:161], v[218:221], v[70:73]
	v_mfma_f32_16x16x32_bf16 v[66:69], v[166:169], v[218:221], v[66:69]
	v_mfma_f32_16x16x32_bf16 v[118:121], v[162:165], v[178:181], v[118:121]
	v_mfma_f32_16x16x32_bf16 v[114:117], v[170:173], v[178:181], v[114:117]
	v_mfma_f32_16x16x32_bf16 v[102:105], v[162:165], v[186:189], v[102:105]
	v_mfma_f32_16x16x32_bf16 v[98:101], v[170:173], v[186:189], v[98:101]
	v_mfma_f32_16x16x32_bf16 v[86:89], v[162:165], v[214:217], v[86:89]
	v_mfma_f32_16x16x32_bf16 v[82:85], v[170:173], v[214:217], v[82:85]
	v_mfma_f32_16x16x32_bf16 v[70:73], v[162:165], v[222:225], v[70:73]
	v_mfma_f32_16x16x32_bf16 v[66:69], v[170:173], v[222:225], v[66:69]
	s_setprio 0
	s_barrier
; #define PG8_STAGE(bufoff, gbase, voff) do { _Pragma("unroll") for (int _i = 0; _i < 2; ++_i) \
;         __builtin_amdgcn_global_load_lds((const unsigned*)((const char*)(gbase) + (voff)[_i]), (LAS unsigned*)(lds + (bufoff) + ldsw + _i * 8192), 16, 0, 0); } while (0)
; #define PG8_LDA(dst, b, h) do { _Pragma("unroll") for (int m = 0; m < 4; ++m) _Pragma("unroll") for (int k = 0; k < 2; ++k) dst[m][k] = *(const LAS bf16x8*)(lds + PG8_SA(b, h) + aoff + m * 2048 + k * 1024); } while (0)
; #define PG8_MMA(ai, bj, At, Bt) do { __builtin_amdgcn_s_setprio(1); _Pragma("unroll") for (int m = 0; m < 4; ++m) _Pragma("unroll") for (int n = 0; n < 2; ++n) _Pragma("unroll") for (int k = 0; k < 2; ++k) \
;         acc[ai][bj][m][n] = __builtin_amdgcn_mfma_f32_16x16x32_bf16(Bt[n][k], At[m][k], acc[ai][bj][m][n], 0, 0, 0); __builtin_amdgcn_s_setprio(0); } while (0)
; #define PG8_WAIT_V(n) asm volatile("s_waitcnt vmcnt(" #n ")" ::: "memory")
; #define PG8_WAIT_L(n) asm volatile("s_waitcnt lgkmcnt(" #n ")" ::: "memory")
; #define PG8_BAR __builtin_amdgcn_s_barrier()
; #define PG8_SCHED __builtin_amdgcn_sched_barrier(0)
; template <class Epi, bool SP2, class Sched>
; __device__ __forceinline__ void gemm_phase(LAS unsigned char* lds, const Gemm g, const Sched& S, const Epi& E) {
;     ...
;             PG8_LDA(At, 1, 1); PG8_STAGE(PG8_SB(1, 0), b3, voffB); PG8_STAGE(PG8_SB(1, 1), b3 + hstepB, voffB); PG8_STAGE(PG8_SA(1, 0), a3, voffA);
;             PG8_WAIT_V(8); PG8_WAIT_L(0); PG8_BAR; PG8_MMA(1, 0, At, B0); PG8_MMA(1, 1, At, B1); PG8_BAR; PG8_SCHED;
;     ...
;         if (wr == 0) PG8_BAR;
	s_add_i32 s10, s22, s72
	v_lshl_add_u64 v[140:141], v[140:141], 0, s[66:67]
	s_mov_b32 m0, s10
	ds_read_b128 v[174:177], v145 offset:49152
	ds_read_b128 v[178:181], v145 offset:50176
	ds_read_b128 v[182:185], v145 offset:51200
	ds_read_b128 v[186:189], v145 offset:52224
	ds_read_b128 v[190:193], v145 offset:53248
	ds_read_b128 v[214:217], v145 offset:54272
	ds_read_b128 v[218:221], v145 offset:55296
	ds_read_b128 v[222:225], v145 offset:56320
	global_load_lds_dwordx4 v[140:141], off
	s_add_i32 m0, s10, 0x2000
	s_add_u32 s6, s6, 0x40080
	v_lshl_add_u64 v[140:141], v[226:227], 0, s[66:67]
	s_addc_u32 s7, s7, 0
	s_add_i32 s10, s23, s72
	global_load_lds_dwordx4 v[140:141], off
	v_lshl_add_u64 v[140:141], s[6:7], 0, v[64:65]
	s_mov_b32 m0, s10
	s_nop 0
	global_load_lds_dwordx4 v[140:141], off
	v_lshl_add_u64 v[140:141], s[6:7], 0, v[130:131]
	s_add_i32 m0, s10, 0x2000
	s_nop 0
	global_load_lds_dwordx4 v[140:141], off
	v_lshl_add_u64 v[140:141], v[228:229], 0, s[66:67]
	s_mov_b32 m0, s12
	s_nop 0
	global_load_lds_dwordx4 v[140:141], off
	v_lshl_add_u64 v[140:141], v[230:231], 0, s[66:67]
	s_mov_b32 m0, s13
	s_nop 0
	global_load_lds_dwordx4 v[140:141], off
	s_waitcnt vmcnt(8) lgkmcnt(0)
	s_barrier
	s_setprio 1
	v_mfma_f32_16x16x32_bf16 v[60:63], v[136:139], v[174:177], v[60:63]
	v_mfma_f32_16x16x32_bf16 v[56:59], v[150:153], v[174:177], v[56:59]
	v_mfma_f32_16x16x32_bf16 v[44:47], v[136:139], v[182:185], v[44:47]
	v_mfma_f32_16x16x32_bf16 v[40:43], v[150:153], v[182:185], v[40:43]
	v_mfma_f32_16x16x32_bf16 v[28:31], v[136:139], v[190:193], v[28:31]
	v_mfma_f32_16x16x32_bf16 v[24:27], v[150:153], v[190:193], v[24:27]
	v_mfma_f32_16x16x32_bf16 v[12:15], v[136:139], v[218:221], v[12:15]
	v_mfma_f32_16x16x32_bf16 v[8:11], v[150:153], v[218:221], v[8:11]
	v_mfma_f32_16x16x32_bf16 v[60:63], v[146:149], v[178:181], v[60:63]
	v_mfma_f32_16x16x32_bf16 v[56:59], v[154:157], v[178:181], v[56:59]
	v_mfma_f32_16x16x32_bf16 v[44:47], v[146:149], v[186:189], v[44:47]
	v_mfma_f32_16x16x32_bf16 v[40:43], v[154:157], v[186:189], v[40:43]
	v_mfma_f32_16x16x32_bf16 v[28:31], v[146:149], v[214:217], v[28:31]
	v_mfma_f32_16x16x32_bf16 v[24:27], v[154:157], v[214:217], v[24:27]
	v_mfma_f32_16x16x32_bf16 v[12:15], v[146:149], v[222:225], v[12:15]
	v_mfma_f32_16x16x32_bf16 v[8:11], v[154:157], v[222:225], v[8:11]
	v_mfma_f32_16x16x32_bf16 v[52:55], v[158:161], v[174:177], v[52:55]
	v_mfma_f32_16x16x32_bf16 v[48:51], v[166:169], v[174:177], v[48:51]
	v_mfma_f32_16x16x32_bf16 v[36:39], v[158:161], v[182:185], v[36:39]
	v_mfma_f32_16x16x32_bf16 v[32:35], v[166:169], v[182:185], v[32:35]
	v_mfma_f32_16x16x32_bf16 v[20:23], v[158:161], v[190:193], v[20:23]
	v_mfma_f32_16x16x32_bf16 v[16:19], v[166:169], v[190:193], v[16:19]
	v_mfma_f32_16x16x32_bf16 v[4:7], v[158:161], v[218:221], v[4:7]
	v_mfma_f32_16x16x32_bf16 v[0:3], v[166:169], v[218:221], v[0:3]
	v_mfma_f32_16x16x32_bf16 v[52:55], v[162:165], v[178:181], v[52:55]
	v_mfma_f32_16x16x32_bf16 v[48:51], v[170:173], v[178:181], v[48:51]
	v_mfma_f32_16x16x32_bf16 v[36:39], v[162:165], v[186:189], v[36:39]
	v_mfma_f32_16x16x32_bf16 v[32:35], v[170:173], v[186:189], v[32:35]
	v_mfma_f32_16x16x32_bf16 v[20:23], v[162:165], v[214:217], v[20:23]
	v_mfma_f32_16x16x32_bf16 v[16:19], v[170:173], v[214:217], v[16:19]
	v_mfma_f32_16x16x32_bf16 v[4:7], v[162:165], v[222:225], v[4:7]
	v_mfma_f32_16x16x32_bf16 v[0:3], v[170:173], v[222:225], v[0:3]
	s_setprio 0
	s_barrier
	s_add_i32 s21, s21, 2
	s_add_u32 s79, s79, 0x100
	s_addc_u32 s20, s20, 0
	s_add_u32 s90, s90, 0x100
	s_addc_u32 s91, s91, 0
	s_cmp_gt_u32 s21, 13
	s_cbranch_scc0 .LBB0_715
	s_and_b64 vcc, exec, s[60:61]
	s_cbranch_vccz .LBB0_718
	s_barrier

; #define PG8_STAGE(bufoff, gbase, voff) do { _Pragma("unroll") for (int _i = 0; _i < 2; ++_i) \
;         __builtin_amdgcn_global_load_lds((const unsigned*)((const char*)(gbase) + (voff)[_i]), (LAS unsigned*)(lds + (bufoff) + ldsw + _i * 8192), 16, 0, 0); } while (0)
; #define PG8_LDA(dst, b, h) do { _Pragma("unroll") for (int m = 0; m < 4; ++m) _Pragma("unroll") for (int k = 0; k < 2; ++k) dst[m][k] = *(const LAS bf16x8*)(lds + PG8_SA(b, h) + aoff + m * 2048 + k * 1024); } while (0)
; #define PG8_LDB(dst, b, h) do { _Pragma("unroll") for (int n = 0; n < 2; ++n) _Pragma("unroll") for (int k = 0; k < 2; ++k) dst[n][k] = *(const LAS bf16x8*)(lds + PG8_SB(b, h) + boff + n * 2048 + k * 1024); } while (0)
; #define PG8_WAIT_V(n) asm volatile("s_waitcnt vmcnt(" #n ")" ::: "memory")
; #define PG8_WAIT_L(n) asm volatile("s_waitcnt lgkmcnt(" #n ")" ::: "memory")
; #define PG8_BAR __builtin_amdgcn_s_barrier()
; #define PG8_SCHED __builtin_amdgcn_sched_barrier(0)
; template <class Epi, bool SP2, class Sched>
; __device__ __forceinline__ void gemm_phase(LAS unsigned char* lds, const Gemm g, const Sched& S, const Epi& E) {
;     ...
;         const bool has_next = S.next(ui + 1, nxt);
;         const char* nA = has_next ? (const char*)g.A + (size_t)nxt.pm * tstep + nxt.ko : cA; const char* nB = has_next ? (const char*)g.Bt + (size_t)nxt.pn * tstepB + nxt.ko : cB;
;         for (int t = 0; t < nt; t += 2) {
;             const bool last = (t == nt - 2);
;             const char* a1 = cA + (size_t)(t + 1) * kstep;
;             const char* a2 = last ? nA : cA + (size_t)(t + 2) * kstep; const char* b2 = last ? nB : cB + (size_t)(t + 2) * kstep;
;             const char* a3 = a2 + kstep; const char* b3 = b2 + kstep;
;             if constexpr (Epi::MID) { if (t == (nt >> 1)) E.mid(acc, cur, wr, fr); }
;             if constexpr (SP2) {
;             PG8_LDB(B0, 0, 0); PG8_LDB(B1, 0, 1); PG8_SCHED; PG8_LDA(At, 0, 0); PG8_STAGE(PG8_SA(1, 1), a1 + hstep, voffA);
;             PG8_WAIT_V(8); PG8_WAIT_L(0); PG8_BAR; PG8_MMA(0, 0, At, B0); PG8_MMA(0, 1, At, B1); PG8_BAR; PG8_SCHED;
;             PG8_LDA(At, 0, 1); PG8_STAGE(PG8_SB(0, 0), b2, voffB); PG8_STAGE(PG8_SB(0, 1), b2 + hstepB, voffB); PG8_STAGE(PG8_SA(0, 0), a2, voffA);
;             PG8_WAIT_V(8); PG8_WAIT_L(0); PG8_BAR; PG8_MMA(1, 0, At, B0); PG8_MMA(1, 1, At, B1); PG8_BAR; PG8_SCHED;
.LBB0_783:
	s_add_u32 s6, s88, 0xfffc0080
	s_addc_u32 s7, s89, -1
	s_add_i32 s22, 0, 0x10000
	s_cmp_eq_u32 s21, 12
	s_cselect_b32 s11, s61, s7
	s_cselect_b32 s10, s74, s6
	s_cselect_b32 s7, s59, s20
	s_cselect_b32 s6, s75, s76
	s_add_i32 s24, 0, 0x14000
	v_add_u32_e32 v156, s22, v145
	v_add_u32_e32 v172, s24, v145
	ds_read_b128 v[140:143], v156
	ds_read_b128 v[148:151], v156 offset:1024
	ds_read_b128 v[152:155], v156 offset:2048
	ds_read_b128 v[156:159], v156 offset:3072
	ds_read_b128 v[160:163], v172
	ds_read_b128 v[164:167], v172 offset:1024
	ds_read_b128 v[168:171], v172 offset:2048
	ds_read_b128 v[172:175], v172 offset:3072
	v_lshl_add_u64 v[192:193], s[88:89], 0, v[138:139]
	s_add_i32 m0, s12, 0xc000
	ds_read_b128 v[176:179], v147
	ds_read_b128 v[180:183], v147 offset:1024
	ds_read_b128 v[184:187], v147 offset:2048
	ds_read_b128 v[188:191], v147 offset:3072
	ds_read_b128 v[214:217], v147 offset:4096
	ds_read_b128 v[218:221], v147 offset:5120
	ds_read_b128 v[222:225], v147 offset:6144
	ds_read_b128 v[226:229], v147 offset:7168
	global_load_lds_dwordx4 v[192:193], off
	v_lshl_add_u64 v[192:193], s[88:89], 0, v[136:137]
	s_add_i32 m0, s12, 0xe000
	s_nop 0
	global_load_lds_dwordx4 v[192:193], off
	s_waitcnt vmcnt(8) lgkmcnt(0)
	s_barrier
	s_setprio 1
	v_mfma_f32_16x16x32_bf16 v[126:129], v[140:143], v[176:179], v[126:129]
	v_mfma_f32_16x16x32_bf16 v[122:125], v[152:155], v[176:179], v[122:125]
	v_mfma_f32_16x16x32_bf16 v[110:113], v[140:143], v[184:187], v[110:113]
	v_mfma_f32_16x16x32_bf16 v[106:109], v[152:155], v[184:187], v[106:109]
	v_mfma_f32_16x16x32_bf16 v[94:97], v[140:143], v[214:217], v[94:97]
	v_mfma_f32_16x16x32_bf16 v[90:93], v[152:155], v[214:217], v[90:93]
	v_mfma_f32_16x16x32_bf16 v[78:81], v[140:143], v[222:225], v[78:81]
	v_mfma_f32_16x16x32_bf16 v[74:77], v[152:155], v[222:225], v[74:77]
	v_mfma_f32_16x16x32_bf16 v[126:129], v[148:151], v[180:183], v[126:129]
	v_mfma_f32_16x16x32_bf16 v[122:125], v[156:159], v[180:183], v[122:125]
	v_mfma_f32_16x16x32_bf16 v[110:113], v[148:151], v[188:191], v[110:113]
	v_mfma_f32_16x16x32_bf16 v[106:109], v[156:159], v[188:191], v[106:109]
	v_mfma_f32_16x16x32_bf16 v[94:97], v[148:151], v[218:221], v[94:97]
	v_mfma_f32_16x16x32_bf16 v[90:93], v[156:159], v[218:221], v[90:93]
	v_mfma_f32_16x16x32_bf16 v[78:81], v[148:151], v[226:229], v[78:81]
	v_mfma_f32_16x16x32_bf16 v[74:77], v[156:159], v[226:229], v[74:77]
	v_mfma_f32_16x16x32_bf16 v[118:121], v[160:163], v[176:179], v[118:121]
	v_mfma_f32_16x16x32_bf16 v[114:117], v[168:171], v[176:179], v[114:117]
	v_mfma_f32_16x16x32_bf16 v[102:105], v[160:163], v[184:187], v[102:105]
	v_mfma_f32_16x16x32_bf16 v[98:101], v[168:171], v[184:187], v[98:101]
	v_mfma_f32_16x16x32_bf16 v[86:89], v[160:163], v[214:217], v[86:89]
	v_mfma_f32_16x16x32_bf16 v[82:85], v[168:171], v[214:217], v[82:85]
	v_mfma_f32_16x16x32_bf16 v[70:73], v[160:163], v[222:225], v[70:73]
	v_mfma_f32_16x16x32_bf16 v[66:69], v[168:171], v[222:225], v[66:69]
	v_mfma_f32_16x16x32_bf16 v[118:121], v[164:167], v[180:183], v[118:121]
	v_mfma_f32_16x16x32_bf16 v[114:117], v[172:175], v[180:183], v[114:117]
	v_mfma_f32_16x16x32_bf16 v[102:105], v[164:167], v[188:191], v[102:105]
	v_mfma_f32_16x16x32_bf16 v[98:101], v[172:175], v[188:191], v[98:101]
	v_mfma_f32_16x16x32_bf16 v[86:89], v[164:167], v[218:221], v[86:89]
	v_mfma_f32_16x16x32_bf16 v[82:85], v[172:175], v[218:221], v[82:85]
	v_mfma_f32_16x16x32_bf16 v[70:73], v[164:167], v[226:229], v[70:73]
	v_mfma_f32_16x16x32_bf16 v[66:69], v[172:175], v[226:229], v[66:69]
	s_setprio 0
	s_barrier
	s_add_i32 s22, s22, s69
	v_lshl_add_u64 v[192:193], s[6:7], 0, v[64:65]
	s_mov_b32 m0, s22
	ds_read_b128 v[176:179], v147 offset:16384
	ds_read_b128 v[180:183], v147 offset:17408
	ds_read_b128 v[184:187], v147 offset:18432
	ds_read_b128 v[188:191], v147 offset:19456
	ds_read_b128 v[214:217], v147 offset:20480
	ds_read_b128 v[218:221], v147 offset:21504
	ds_read_b128 v[222:225], v147 offset:22528
	ds_read_b128 v[226:229], v147 offset:23552
	global_load_lds_dwordx4 v[192:193], off
	s_add_i32 m0, s22, 0x2000
	s_add_u32 s22, s6, 0x40000
	v_lshl_add_u64 v[230:231], s[6:7], 0, v[130:131]
	s_addc_u32 s23, s7, 0
	s_add_i32 s24, s24, s69
	global_load_lds_dwordx4 v[230:231], off
	v_lshl_add_u64 v[232:233], s[22:23], 0, v[64:65]
	s_mov_b32 m0, s24
	v_lshl_add_u64 v[234:235], s[10:11], 0, v[132:133]
	global_load_lds_dwordx4 v[232:233], off
	v_lshl_add_u64 v[232:233], s[22:23], 0, v[130:131]
	s_add_i32 m0, s24, 0x2000
	s_nop 0
	global_load_lds_dwordx4 v[232:233], off
	v_lshl_add_u64 v[232:233], s[10:11], 0, v[134:135]
	s_mov_b32 m0, s12
	s_nop 0
	global_load_lds_dwordx4 v[232:233], off
	s_mov_b32 m0, s13
	s_nop 0
	global_load_lds_dwordx4 v[234:235], off
	s_waitcnt vmcnt(8) lgkmcnt(0)
	s_barrier
; #define PG8_STAGE(bufoff, gbase, voff) do { _Pragma("unroll") for (int _i = 0; _i < 2; ++_i) \
;         __builtin_amdgcn_global_load_lds((const unsigned*)((const char*)(gbase) + (voff)[_i]), (LAS unsigned*)(lds + (bufoff) + ldsw + _i * 8192), 16, 0, 0); } while (0)
; #define PG8_LDA(dst, b, h) do { _Pragma("unroll") for (int m = 0; m < 4; ++m) _Pragma("unroll") for (int k = 0; k < 2; ++k) dst[m][k] = *(const LAS bf16x8*)(lds + PG8_SA(b, h) + aoff + m * 2048 + k * 1024); } while (0)
; #define PG8_LDB(dst, b, h) do { _Pragma("unroll") for (int n = 0; n < 2; ++n) _Pragma("unroll") for (int k = 0; k < 2; ++k) dst[n][k] = *(const LAS bf16x8*)(lds + PG8_SB(b, h) + boff + n * 2048 + k * 1024); } while (0)
; #define PG8_MMA(ai, bj, At, Bt) do { __builtin_amdgcn_s_setprio(1); _Pragma("unroll") for (int m = 0; m < 4; ++m) _Pragma("unroll") for (int n = 0; n < 2; ++n) _Pragma("unroll") for (int k = 0; k < 2; ++k) \
;         acc[ai][bj][m][n] = __builtin_amdgcn_mfma_f32_16x16x32_bf16(Bt[n][k], At[m][k], acc[ai][bj][m][n], 0, 0, 0); __builtin_amdgcn_s_setprio(0); } while (0)
; #define PG8_WAIT_V(n) asm volatile("s_waitcnt vmcnt(" #n ")" ::: "memory")
; #define PG8_WAIT_L(n) asm volatile("s_waitcnt lgkmcnt(" #n ")" ::: "memory")
; #define PG8_BAR __builtin_amdgcn_s_barrier()
; #define PG8_SCHED __builtin_amdgcn_sched_barrier(0)
; template <class Epi, bool SP2, class Sched>
; __device__ __forceinline__ void gemm_phase(LAS unsigned char* lds, const Gemm g, const Sched& S, const Epi& E) {
;     ...
;             PG8_WAIT_V(8); PG8_WAIT_L(0); PG8_BAR; PG8_MMA(1, 0, At, B0); PG8_MMA(1, 1, At, B1); PG8_BAR; PG8_SCHED;
;             PG8_LDB(B0, 1, 0); PG8_LDB(B1, 1, 1); PG8_SCHED; PG8_LDA(At, 1, 0); PG8_STAGE(PG8_SA(0, 1), a2 + hstep, voffA);
;             PG8_WAIT_V(8); PG8_WAIT_L(0); PG8_BAR; PG8_MMA(0, 0, At, B0); PG8_MMA(0, 1, At, B1); PG8_BAR; PG8_SCHED;
	s_setprio 1
	v_mfma_f32_16x16x32_bf16 v[60:63], v[140:143], v[176:179], v[60:63]
	v_mfma_f32_16x16x32_bf16 v[56:59], v[152:155], v[176:179], v[56:59]
	v_mfma_f32_16x16x32_bf16 v[44:47], v[140:143], v[184:187], v[44:47]
	v_mfma_f32_16x16x32_bf16 v[40:43], v[152:155], v[184:187], v[40:43]
	v_mfma_f32_16x16x32_bf16 v[28:31], v[140:143], v[214:217], v[28:31]
	v_mfma_f32_16x16x32_bf16 v[24:27], v[152:155], v[214:217], v[24:27]
	v_mfma_f32_16x16x32_bf16 v[12:15], v[140:143], v[222:225], v[12:15]
	v_mfma_f32_16x16x32_bf16 v[8:11], v[152:155], v[222:225], v[8:11]
	v_mfma_f32_16x16x32_bf16 v[60:63], v[148:151], v[180:183], v[60:63]
	v_mfma_f32_16x16x32_bf16 v[56:59], v[156:159], v[180:183], v[56:59]
	v_mfma_f32_16x16x32_bf16 v[44:47], v[148:151], v[188:191], v[44:47]
	v_mfma_f32_16x16x32_bf16 v[40:43], v[156:159], v[188:191], v[40:43]
	v_mfma_f32_16x16x32_bf16 v[28:31], v[148:151], v[218:221], v[28:31]
	v_mfma_f32_16x16x32_bf16 v[24:27], v[156:159], v[218:221], v[24:27]
	v_mfma_f32_16x16x32_bf16 v[12:15], v[148:151], v[226:229], v[12:15]
	v_mfma_f32_16x16x32_bf16 v[8:11], v[156:159], v[226:229], v[8:11]
	v_mfma_f32_16x16x32_bf16 v[52:55], v[160:163], v[176:179], v[52:55]
	v_mfma_f32_16x16x32_bf16 v[48:51], v[168:171], v[176:179], v[48:51]
	v_mfma_f32_16x16x32_bf16 v[36:39], v[160:163], v[184:187], v[36:39]
	v_mfma_f32_16x16x32_bf16 v[32:35], v[168:171], v[184:187], v[32:35]
	v_mfma_f32_16x16x32_bf16 v[20:23], v[160:163], v[214:217], v[20:23]
	v_mfma_f32_16x16x32_bf16 v[16:19], v[168:171], v[214:217], v[16:19]
	v_mfma_f32_16x16x32_bf16 v[4:7], v[160:163], v[222:225], v[4:7]
	v_mfma_f32_16x16x32_bf16 v[0:3], v[168:171], v[222:225], v[0:3]
	v_mfma_f32_16x16x32_bf16 v[52:55], v[164:167], v[180:183], v[52:55]
	v_mfma_f32_16x16x32_bf16 v[48:51], v[172:175], v[180:183], v[48:51]
	v_mfma_f32_16x16x32_bf16 v[36:39], v[164:167], v[188:191], v[36:39]
	v_mfma_f32_16x16x32_bf16 v[32:35], v[172:175], v[188:191], v[32:35]
	v_mfma_f32_16x16x32_bf16 v[20:23], v[164:167], v[218:221], v[20:23]
	v_mfma_f32_16x16x32_bf16 v[16:19], v[172:175], v[218:221], v[16:19]
	v_mfma_f32_16x16x32_bf16 v[4:7], v[164:167], v[226:229], v[4:7]
	v_mfma_f32_16x16x32_bf16 v[0:3], v[172:175], v[226:229], v[0:3]
	s_setprio 0
	s_barrier
	s_add_i32 s22, 0, 0x18000
	s_add_i32 s23, 0, 0x1c000
	v_add_u32_e32 v156, s22, v145
	v_add_u32_e32 v172, s23, v145
	ds_read_b128 v[140:143], v156
	ds_read_b128 v[148:151], v156 offset:1024
	ds_read_b128 v[152:155], v156 offset:2048
	ds_read_b128 v[156:159], v156 offset:3072
	ds_read_b128 v[160:163], v172
	ds_read_b128 v[164:167], v172 offset:1024
	ds_read_b128 v[168:171], v172 offset:2048
	ds_read_b128 v[172:175], v172 offset:3072
	s_add_u32 s10, s10, 0x40000
	s_addc_u32 s11, s11, 0
	s_mov_b32 m0, s14
	v_lshl_add_u64 v[236:237], s[10:11], 0, v[134:135]
	ds_read_b128 v[176:179], v147 offset:32768
	ds_read_b128 v[180:183], v147 offset:33792
	ds_read_b128 v[184:187], v147 offset:34816
	ds_read_b128 v[188:191], v147 offset:35840
	ds_read_b128 v[214:217], v147 offset:36864
	ds_read_b128 v[218:221], v147 offset:37888
	ds_read_b128 v[222:225], v147 offset:38912
	ds_read_b128 v[226:229], v147 offset:39936
	global_load_lds_dwordx4 v[236:237], off
	v_lshl_add_u64 v[236:237], s[10:11], 0, v[132:133]
	s_mov_b32 m0, s15
	s_nop 0
	global_load_lds_dwordx4 v[236:237], off
	s_waitcnt vmcnt(8) lgkmcnt(0)
	s_barrier
	s_setprio 1
	v_mfma_f32_16x16x32_bf16 v[126:129], v[140:143], v[176:179], v[126:129]
	v_mfma_f32_16x16x32_bf16 v[122:125], v[152:155], v[176:179], v[122:125]
	v_mfma_f32_16x16x32_bf16 v[110:113], v[140:143], v[184:187], v[110:113]
	v_mfma_f32_16x16x32_bf16 v[106:109], v[152:155], v[184:187], v[106:109]
	v_mfma_f32_16x16x32_bf16 v[94:97], v[140:143], v[214:217], v[94:97]
	v_mfma_f32_16x16x32_bf16 v[90:93], v[152:155], v[214:217], v[90:93]
	v_mfma_f32_16x16x32_bf16 v[78:81], v[140:143], v[222:225], v[78:81]
	v_mfma_f32_16x16x32_bf16 v[74:77], v[152:155], v[222:225], v[74:77]
	v_mfma_f32_16x16x32_bf16 v[126:129], v[148:151], v[180:183], v[126:129]
	v_mfma_f32_16x16x32_bf16 v[122:125], v[156:159], v[180:183], v[122:125]
	v_mfma_f32_16x16x32_bf16 v[110:113], v[148:151], v[188:191], v[110:113]
	v_mfma_f32_16x16x32_bf16 v[106:109], v[156:159], v[188:191], v[106:109]
	v_mfma_f32_16x16x32_bf16 v[94:97], v[148:151], v[218:221], v[94:97]
	v_mfma_f32_16x16x32_bf16 v[90:93], v[156:159], v[218:221], v[90:93]
	v_mfma_f32_16x16x32_bf16 v[78:81], v[148:151], v[226:229], v[78:81]
	v_mfma_f32_16x16x32_bf16 v[74:77], v[156:159], v[226:229], v[74:77]
	v_mfma_f32_16x16x32_bf16 v[118:121], v[160:163], v[176:179], v[118:121]
	v_mfma_f32_16x16x32_bf16 v[114:117], v[168:171], v[176:179], v[114:117]
	v_mfma_f32_16x16x32_bf16 v[102:105], v[160:163], v[184:187], v[102:105]
	v_mfma_f32_16x16x32_bf16 v[98:101], v[168:171], v[184:187], v[98:101]
	v_mfma_f32_16x16x32_bf16 v[86:89], v[160:163], v[214:217], v[86:89]
	v_mfma_f32_16x16x32_bf16 v[82:85], v[168:171], v[214:217], v[82:85]
	v_mfma_f32_16x16x32_bf16 v[70:73], v[160:163], v[222:225], v[70:73]
	v_mfma_f32_16x16x32_bf16 v[66:69], v[168:171], v[222:225], v[66:69]
	v_mfma_f32_16x16x32_bf16 v[118:121], v[164:167], v[180:183], v[118:121]
	v_mfma_f32_16x16x32_bf16 v[114:117], v[172:175], v[180:183], v[114:117]
	v_mfma_f32_16x16x32_bf16 v[102:105], v[164:167], v[188:191], v[102:105]
	v_mfma_f32_16x16x32_bf16 v[98:101], v[172:175], v[188:191], v[98:101]
	v_mfma_f32_16x16x32_bf16 v[86:89], v[164:167], v[218:221], v[86:89]
	v_mfma_f32_16x16x32_bf16 v[82:85], v[172:175], v[218:221], v[82:85]
	v_mfma_f32_16x16x32_bf16 v[70:73], v[164:167], v[226:229], v[70:73]
	v_mfma_f32_16x16x32_bf16 v[66:69], v[172:175], v[226:229], v[66:69]
	s_setprio 0
	s_barrier
; #define PG8_STAGE(bufoff, gbase, voff) do { _Pragma("unroll") for (int _i = 0; _i < 2; ++_i) \
;         __builtin_amdgcn_global_load_lds((const unsigned*)((const char*)(gbase) + (voff)[_i]), (LAS unsigned*)(lds + (bufoff) + ldsw + _i * 8192), 16, 0, 0); } while (0)
; #define PG8_LDA(dst, b, h) do { _Pragma("unroll") for (int m = 0; m < 4; ++m) _Pragma("unroll") for (int k = 0; k < 2; ++k) dst[m][k] = *(const LAS bf16x8*)(lds + PG8_SA(b, h) + aoff + m * 2048 + k * 1024); } while (0)
; #define PG8_MMA(ai, bj, At, Bt) do { __builtin_amdgcn_s_setprio(1); _Pragma("unroll") for (int m = 0; m < 4; ++m) _Pragma("unroll") for (int n = 0; n < 2; ++n) _Pragma("unroll") for (int k = 0; k < 2; ++k) \
;         acc[ai][bj][m][n] = __builtin_amdgcn_mfma_f32_16x16x32_bf16(Bt[n][k], At[m][k], acc[ai][bj][m][n], 0, 0, 0); __builtin_amdgcn_s_setprio(0); } while (0)
; #define PG8_WAIT_V(n) asm volatile("s_waitcnt vmcnt(" #n ")" ::: "memory")
; #define PG8_WAIT_L(n) asm volatile("s_waitcnt lgkmcnt(" #n ")" ::: "memory")
; #define PG8_BAR __builtin_amdgcn_s_barrier()
; #define PG8_SCHED __builtin_amdgcn_sched_barrier(0)
; template <class Epi, bool SP2, class Sched>
; __device__ __forceinline__ void gemm_phase(LAS unsigned char* lds, const Gemm g, const Sched& S, const Epi& E) {
;     ...
;             PG8_LDA(At, 1, 1); PG8_STAGE(PG8_SB(1, 0), b3, voffB); PG8_STAGE(PG8_SB(1, 1), b3 + hstepB, voffB); PG8_STAGE(PG8_SA(1, 0), a3, voffA);
;             PG8_WAIT_V(8); PG8_WAIT_L(0); PG8_BAR; PG8_MMA(1, 0, At, B0); PG8_MMA(1, 1, At, B1); PG8_BAR; PG8_SCHED;
;     ...
;         if (wr == 0) PG8_BAR;
	s_add_i32 s10, s22, s69
	v_lshl_add_u64 v[192:193], v[192:193], 0, s[66:67]
	s_mov_b32 m0, s10
	ds_read_b128 v[176:179], v147 offset:49152
	ds_read_b128 v[180:183], v147 offset:50176
	ds_read_b128 v[184:187], v147 offset:51200
	ds_read_b128 v[188:191], v147 offset:52224
	ds_read_b128 v[214:217], v147 offset:53248
	ds_read_b128 v[218:221], v147 offset:54272
	ds_read_b128 v[222:225], v147 offset:55296
	ds_read_b128 v[226:229], v147 offset:56320
	global_load_lds_dwordx4 v[192:193], off
	s_add_i32 m0, s10, 0x2000
	s_add_u32 s6, s6, 0x40080
	v_lshl_add_u64 v[192:193], v[230:231], 0, s[66:67]
	s_addc_u32 s7, s7, 0
	s_add_i32 s10, s23, s69
	global_load_lds_dwordx4 v[192:193], off
	v_lshl_add_u64 v[192:193], s[6:7], 0, v[64:65]
	s_mov_b32 m0, s10
	s_nop 0
	global_load_lds_dwordx4 v[192:193], off
	v_lshl_add_u64 v[192:193], s[6:7], 0, v[130:131]
	s_add_i32 m0, s10, 0x2000
	s_nop 0
	global_load_lds_dwordx4 v[192:193], off
	v_lshl_add_u64 v[192:193], v[232:233], 0, s[66:67]
	s_mov_b32 m0, s17
	s_nop 0
	global_load_lds_dwordx4 v[192:193], off
	v_lshl_add_u64 v[192:193], v[234:235], 0, s[66:67]
	s_mov_b32 m0, s18
	s_nop 0
	global_load_lds_dwordx4 v[192:193], off
	s_waitcnt vmcnt(8) lgkmcnt(0)
	s_barrier
	s_setprio 1
	v_mfma_f32_16x16x32_bf16 v[60:63], v[140:143], v[176:179], v[60:63]
	v_mfma_f32_16x16x32_bf16 v[56:59], v[152:155], v[176:179], v[56:59]
	v_mfma_f32_16x16x32_bf16 v[44:47], v[140:143], v[184:187], v[44:47]
	v_mfma_f32_16x16x32_bf16 v[40:43], v[152:155], v[184:187], v[40:43]
	v_mfma_f32_16x16x32_bf16 v[28:31], v[140:143], v[214:217], v[28:31]
	v_mfma_f32_16x16x32_bf16 v[24:27], v[152:155], v[214:217], v[24:27]
	v_mfma_f32_16x16x32_bf16 v[12:15], v[140:143], v[222:225], v[12:15]
	v_mfma_f32_16x16x32_bf16 v[8:11], v[152:155], v[222:225], v[8:11]
	v_mfma_f32_16x16x32_bf16 v[60:63], v[148:151], v[180:183], v[60:63]
	v_mfma_f32_16x16x32_bf16 v[56:59], v[156:159], v[180:183], v[56:59]
	v_mfma_f32_16x16x32_bf16 v[44:47], v[148:151], v[188:191], v[44:47]
	v_mfma_f32_16x16x32_bf16 v[40:43], v[156:159], v[188:191], v[40:43]
	v_mfma_f32_16x16x32_bf16 v[28:31], v[148:151], v[218:221], v[28:31]
	v_mfma_f32_16x16x32_bf16 v[24:27], v[156:159], v[218:221], v[24:27]
	v_mfma_f32_16x16x32_bf16 v[12:15], v[148:151], v[226:229], v[12:15]
	v_mfma_f32_16x16x32_bf16 v[8:11], v[156:159], v[226:229], v[8:11]
	v_mfma_f32_16x16x32_bf16 v[52:55], v[160:163], v[176:179], v[52:55]
	v_mfma_f32_16x16x32_bf16 v[48:51], v[168:171], v[176:179], v[48:51]
	v_mfma_f32_16x16x32_bf16 v[36:39], v[160:163], v[184:187], v[36:39]
	v_mfma_f32_16x16x32_bf16 v[32:35], v[168:171], v[184:187], v[32:35]
	v_mfma_f32_16x16x32_bf16 v[20:23], v[160:163], v[214:217], v[20:23]
	v_mfma_f32_16x16x32_bf16 v[16:19], v[168:171], v[214:217], v[16:19]
	v_mfma_f32_16x16x32_bf16 v[4:7], v[160:163], v[222:225], v[4:7]
	v_mfma_f32_16x16x32_bf16 v[0:3], v[168:171], v[222:225], v[0:3]
	v_mfma_f32_16x16x32_bf16 v[52:55], v[164:167], v[180:183], v[52:55]
	v_mfma_f32_16x16x32_bf16 v[48:51], v[172:175], v[180:183], v[48:51]
	v_mfma_f32_16x16x32_bf16 v[36:39], v[164:167], v[188:191], v[36:39]
	v_mfma_f32_16x16x32_bf16 v[32:35], v[172:175], v[188:191], v[32:35]
	v_mfma_f32_16x16x32_bf16 v[20:23], v[164:167], v[218:221], v[20:23]
	v_mfma_f32_16x16x32_bf16 v[16:19], v[172:175], v[218:221], v[16:19]
	v_mfma_f32_16x16x32_bf16 v[4:7], v[164:167], v[226:229], v[4:7]
	v_mfma_f32_16x16x32_bf16 v[0:3], v[172:175], v[226:229], v[0:3]
	s_setprio 0
	s_barrier
	s_add_i32 s21, s21, 2
	s_add_u32 s76, s76, 0x100
	s_addc_u32 s20, s20, 0
	s_add_u32 s88, s88, 0x100
	s_addc_u32 s89, s89, 0
	s_cmp_gt_u32 s21, 13
	s_cbranch_scc0 .LBB0_783
	s_and_b64 vcc, exec, s[4:5]
	s_cbranch_vccz .LBB0_786
	s_barrier

; #define PG8_STAGE(bufoff, gbase, voff) do { _Pragma("unroll") for (int _i = 0; _i < 2; ++_i) \
;         __builtin_amdgcn_global_load_lds((const unsigned*)((const char*)(gbase) + (voff)[_i]), (LAS unsigned*)(lds + (bufoff) + ldsw + _i * 8192), 16, 0, 0); } while (0)
; #define PG8_LDA(dst, b, h) do { _Pragma("unroll") for (int m = 0; m < 4; ++m) _Pragma("unroll") for (int k = 0; k < 2; ++k) dst[m][k] = *(const LAS bf16x8*)(lds + PG8_SA(b, h) + aoff + m * 2048 + k * 1024); } while (0)
; #define PG8_LDB(dst, b, h) do { _Pragma("unroll") for (int n = 0; n < 2; ++n) _Pragma("unroll") for (int k = 0; k < 2; ++k) dst[n][k] = *(const LAS bf16x8*)(lds + PG8_SB(b, h) + boff + n * 2048 + k * 1024); } while (0)
; #define PG8_WAIT_V(n) asm volatile("s_waitcnt vmcnt(" #n ")" ::: "memory")
; #define PG8_WAIT_L(n) asm volatile("s_waitcnt lgkmcnt(" #n ")" ::: "memory")
; #define PG8_BAR __builtin_amdgcn_s_barrier()
; #define PG8_SCHED __builtin_amdgcn_sched_barrier(0)
; template <class Epi, bool SP2, class Sched>
; __device__ __forceinline__ void gemm_phase(LAS unsigned char* lds, const Gemm g, const Sched& S, const Epi& E) {
;     ...
;         const bool has_next = S.next(ui + 1, nxt);
;         const char* nA = has_next ? (const char*)g.A + (size_t)nxt.pm * tstep + nxt.ko : cA; const char* nB = has_next ? (const char*)g.Bt + (size_t)nxt.pn * tstepB + nxt.ko : cB;
;         for (int t = 0; t < nt; t += 2) {
;             const bool last = (t == nt - 2);
;             const char* a1 = cA + (size_t)(t + 1) * kstep;
;             const char* a2 = last ? nA : cA + (size_t)(t + 2) * kstep; const char* b2 = last ? nB : cB + (size_t)(t + 2) * kstep;
;             const char* a3 = a2 + kstep; const char* b3 = b2 + kstep;
;             if constexpr (Epi::MID) { if (t == (nt >> 1)) E.mid(acc, cur, wr, fr); }
;             if constexpr (SP2) {
;             PG8_LDB(B0, 0, 0); PG8_LDB(B1, 0, 1); PG8_SCHED; PG8_LDA(At, 0, 0); PG8_STAGE(PG8_SA(1, 1), a1 + hstep, voffA);
;             PG8_WAIT_V(8); PG8_WAIT_L(0); PG8_BAR; PG8_MMA(0, 0, At, B0); PG8_MMA(0, 1, At, B1); PG8_BAR; PG8_SCHED;
;             PG8_LDA(At, 0, 1); PG8_STAGE(PG8_SB(0, 0), b2, voffB); PG8_STAGE(PG8_SB(0, 1), b2 + hstepB, voffB); PG8_STAGE(PG8_SA(0, 0), a2, voffA);
;             PG8_WAIT_V(8); PG8_WAIT_L(0); PG8_BAR; PG8_MMA(1, 0, At, B0); PG8_MMA(1, 1, At, B1); PG8_BAR; PG8_SCHED;
.LBB0_807:
	s_add_u32 s6, s88, 0xfffc0080
	s_addc_u32 s7, s89, -1
	s_add_i32 s22, 0, 0x10000
	s_cmp_eq_u32 s21, 12
	s_cselect_b32 s11, s59, s7
	s_cselect_b32 s10, s75, s6
	v_add_u32_e32 v64, s22, v143
	s_cselect_b32 s7, s57, s20
	s_cselect_b32 s6, s76, s77
	s_add_i32 s24, 0, 0x14000
	ds_read_b128 v[138:141], v64
	ds_read_b128 v[146:149], v64 offset:1024
	ds_read_b128 v[150:153], v64 offset:2048
	ds_read_b128 v[154:157], v64 offset:3072
	v_add_u32_e32 v64, s24, v143
	ds_read_b128 v[158:161], v64
	ds_read_b128 v[162:165], v64 offset:1024
	ds_read_b128 v[166:169], v64 offset:2048
	ds_read_b128 v[170:173], v64 offset:3072
	v_lshl_add_u64 v[226:227], s[88:89], 0, v[136:137]
	s_add_i32 m0, s33, 0xc000
	ds_read_b128 v[174:177], v145
	ds_read_b128 v[178:181], v145 offset:1024
	ds_read_b128 v[182:185], v145 offset:2048
	ds_read_b128 v[186:189], v145 offset:3072
	ds_read_b128 v[190:193], v145 offset:4096
	ds_read_b128 v[214:217], v145 offset:5120
	ds_read_b128 v[218:221], v145 offset:6144
	ds_read_b128 v[222:225], v145 offset:7168
	global_load_lds_dwordx4 v[226:227], off
	v_lshl_add_u64 v[226:227], s[88:89], 0, v[134:135]
	s_add_i32 m0, s33, 0xe000
	s_nop 0
	global_load_lds_dwordx4 v[226:227], off
	s_waitcnt vmcnt(8) lgkmcnt(0)
	s_barrier
	s_setprio 1
	v_mfma_f32_16x16x32_bf16 v[126:129], v[138:141], v[174:177], v[126:129]
	v_mfma_f32_16x16x32_bf16 v[122:125], v[150:153], v[174:177], v[122:125]
	v_mfma_f32_16x16x32_bf16 v[114:117], v[138:141], v[182:185], v[114:117]
	v_mfma_f32_16x16x32_bf16 v[106:109], v[150:153], v[182:185], v[106:109]
	v_mfma_f32_16x16x32_bf16 v[98:101], v[138:141], v[190:193], v[98:101]
	v_mfma_f32_16x16x32_bf16 v[90:93], v[150:153], v[190:193], v[90:93]
	v_mfma_f32_16x16x32_bf16 v[82:85], v[138:141], v[218:221], v[82:85]
	v_mfma_f32_16x16x32_bf16 v[74:77], v[150:153], v[218:221], v[74:77]
	v_mfma_f32_16x16x32_bf16 v[126:129], v[146:149], v[178:181], v[126:129]
	v_mfma_f32_16x16x32_bf16 v[122:125], v[154:157], v[178:181], v[122:125]
	v_mfma_f32_16x16x32_bf16 v[114:117], v[146:149], v[186:189], v[114:117]
	v_mfma_f32_16x16x32_bf16 v[106:109], v[154:157], v[186:189], v[106:109]
	v_mfma_f32_16x16x32_bf16 v[98:101], v[146:149], v[214:217], v[98:101]
	v_mfma_f32_16x16x32_bf16 v[90:93], v[154:157], v[214:217], v[90:93]
	v_mfma_f32_16x16x32_bf16 v[82:85], v[146:149], v[222:225], v[82:85]
	v_mfma_f32_16x16x32_bf16 v[74:77], v[154:157], v[222:225], v[74:77]
	v_mfma_f32_16x16x32_bf16 v[118:121], v[158:161], v[174:177], v[118:121]
	v_mfma_f32_16x16x32_bf16 v[110:113], v[166:169], v[174:177], v[110:113]
	v_mfma_f32_16x16x32_bf16 v[102:105], v[158:161], v[182:185], v[102:105]
	v_mfma_f32_16x16x32_bf16 v[94:97], v[166:169], v[182:185], v[94:97]
	v_mfma_f32_16x16x32_bf16 v[86:89], v[158:161], v[190:193], v[86:89]
	v_mfma_f32_16x16x32_bf16 v[78:81], v[166:169], v[190:193], v[78:81]
	v_mfma_f32_16x16x32_bf16 v[70:73], v[158:161], v[218:221], v[70:73]
	v_mfma_f32_16x16x32_bf16 v[66:69], v[166:169], v[218:221], v[66:69]
	v_mfma_f32_16x16x32_bf16 v[118:121], v[162:165], v[178:181], v[118:121]
	v_mfma_f32_16x16x32_bf16 v[110:113], v[170:173], v[178:181], v[110:113]
	v_mfma_f32_16x16x32_bf16 v[102:105], v[162:165], v[186:189], v[102:105]
	v_mfma_f32_16x16x32_bf16 v[94:97], v[170:173], v[186:189], v[94:97]
	v_mfma_f32_16x16x32_bf16 v[86:89], v[162:165], v[214:217], v[86:89]
	v_mfma_f32_16x16x32_bf16 v[78:81], v[170:173], v[214:217], v[78:81]
	v_mfma_f32_16x16x32_bf16 v[70:73], v[162:165], v[222:225], v[70:73]
	v_mfma_f32_16x16x32_bf16 v[66:69], v[170:173], v[222:225], v[66:69]
	s_setprio 0
	s_barrier
	s_add_i32 s22, s22, s19
	v_lshl_add_u64 v[226:227], s[6:7], 0, v[130:131]
	s_mov_b32 m0, s22
	ds_read_b128 v[174:177], v145 offset:16384
	ds_read_b128 v[178:181], v145 offset:17408
	ds_read_b128 v[182:185], v145 offset:18432
	ds_read_b128 v[186:189], v145 offset:19456
	ds_read_b128 v[190:193], v145 offset:20480
	ds_read_b128 v[214:217], v145 offset:21504
	ds_read_b128 v[218:221], v145 offset:22528
	ds_read_b128 v[222:225], v145 offset:23552
	global_load_lds_dwordx4 v[226:227], off
	s_add_i32 m0, s22, 0x2000
	s_add_u32 s22, s6, 0x40000
	v_lshl_add_u64 v[228:229], s[6:7], 0, v[132:133]
	s_addc_u32 s23, s7, 0
	s_add_i32 s24, s24, s19
	global_load_lds_dwordx4 v[228:229], off
	v_lshl_add_u64 v[230:231], s[22:23], 0, v[130:131]
	s_mov_b32 m0, s24
	v_lshl_add_u64 v[232:233], s[10:11], 0, v[132:133]
	global_load_lds_dwordx4 v[230:231], off
	v_lshl_add_u64 v[230:231], s[22:23], 0, v[132:133]
	s_add_i32 m0, s24, 0x2000
	s_nop 0
	global_load_lds_dwordx4 v[230:231], off
	v_lshl_add_u64 v[230:231], s[10:11], 0, v[130:131]
	s_mov_b32 m0, s33
	s_nop 0
	global_load_lds_dwordx4 v[230:231], off
	s_mov_b32 m0, s62
	s_nop 0
	global_load_lds_dwordx4 v[232:233], off
	s_waitcnt vmcnt(8) lgkmcnt(0)
	s_barrier
; #define PG8_STAGE(bufoff, gbase, voff) do { _Pragma("unroll") for (int _i = 0; _i < 2; ++_i) \
;         __builtin_amdgcn_global_load_lds((const unsigned*)((const char*)(gbase) + (voff)[_i]), (LAS unsigned*)(lds + (bufoff) + ldsw + _i * 8192), 16, 0, 0); } while (0)
; #define PG8_LDA(dst, b, h) do { _Pragma("unroll") for (int m = 0; m < 4; ++m) _Pragma("unroll") for (int k = 0; k < 2; ++k) dst[m][k] = *(const LAS bf16x8*)(lds + PG8_SA(b, h) + aoff + m * 2048 + k * 1024); } while (0)
; #define PG8_LDB(dst, b, h) do { _Pragma("unroll") for (int n = 0; n < 2; ++n) _Pragma("unroll") for (int k = 0; k < 2; ++k) dst[n][k] = *(const LAS bf16x8*)(lds + PG8_SB(b, h) + boff + n * 2048 + k * 1024); } while (0)
; #define PG8_MMA(ai, bj, At, Bt) do { __builtin_amdgcn_s_setprio(1); _Pragma("unroll") for (int m = 0; m < 4; ++m) _Pragma("unroll") for (int n = 0; n < 2; ++n) _Pragma("unroll") for (int k = 0; k < 2; ++k) \
;         acc[ai][bj][m][n] = __builtin_amdgcn_mfma_f32_16x16x32_bf16(Bt[n][k], At[m][k], acc[ai][bj][m][n], 0, 0, 0); __builtin_amdgcn_s_setprio(0); } while (0)
; #define PG8_WAIT_V(n) asm volatile("s_waitcnt vmcnt(" #n ")" ::: "memory")
; #define PG8_WAIT_L(n) asm volatile("s_waitcnt lgkmcnt(" #n ")" ::: "memory")
; #define PG8_BAR __builtin_amdgcn_s_barrier()
; #define PG8_SCHED __builtin_amdgcn_sched_barrier(0)
; template <class Epi, bool SP2, class Sched>
; __device__ __forceinline__ void gemm_phase(LAS unsigned char* lds, const Gemm g, const Sched& S, const Epi& E) {
;     ...
;             PG8_WAIT_V(8); PG8_WAIT_L(0); PG8_BAR; PG8_MMA(1, 0, At, B0); PG8_MMA(1, 1, At, B1); PG8_BAR; PG8_SCHED;
;             PG8_LDB(B0, 1, 0); PG8_LDB(B1, 1, 1); PG8_SCHED; PG8_LDA(At, 1, 0); PG8_STAGE(PG8_SA(0, 1), a2 + hstep, voffA);
;             PG8_WAIT_V(8); PG8_WAIT_L(0); PG8_BAR; PG8_MMA(0, 0, At, B0); PG8_MMA(0, 1, At, B1); PG8_BAR; PG8_SCHED;
	s_setprio 1
	v_mfma_f32_16x16x32_bf16 v[60:63], v[138:141], v[174:177], v[60:63]
	v_mfma_f32_16x16x32_bf16 v[56:59], v[150:153], v[174:177], v[56:59]
	v_mfma_f32_16x16x32_bf16 v[48:51], v[138:141], v[182:185], v[48:51]
	v_mfma_f32_16x16x32_bf16 v[40:43], v[150:153], v[182:185], v[40:43]
	v_mfma_f32_16x16x32_bf16 v[32:35], v[138:141], v[190:193], v[32:35]
	v_mfma_f32_16x16x32_bf16 v[24:27], v[150:153], v[190:193], v[24:27]
	v_mfma_f32_16x16x32_bf16 v[12:15], v[138:141], v[218:221], v[12:15]
	v_mfma_f32_16x16x32_bf16 v[8:11], v[150:153], v[218:221], v[8:11]
	v_mfma_f32_16x16x32_bf16 v[60:63], v[146:149], v[178:181], v[60:63]
	v_mfma_f32_16x16x32_bf16 v[56:59], v[154:157], v[178:181], v[56:59]
	v_mfma_f32_16x16x32_bf16 v[48:51], v[146:149], v[186:189], v[48:51]
	v_mfma_f32_16x16x32_bf16 v[40:43], v[154:157], v[186:189], v[40:43]
	v_mfma_f32_16x16x32_bf16 v[32:35], v[146:149], v[214:217], v[32:35]
	v_mfma_f32_16x16x32_bf16 v[24:27], v[154:157], v[214:217], v[24:27]
	v_mfma_f32_16x16x32_bf16 v[12:15], v[146:149], v[222:225], v[12:15]
	v_mfma_f32_16x16x32_bf16 v[8:11], v[154:157], v[222:225], v[8:11]
	v_mfma_f32_16x16x32_bf16 v[52:55], v[158:161], v[174:177], v[52:55]
	v_mfma_f32_16x16x32_bf16 v[44:47], v[166:169], v[174:177], v[44:47]
	v_mfma_f32_16x16x32_bf16 v[36:39], v[158:161], v[182:185], v[36:39]
	v_mfma_f32_16x16x32_bf16 v[28:31], v[166:169], v[182:185], v[28:31]
	v_mfma_f32_16x16x32_bf16 v[20:23], v[158:161], v[190:193], v[20:23]
	v_mfma_f32_16x16x32_bf16 v[16:19], v[166:169], v[190:193], v[16:19]
	v_mfma_f32_16x16x32_bf16 v[4:7], v[158:161], v[218:221], v[4:7]
	v_mfma_f32_16x16x32_bf16 v[0:3], v[166:169], v[218:221], v[0:3]
	v_mfma_f32_16x16x32_bf16 v[52:55], v[162:165], v[178:181], v[52:55]
	v_mfma_f32_16x16x32_bf16 v[44:47], v[170:173], v[178:181], v[44:47]
	v_mfma_f32_16x16x32_bf16 v[36:39], v[162:165], v[186:189], v[36:39]
	v_mfma_f32_16x16x32_bf16 v[28:31], v[170:173], v[186:189], v[28:31]
	v_mfma_f32_16x16x32_bf16 v[20:23], v[162:165], v[214:217], v[20:23]
	v_mfma_f32_16x16x32_bf16 v[16:19], v[170:173], v[214:217], v[16:19]
	v_mfma_f32_16x16x32_bf16 v[4:7], v[162:165], v[222:225], v[4:7]
	v_mfma_f32_16x16x32_bf16 v[0:3], v[170:173], v[222:225], v[0:3]
	s_setprio 0
	s_barrier
	s_add_i32 s22, 0, 0x18000
	v_add_u32_e32 v64, s22, v143
	s_add_i32 s23, 0, 0x1c000
	ds_read_b128 v[138:141], v64
	ds_read_b128 v[146:149], v64 offset:1024
	ds_read_b128 v[150:153], v64 offset:2048
	ds_read_b128 v[154:157], v64 offset:3072
	v_add_u32_e32 v64, s23, v143
	ds_read_b128 v[158:161], v64
	ds_read_b128 v[162:165], v64 offset:1024
	ds_read_b128 v[166:169], v64 offset:2048
	ds_read_b128 v[170:173], v64 offset:3072
	s_add_u32 s10, s10, 0x40000
	s_addc_u32 s11, s11, 0
	s_mov_b32 m0, s64
	v_lshl_add_u64 v[234:235], s[10:11], 0, v[130:131]
	ds_read_b128 v[174:177], v145 offset:32768
	ds_read_b128 v[178:181], v145 offset:33792
	ds_read_b128 v[182:185], v145 offset:34816
	ds_read_b128 v[186:189], v145 offset:35840
	ds_read_b128 v[190:193], v145 offset:36864
	ds_read_b128 v[214:217], v145 offset:37888
	ds_read_b128 v[218:221], v145 offset:38912
	ds_read_b128 v[222:225], v145 offset:39936
	global_load_lds_dwordx4 v[234:235], off
	v_lshl_add_u64 v[234:235], s[10:11], 0, v[132:133]
	s_mov_b32 m0, s65
	s_nop 0
	global_load_lds_dwordx4 v[234:235], off
	s_waitcnt vmcnt(8) lgkmcnt(0)
	s_barrier
	s_setprio 1
	v_mfma_f32_16x16x32_bf16 v[126:129], v[138:141], v[174:177], v[126:129]
	v_mfma_f32_16x16x32_bf16 v[122:125], v[150:153], v[174:177], v[122:125]
	v_mfma_f32_16x16x32_bf16 v[114:117], v[138:141], v[182:185], v[114:117]
	v_mfma_f32_16x16x32_bf16 v[106:109], v[150:153], v[182:185], v[106:109]
	v_mfma_f32_16x16x32_bf16 v[98:101], v[138:141], v[190:193], v[98:101]
	v_mfma_f32_16x16x32_bf16 v[90:93], v[150:153], v[190:193], v[90:93]
	v_mfma_f32_16x16x32_bf16 v[82:85], v[138:141], v[218:221], v[82:85]
	v_mfma_f32_16x16x32_bf16 v[74:77], v[150:153], v[218:221], v[74:77]
	v_mfma_f32_16x16x32_bf16 v[126:129], v[146:149], v[178:181], v[126:129]
	v_mfma_f32_16x16x32_bf16 v[122:125], v[154:157], v[178:181], v[122:125]
	v_mfma_f32_16x16x32_bf16 v[114:117], v[146:149], v[186:189], v[114:117]
	v_mfma_f32_16x16x32_bf16 v[106:109], v[154:157], v[186:189], v[106:109]
	v_mfma_f32_16x16x32_bf16 v[98:101], v[146:149], v[214:217], v[98:101]
	v_mfma_f32_16x16x32_bf16 v[90:93], v[154:157], v[214:217], v[90:93]
	v_mfma_f32_16x16x32_bf16 v[82:85], v[146:149], v[222:225], v[82:85]
	v_mfma_f32_16x16x32_bf16 v[74:77], v[154:157], v[222:225], v[74:77]
	v_mfma_f32_16x16x32_bf16 v[118:121], v[158:161], v[174:177], v[118:121]
	v_mfma_f32_16x16x32_bf16 v[110:113], v[166:169], v[174:177], v[110:113]
	v_mfma_f32_16x16x32_bf16 v[102:105], v[158:161], v[182:185], v[102:105]
	v_mfma_f32_16x16x32_bf16 v[94:97], v[166:169], v[182:185], v[94:97]
	v_mfma_f32_16x16x32_bf16 v[86:89], v[158:161], v[190:193], v[86:89]
	v_mfma_f32_16x16x32_bf16 v[78:81], v[166:169], v[190:193], v[78:81]
	v_mfma_f32_16x16x32_bf16 v[70:73], v[158:161], v[218:221], v[70:73]
	v_mfma_f32_16x16x32_bf16 v[66:69], v[166:169], v[218:221], v[66:69]
	v_mfma_f32_16x16x32_bf16 v[118:121], v[162:165], v[178:181], v[118:121]
	v_mfma_f32_16x16x32_bf16 v[110:113], v[170:173], v[178:181], v[110:113]
	v_mfma_f32_16x16x32_bf16 v[102:105], v[162:165], v[186:189], v[102:105]
	v_mfma_f32_16x16x32_bf16 v[94:97], v[170:173], v[186:189], v[94:97]
	v_mfma_f32_16x16x32_bf16 v[86:89], v[162:165], v[214:217], v[86:89]
	v_mfma_f32_16x16x32_bf16 v[78:81], v[170:173], v[214:217], v[78:81]
	v_mfma_f32_16x16x32_bf16 v[70:73], v[162:165], v[222:225], v[70:73]
	v_mfma_f32_16x16x32_bf16 v[66:69], v[170:173], v[222:225], v[66:69]
	s_setprio 0
	s_barrier
; #define PG8_STAGE(bufoff, gbase, voff) do { _Pragma("unroll") for (int _i = 0; _i < 2; ++_i) \
;         __builtin_amdgcn_global_load_lds((const unsigned*)((const char*)(gbase) + (voff)[_i]), (LAS unsigned*)(lds + (bufoff) + ldsw + _i * 8192), 16, 0, 0); } while (0)
; #define PG8_LDA(dst, b, h) do { _Pragma("unroll") for (int m = 0; m < 4; ++m) _Pragma("unroll") for (int k = 0; k < 2; ++k) dst[m][k] = *(const LAS bf16x8*)(lds + PG8_SA(b, h) + aoff + m * 2048 + k * 1024); } while (0)
; #define PG8_MMA(ai, bj, At, Bt) do { __builtin_amdgcn_s_setprio(1); _Pragma("unroll") for (int m = 0; m < 4; ++m) _Pragma("unroll") for (int n = 0; n < 2; ++n) _Pragma("unroll") for (int k = 0; k < 2; ++k) \
;         acc[ai][bj][m][n] = __builtin_amdgcn_mfma_f32_16x16x32_bf16(Bt[n][k], At[m][k], acc[ai][bj][m][n], 0, 0, 0); __builtin_amdgcn_s_setprio(0); } while (0)
; #define PG8_WAIT_V(n) asm volatile("s_waitcnt vmcnt(" #n ")" ::: "memory")
; #define PG8_WAIT_L(n) asm volatile("s_waitcnt lgkmcnt(" #n ")" ::: "memory")
; #define PG8_BAR __builtin_amdgcn_s_barrier()
; #define PG8_SCHED __builtin_amdgcn_sched_barrier(0)
; template <class Epi, bool SP2, class Sched>
; __device__ __forceinline__ void gemm_phase(LAS unsigned char* lds, const Gemm g, const Sched& S, const Epi& E) {
;     ...
;             PG8_LDA(At, 1, 1); PG8_STAGE(PG8_SB(1, 0), b3, voffB); PG8_STAGE(PG8_SB(1, 1), b3 + hstepB, voffB); PG8_STAGE(PG8_SA(1, 0), a3, voffA);
;             PG8_WAIT_V(8); PG8_WAIT_L(0); PG8_BAR; PG8_MMA(1, 0, At, B0); PG8_MMA(1, 1, At, B1); PG8_BAR; PG8_SCHED;
;     ...
;         if (wr == 0) PG8_BAR;
	s_add_i32 s10, s22, s19
	v_lshl_add_u64 v[226:227], v[226:227], 0, s[66:67]
	s_mov_b32 m0, s10
	ds_read_b128 v[174:177], v145 offset:49152
	ds_read_b128 v[178:181], v145 offset:50176
	ds_read_b128 v[182:185], v145 offset:51200
	ds_read_b128 v[186:189], v145 offset:52224
	ds_read_b128 v[190:193], v145 offset:53248
	ds_read_b128 v[214:217], v145 offset:54272
	ds_read_b128 v[218:221], v145 offset:55296
	ds_read_b128 v[222:225], v145 offset:56320
	global_load_lds_dwordx4 v[226:227], off
	s_add_i32 m0, s10, 0x2000
	s_add_u32 s6, s6, 0x40080
	v_lshl_add_u64 v[226:227], v[228:229], 0, s[66:67]
	s_addc_u32 s7, s7, 0
	s_add_i32 s10, s23, s19
	global_load_lds_dwordx4 v[226:227], off
	v_lshl_add_u64 v[226:227], s[6:7], 0, v[130:131]
	s_mov_b32 m0, s10
	s_nop 0
	global_load_lds_dwordx4 v[226:227], off
	v_lshl_add_u64 v[226:227], s[6:7], 0, v[132:133]
	s_add_i32 m0, s10, 0x2000
	s_nop 0
	global_load_lds_dwordx4 v[226:227], off
	v_lshl_add_u64 v[226:227], v[230:231], 0, s[66:67]
	s_mov_b32 m0, s68
	s_nop 0
	global_load_lds_dwordx4 v[226:227], off
	v_lshl_add_u64 v[226:227], v[232:233], 0, s[66:67]
	s_mov_b32 m0, s69
	s_nop 0
	global_load_lds_dwordx4 v[226:227], off
	s_waitcnt vmcnt(8) lgkmcnt(0)
	s_barrier
	s_setprio 1
	v_mfma_f32_16x16x32_bf16 v[60:63], v[138:141], v[174:177], v[60:63]
	v_mfma_f32_16x16x32_bf16 v[56:59], v[150:153], v[174:177], v[56:59]
	v_mfma_f32_16x16x32_bf16 v[48:51], v[138:141], v[182:185], v[48:51]
	v_mfma_f32_16x16x32_bf16 v[40:43], v[150:153], v[182:185], v[40:43]
	v_mfma_f32_16x16x32_bf16 v[32:35], v[138:141], v[190:193], v[32:35]
	v_mfma_f32_16x16x32_bf16 v[24:27], v[150:153], v[190:193], v[24:27]
	v_mfma_f32_16x16x32_bf16 v[12:15], v[138:141], v[218:221], v[12:15]
	v_mfma_f32_16x16x32_bf16 v[8:11], v[150:153], v[218:221], v[8:11]
	v_mfma_f32_16x16x32_bf16 v[60:63], v[146:149], v[178:181], v[60:63]
	v_mfma_f32_16x16x32_bf16 v[56:59], v[154:157], v[178:181], v[56:59]
	v_mfma_f32_16x16x32_bf16 v[48:51], v[146:149], v[186:189], v[48:51]
	v_mfma_f32_16x16x32_bf16 v[40:43], v[154:157], v[186:189], v[40:43]
	v_mfma_f32_16x16x32_bf16 v[32:35], v[146:149], v[214:217], v[32:35]
	v_mfma_f32_16x16x32_bf16 v[24:27], v[154:157], v[214:217], v[24:27]
	v_mfma_f32_16x16x32_bf16 v[12:15], v[146:149], v[222:225], v[12:15]
	v_mfma_f32_16x16x32_bf16 v[8:11], v[154:157], v[222:225], v[8:11]
	v_mfma_f32_16x16x32_bf16 v[52:55], v[158:161], v[174:177], v[52:55]
	v_mfma_f32_16x16x32_bf16 v[44:47], v[166:169], v[174:177], v[44:47]
	v_mfma_f32_16x16x32_bf16 v[36:39], v[158:161], v[182:185], v[36:39]
	v_mfma_f32_16x16x32_bf16 v[28:31], v[166:169], v[182:185], v[28:31]
	v_mfma_f32_16x16x32_bf16 v[20:23], v[158:161], v[190:193], v[20:23]
	v_mfma_f32_16x16x32_bf16 v[16:19], v[166:169], v[190:193], v[16:19]
	v_mfma_f32_16x16x32_bf16 v[4:7], v[158:161], v[218:221], v[4:7]
	v_mfma_f32_16x16x32_bf16 v[0:3], v[166:169], v[218:221], v[0:3]
	v_mfma_f32_16x16x32_bf16 v[52:55], v[162:165], v[178:181], v[52:55]
	v_mfma_f32_16x16x32_bf16 v[44:47], v[170:173], v[178:181], v[44:47]
	v_mfma_f32_16x16x32_bf16 v[36:39], v[162:165], v[186:189], v[36:39]
	v_mfma_f32_16x16x32_bf16 v[28:31], v[170:173], v[186:189], v[28:31]
	v_mfma_f32_16x16x32_bf16 v[20:23], v[162:165], v[214:217], v[20:23]
	v_mfma_f32_16x16x32_bf16 v[16:19], v[170:173], v[214:217], v[16:19]
	v_mfma_f32_16x16x32_bf16 v[4:7], v[162:165], v[222:225], v[4:7]
	v_mfma_f32_16x16x32_bf16 v[0:3], v[170:173], v[222:225], v[0:3]
	s_setprio 0
	s_barrier
	s_add_i32 s21, s21, 2
	s_add_u32 s77, s77, 0x100
	s_addc_u32 s20, s20, 0
	s_add_u32 s88, s88, 0x100
	s_addc_u32 s89, s89, 0
	s_cmp_gt_u32 s21, 13
	s_cbranch_scc0 .LBB0_807
	s_and_b64 vcc, exec, s[16:17]
	s_cbranch_vccz .LBB0_810
	s_barrier

; #define PG8_STAGE(bufoff, gbase, voff) do { _Pragma("unroll") for (int _i = 0; _i < 2; ++_i) \
;         __builtin_amdgcn_global_load_lds((const unsigned*)((const char*)(gbase) + (voff)[_i]), (LAS unsigned*)(lds + (bufoff) + ldsw + _i * 8192), 16, 0, 0); } while (0)
; #define PG8_LDA(dst, b, h) do { _Pragma("unroll") for (int m = 0; m < 4; ++m) _Pragma("unroll") for (int k = 0; k < 2; ++k) dst[m][k] = *(const LAS bf16x8*)(lds + PG8_SA(b, h) + aoff + m * 2048 + k * 1024); } while (0)
; #define PG8_LDB(dst, b, h) do { _Pragma("unroll") for (int n = 0; n < 2; ++n) _Pragma("unroll") for (int k = 0; k < 2; ++k) dst[n][k] = *(const LAS bf16x8*)(lds + PG8_SB(b, h) + boff + n * 2048 + k * 1024); } while (0)
; #define PG8_WAIT_V(n) asm volatile("s_waitcnt vmcnt(" #n ")" ::: "memory")
; #define PG8_WAIT_L(n) asm volatile("s_waitcnt lgkmcnt(" #n ")" ::: "memory")
; #define PG8_BAR __builtin_amdgcn_s_barrier()
; #define PG8_SCHED __builtin_amdgcn_sched_barrier(0)
; template <class Epi, bool SP2, class Sched>
; __device__ __forceinline__ void gemm_phase(LAS unsigned char* lds, const Gemm g, const Sched& S, const Epi& E) {
;     ...
;         const bool has_next = S.next(ui + 1, nxt);
;         const char* nA = has_next ? (const char*)g.A + (size_t)nxt.pm * tstep + nxt.ko : cA; const char* nB = has_next ? (const char*)g.Bt + (size_t)nxt.pn * tstepB + nxt.ko : cB;
;         for (int t = 0; t < nt; t += 2) {
;             const bool last = (t == nt - 2);
;             const char* a1 = cA + (size_t)(t + 1) * kstep;
;             const char* a2 = last ? nA : cA + (size_t)(t + 2) * kstep; const char* b2 = last ? nB : cB + (size_t)(t + 2) * kstep;
;             const char* a3 = a2 + kstep; const char* b3 = b2 + kstep;
;             if constexpr (Epi::MID) { if (t == (nt >> 1)) E.mid(acc, cur, wr, fr); }
;             if constexpr (SP2) {
;             PG8_LDB(B0, 0, 0); PG8_LDB(B1, 0, 1); PG8_SCHED; PG8_LDA(At, 0, 0); PG8_STAGE(PG8_SA(1, 1), a1 + hstep, voffA);
;             PG8_WAIT_V(8); PG8_WAIT_L(0); PG8_BAR; PG8_MMA(0, 0, At, B0); PG8_MMA(0, 1, At, B1); PG8_BAR; PG8_SCHED;
;             PG8_LDA(At, 0, 1); PG8_STAGE(PG8_SB(0, 0), b2, voffB); PG8_STAGE(PG8_SB(0, 1), b2 + hstepB, voffB); PG8_STAGE(PG8_SA(0, 0), a2, voffA);
;             PG8_WAIT_V(8); PG8_WAIT_L(0); PG8_BAR; PG8_MMA(1, 0, At, B0); PG8_MMA(1, 1, At, B1); PG8_BAR; PG8_SCHED;
.LBB0_955:
	s_add_u32 s6, s92, 0xfffc0080
	s_addc_u32 s7, s93, -1
	s_add_i32 s22, 0, 0x10000
	s_cmp_eq_u32 s21, 12
	s_cselect_b32 s11, s73, s7
	s_cselect_b32 s10, s74, s6
	v_add_u32_e32 v144, s22, v147
	s_cselect_b32 s7, s5, s20
	s_cselect_b32 s6, s75, s76
	s_add_i32 s24, 0, 0x14000
	ds_read_b128 v[140:143], v144
	ds_read_b128 v[150:153], v144 offset:1024
	ds_read_b128 v[154:157], v144 offset:2048
	ds_read_b128 v[158:161], v144 offset:3072
	v_add_u32_e32 v144, s24, v147
	ds_read_b128 v[162:165], v144
	ds_read_b128 v[166:169], v144 offset:1024
	ds_read_b128 v[170:173], v144 offset:2048
	ds_read_b128 v[174:177], v144 offset:3072
	v_lshl_add_u64 v[144:145], s[92:93], 0, v[138:139]
	s_add_i32 m0, s13, 0xc000
	ds_read_b128 v[178:181], v149
	ds_read_b128 v[182:185], v149 offset:1024
	ds_read_b128 v[186:189], v149 offset:2048
	ds_read_b128 v[190:193], v149 offset:3072
	ds_read_b128 v[214:217], v149 offset:4096
	ds_read_b128 v[218:221], v149 offset:5120
	ds_read_b128 v[222:225], v149 offset:6144
	ds_read_b128 v[226:229], v149 offset:7168
	global_load_lds_dwordx4 v[144:145], off
	v_lshl_add_u64 v[144:145], s[92:93], 0, v[136:137]
	s_add_i32 m0, s13, 0xe000
	s_nop 0
	global_load_lds_dwordx4 v[144:145], off
	s_waitcnt vmcnt(8) lgkmcnt(0)
	s_barrier
	s_setprio 1
	v_mfma_f32_16x16x32_bf16 v[126:129], v[140:143], v[178:181], v[126:129]
	v_mfma_f32_16x16x32_bf16 v[122:125], v[154:157], v[178:181], v[122:125]
	v_mfma_f32_16x16x32_bf16 v[110:113], v[140:143], v[186:189], v[110:113]
	v_mfma_f32_16x16x32_bf16 v[106:109], v[154:157], v[186:189], v[106:109]
	v_mfma_f32_16x16x32_bf16 v[94:97], v[140:143], v[214:217], v[94:97]
	v_mfma_f32_16x16x32_bf16 v[90:93], v[154:157], v[214:217], v[90:93]
	v_mfma_f32_16x16x32_bf16 v[78:81], v[140:143], v[222:225], v[78:81]
	v_mfma_f32_16x16x32_bf16 v[74:77], v[154:157], v[222:225], v[74:77]
	v_mfma_f32_16x16x32_bf16 v[126:129], v[150:153], v[182:185], v[126:129]
	v_mfma_f32_16x16x32_bf16 v[122:125], v[158:161], v[182:185], v[122:125]
	v_mfma_f32_16x16x32_bf16 v[110:113], v[150:153], v[190:193], v[110:113]
	v_mfma_f32_16x16x32_bf16 v[106:109], v[158:161], v[190:193], v[106:109]
	v_mfma_f32_16x16x32_bf16 v[94:97], v[150:153], v[218:221], v[94:97]
	v_mfma_f32_16x16x32_bf16 v[90:93], v[158:161], v[218:221], v[90:93]
	v_mfma_f32_16x16x32_bf16 v[78:81], v[150:153], v[226:229], v[78:81]
	v_mfma_f32_16x16x32_bf16 v[74:77], v[158:161], v[226:229], v[74:77]
	v_mfma_f32_16x16x32_bf16 v[118:121], v[162:165], v[178:181], v[118:121]
	v_mfma_f32_16x16x32_bf16 v[114:117], v[170:173], v[178:181], v[114:117]
	v_mfma_f32_16x16x32_bf16 v[102:105], v[162:165], v[186:189], v[102:105]
	v_mfma_f32_16x16x32_bf16 v[98:101], v[170:173], v[186:189], v[98:101]
	v_mfma_f32_16x16x32_bf16 v[86:89], v[162:165], v[214:217], v[86:89]
	v_mfma_f32_16x16x32_bf16 v[82:85], v[170:173], v[214:217], v[82:85]
	v_mfma_f32_16x16x32_bf16 v[70:73], v[162:165], v[222:225], v[70:73]
	v_mfma_f32_16x16x32_bf16 v[66:69], v[170:173], v[222:225], v[66:69]
	v_mfma_f32_16x16x32_bf16 v[118:121], v[166:169], v[182:185], v[118:121]
	v_mfma_f32_16x16x32_bf16 v[114:117], v[174:177], v[182:185], v[114:117]
	v_mfma_f32_16x16x32_bf16 v[102:105], v[166:169], v[190:193], v[102:105]
	v_mfma_f32_16x16x32_bf16 v[98:101], v[174:177], v[190:193], v[98:101]
	v_mfma_f32_16x16x32_bf16 v[86:89], v[166:169], v[218:221], v[86:89]
	v_mfma_f32_16x16x32_bf16 v[82:85], v[174:177], v[218:221], v[82:85]
	v_mfma_f32_16x16x32_bf16 v[70:73], v[166:169], v[226:229], v[70:73]
	v_mfma_f32_16x16x32_bf16 v[66:69], v[174:177], v[226:229], v[66:69]
	s_setprio 0
	s_barrier
	s_add_i32 s22, s22, s12
	v_lshl_add_u64 v[144:145], s[6:7], 0, v[64:65]
	s_mov_b32 m0, s22
	ds_read_b128 v[178:181], v149 offset:16384
	ds_read_b128 v[182:185], v149 offset:17408
	ds_read_b128 v[186:189], v149 offset:18432
	ds_read_b128 v[190:193], v149 offset:19456
	ds_read_b128 v[214:217], v149 offset:20480
	ds_read_b128 v[218:221], v149 offset:21504
	ds_read_b128 v[222:225], v149 offset:22528
	ds_read_b128 v[226:229], v149 offset:23552
	global_load_lds_dwordx4 v[144:145], off
	s_add_i32 m0, s22, 0x2000
	s_add_u32 s22, s6, 0x40000
	v_lshl_add_u64 v[230:231], s[6:7], 0, v[134:135]
	s_addc_u32 s23, s7, 0
	s_add_i32 s24, s24, s12
	global_load_lds_dwordx4 v[230:231], off
	v_lshl_add_u64 v[232:233], s[22:23], 0, v[64:65]
	s_mov_b32 m0, s24
	v_lshl_add_u64 v[234:235], s[10:11], 0, v[132:133]
	global_load_lds_dwordx4 v[232:233], off
	v_lshl_add_u64 v[232:233], s[22:23], 0, v[134:135]
	s_add_i32 m0, s24, 0x2000
	s_nop 0
	global_load_lds_dwordx4 v[232:233], off
	v_lshl_add_u64 v[232:233], s[10:11], 0, v[130:131]
	s_mov_b32 m0, s13
	s_nop 0
	global_load_lds_dwordx4 v[232:233], off
	s_mov_b32 m0, s14
	s_nop 0
	global_load_lds_dwordx4 v[234:235], off
	s_waitcnt vmcnt(8) lgkmcnt(0)
	s_barrier
; #define PG8_STAGE(bufoff, gbase, voff) do { _Pragma("unroll") for (int _i = 0; _i < 2; ++_i) \
;         __builtin_amdgcn_global_load_lds((const unsigned*)((const char*)(gbase) + (voff)[_i]), (LAS unsigned*)(lds + (bufoff) + ldsw + _i * 8192), 16, 0, 0); } while (0)
; #define PG8_LDA(dst, b, h) do { _Pragma("unroll") for (int m = 0; m < 4; ++m) _Pragma("unroll") for (int k = 0; k < 2; ++k) dst[m][k] = *(const LAS bf16x8*)(lds + PG8_SA(b, h) + aoff + m * 2048 + k * 1024); } while (0)
; #define PG8_LDB(dst, b, h) do { _Pragma("unroll") for (int n = 0; n < 2; ++n) _Pragma("unroll") for (int k = 0; k < 2; ++k) dst[n][k] = *(const LAS bf16x8*)(lds + PG8_SB(b, h) + boff + n * 2048 + k * 1024); } while (0)
; #define PG8_MMA(ai, bj, At, Bt) do { __builtin_amdgcn_s_setprio(1); _Pragma("unroll") for (int m = 0; m < 4; ++m) _Pragma("unroll") for (int n = 0; n < 2; ++n) _Pragma("unroll") for (int k = 0; k < 2; ++k) \
;         acc[ai][bj][m][n] = __builtin_amdgcn_mfma_f32_16x16x32_bf16(Bt[n][k], At[m][k], acc[ai][bj][m][n], 0, 0, 0); __builtin_amdgcn_s_setprio(0); } while (0)
; #define PG8_WAIT_V(n) asm volatile("s_waitcnt vmcnt(" #n ")" ::: "memory")
; #define PG8_WAIT_L(n) asm volatile("s_waitcnt lgkmcnt(" #n ")" ::: "memory")
; #define PG8_BAR __builtin_amdgcn_s_barrier()
; #define PG8_SCHED __builtin_amdgcn_sched_barrier(0)
; template <class Epi, bool SP2, class Sched>
; __device__ __forceinline__ void gemm_phase(LAS unsigned char* lds, const Gemm g, const Sched& S, const Epi& E) {
;     ...
;             PG8_WAIT_V(8); PG8_WAIT_L(0); PG8_BAR; PG8_MMA(1, 0, At, B0); PG8_MMA(1, 1, At, B1); PG8_BAR; PG8_SCHED;
;             PG8_LDB(B0, 1, 0); PG8_LDB(B1, 1, 1); PG8_SCHED; PG8_LDA(At, 1, 0); PG8_STAGE(PG8_SA(0, 1), a2 + hstep, voffA);
;             PG8_WAIT_V(8); PG8_WAIT_L(0); PG8_BAR; PG8_MMA(0, 0, At, B0); PG8_MMA(0, 1, At, B1); PG8_BAR; PG8_SCHED;
	s_setprio 1
	v_mfma_f32_16x16x32_bf16 v[60:63], v[140:143], v[178:181], v[60:63]
	v_mfma_f32_16x16x32_bf16 v[56:59], v[154:157], v[178:181], v[56:59]
	v_mfma_f32_16x16x32_bf16 v[44:47], v[140:143], v[186:189], v[44:47]
	v_mfma_f32_16x16x32_bf16 v[40:43], v[154:157], v[186:189], v[40:43]
	v_mfma_f32_16x16x32_bf16 v[28:31], v[140:143], v[214:217], v[28:31]
	v_mfma_f32_16x16x32_bf16 v[24:27], v[154:157], v[214:217], v[24:27]
	v_mfma_f32_16x16x32_bf16 v[12:15], v[140:143], v[222:225], v[12:15]
	v_mfma_f32_16x16x32_bf16 v[8:11], v[154:157], v[222:225], v[8:11]
	v_mfma_f32_16x16x32_bf16 v[60:63], v[150:153], v[182:185], v[60:63]
	v_mfma_f32_16x16x32_bf16 v[56:59], v[158:161], v[182:185], v[56:59]
	v_mfma_f32_16x16x32_bf16 v[44:47], v[150:153], v[190:193], v[44:47]
	v_mfma_f32_16x16x32_bf16 v[40:43], v[158:161], v[190:193], v[40:43]
	v_mfma_f32_16x16x32_bf16 v[28:31], v[150:153], v[218:221], v[28:31]
	v_mfma_f32_16x16x32_bf16 v[24:27], v[158:161], v[218:221], v[24:27]
	v_mfma_f32_16x16x32_bf16 v[12:15], v[150:153], v[226:229], v[12:15]
	v_mfma_f32_16x16x32_bf16 v[8:11], v[158:161], v[226:229], v[8:11]
	v_mfma_f32_16x16x32_bf16 v[52:55], v[162:165], v[178:181], v[52:55]
	v_mfma_f32_16x16x32_bf16 v[48:51], v[170:173], v[178:181], v[48:51]
	v_mfma_f32_16x16x32_bf16 v[36:39], v[162:165], v[186:189], v[36:39]
	v_mfma_f32_16x16x32_bf16 v[32:35], v[170:173], v[186:189], v[32:35]
	v_mfma_f32_16x16x32_bf16 v[20:23], v[162:165], v[214:217], v[20:23]
	v_mfma_f32_16x16x32_bf16 v[16:19], v[170:173], v[214:217], v[16:19]
	v_mfma_f32_16x16x32_bf16 v[4:7], v[162:165], v[222:225], v[4:7]
	v_mfma_f32_16x16x32_bf16 v[0:3], v[170:173], v[222:225], v[0:3]
	v_mfma_f32_16x16x32_bf16 v[52:55], v[166:169], v[182:185], v[52:55]
	v_mfma_f32_16x16x32_bf16 v[48:51], v[174:177], v[182:185], v[48:51]
	v_mfma_f32_16x16x32_bf16 v[36:39], v[166:169], v[190:193], v[36:39]
	v_mfma_f32_16x16x32_bf16 v[32:35], v[174:177], v[190:193], v[32:35]
	v_mfma_f32_16x16x32_bf16 v[20:23], v[166:169], v[218:221], v[20:23]
	v_mfma_f32_16x16x32_bf16 v[16:19], v[174:177], v[218:221], v[16:19]
	v_mfma_f32_16x16x32_bf16 v[4:7], v[166:169], v[226:229], v[4:7]
	v_mfma_f32_16x16x32_bf16 v[0:3], v[174:177], v[226:229], v[0:3]
	s_setprio 0
	s_barrier
	s_add_i32 s22, 0, 0x18000
	s_add_i32 s23, 0, 0x1c000
	v_add_u32_e32 v158, s22, v147
	v_add_u32_e32 v174, s23, v147
	ds_read_b128 v[140:143], v158
	ds_read_b128 v[150:153], v158 offset:1024
	ds_read_b128 v[154:157], v158 offset:2048
	ds_read_b128 v[158:161], v158 offset:3072
	ds_read_b128 v[162:165], v174
	ds_read_b128 v[166:169], v174 offset:1024
	ds_read_b128 v[170:173], v174 offset:2048
	ds_read_b128 v[174:177], v174 offset:3072
	s_add_u32 s10, s10, 0x40000
	s_addc_u32 s11, s11, 0
	s_mov_b32 m0, s15
	v_lshl_add_u64 v[236:237], s[10:11], 0, v[130:131]
	ds_read_b128 v[178:181], v149 offset:32768
	ds_read_b128 v[182:185], v149 offset:33792
	ds_read_b128 v[186:189], v149 offset:34816
	ds_read_b128 v[190:193], v149 offset:35840
	ds_read_b128 v[214:217], v149 offset:36864
	ds_read_b128 v[218:221], v149 offset:37888
	ds_read_b128 v[222:225], v149 offset:38912
	ds_read_b128 v[226:229], v149 offset:39936
	global_load_lds_dwordx4 v[236:237], off
	v_lshl_add_u64 v[236:237], s[10:11], 0, v[132:133]
	s_mov_b32 m0, s17
	s_nop 0
	global_load_lds_dwordx4 v[236:237], off
	s_waitcnt vmcnt(8) lgkmcnt(0)
	s_barrier
	s_setprio 1
	v_mfma_f32_16x16x32_bf16 v[126:129], v[140:143], v[178:181], v[126:129]
	v_mfma_f32_16x16x32_bf16 v[122:125], v[154:157], v[178:181], v[122:125]
	v_mfma_f32_16x16x32_bf16 v[110:113], v[140:143], v[186:189], v[110:113]
	v_mfma_f32_16x16x32_bf16 v[106:109], v[154:157], v[186:189], v[106:109]
	v_mfma_f32_16x16x32_bf16 v[94:97], v[140:143], v[214:217], v[94:97]
	v_mfma_f32_16x16x32_bf16 v[90:93], v[154:157], v[214:217], v[90:93]
	v_mfma_f32_16x16x32_bf16 v[78:81], v[140:143], v[222:225], v[78:81]
	v_mfma_f32_16x16x32_bf16 v[74:77], v[154:157], v[222:225], v[74:77]
	v_mfma_f32_16x16x32_bf16 v[126:129], v[150:153], v[182:185], v[126:129]
	v_mfma_f32_16x16x32_bf16 v[122:125], v[158:161], v[182:185], v[122:125]
	v_mfma_f32_16x16x32_bf16 v[110:113], v[150:153], v[190:193], v[110:113]
	v_mfma_f32_16x16x32_bf16 v[106:109], v[158:161], v[190:193], v[106:109]
	v_mfma_f32_16x16x32_bf16 v[94:97], v[150:153], v[218:221], v[94:97]
	v_mfma_f32_16x16x32_bf16 v[90:93], v[158:161], v[218:221], v[90:93]
	v_mfma_f32_16x16x32_bf16 v[78:81], v[150:153], v[226:229], v[78:81]
	v_mfma_f32_16x16x32_bf16 v[74:77], v[158:161], v[226:229], v[74:77]
	v_mfma_f32_16x16x32_bf16 v[118:121], v[162:165], v[178:181], v[118:121]
	v_mfma_f32_16x16x32_bf16 v[114:117], v[170:173], v[178:181], v[114:117]
	v_mfma_f32_16x16x32_bf16 v[102:105], v[162:165], v[186:189], v[102:105]
	v_mfma_f32_16x16x32_bf16 v[98:101], v[170:173], v[186:189], v[98:101]
	v_mfma_f32_16x16x32_bf16 v[86:89], v[162:165], v[214:217], v[86:89]
	v_mfma_f32_16x16x32_bf16 v[82:85], v[170:173], v[214:217], v[82:85]
	v_mfma_f32_16x16x32_bf16 v[70:73], v[162:165], v[222:225], v[70:73]
	v_mfma_f32_16x16x32_bf16 v[66:69], v[170:173], v[222:225], v[66:69]
	v_mfma_f32_16x16x32_bf16 v[118:121], v[166:169], v[182:185], v[118:121]
	v_mfma_f32_16x16x32_bf16 v[114:117], v[174:177], v[182:185], v[114:117]
	v_mfma_f32_16x16x32_bf16 v[102:105], v[166:169], v[190:193], v[102:105]
	v_mfma_f32_16x16x32_bf16 v[98:101], v[174:177], v[190:193], v[98:101]
	v_mfma_f32_16x16x32_bf16 v[86:89], v[166:169], v[218:221], v[86:89]
	v_mfma_f32_16x16x32_bf16 v[82:85], v[174:177], v[218:221], v[82:85]
	v_mfma_f32_16x16x32_bf16 v[70:73], v[166:169], v[226:229], v[70:73]
	v_mfma_f32_16x16x32_bf16 v[66:69], v[174:177], v[226:229], v[66:69]
	s_setprio 0
	s_barrier
; #define PG8_STAGE(bufoff, gbase, voff) do { _Pragma("unroll") for (int _i = 0; _i < 2; ++_i) \
;         __builtin_amdgcn_global_load_lds((const unsigned*)((const char*)(gbase) + (voff)[_i]), (LAS unsigned*)(lds + (bufoff) + ldsw + _i * 8192), 16, 0, 0); } while (0)
; #define PG8_LDA(dst, b, h) do { _Pragma("unroll") for (int m = 0; m < 4; ++m) _Pragma("unroll") for (int k = 0; k < 2; ++k) dst[m][k] = *(const LAS bf16x8*)(lds + PG8_SA(b, h) + aoff + m * 2048 + k * 1024); } while (0)
; #define PG8_MMA(ai, bj, At, Bt) do { __builtin_amdgcn_s_setprio(1); _Pragma("unroll") for (int m = 0; m < 4; ++m) _Pragma("unroll") for (int n = 0; n < 2; ++n) _Pragma("unroll") for (int k = 0; k < 2; ++k) \
;         acc[ai][bj][m][n] = __builtin_amdgcn_mfma_f32_16x16x32_bf16(Bt[n][k], At[m][k], acc[ai][bj][m][n], 0, 0, 0); __builtin_amdgcn_s_setprio(0); } while (0)
; #define PG8_WAIT_V(n) asm volatile("s_waitcnt vmcnt(" #n ")" ::: "memory")
; #define PG8_WAIT_L(n) asm volatile("s_waitcnt lgkmcnt(" #n ")" ::: "memory")
; #define PG8_BAR __builtin_amdgcn_s_barrier()
; #define PG8_SCHED __builtin_amdgcn_sched_barrier(0)
; template <class Epi, bool SP2, class Sched>
; __device__ __forceinline__ void gemm_phase(LAS unsigned char* lds, const Gemm g, const Sched& S, const Epi& E) {
;     ...
;             PG8_LDA(At, 1, 1); PG8_STAGE(PG8_SB(1, 0), b3, voffB); PG8_STAGE(PG8_SB(1, 1), b3 + hstepB, voffB); PG8_STAGE(PG8_SA(1, 0), a3, voffA);
;             PG8_WAIT_V(8); PG8_WAIT_L(0); PG8_BAR; PG8_MMA(1, 0, At, B0); PG8_MMA(1, 1, At, B1); PG8_BAR; PG8_SCHED;
;     ...
;         if (wr == 0) PG8_BAR;
	s_add_i32 s10, s22, s12
	v_lshl_add_u64 v[144:145], v[144:145], 0, s[66:67]
	s_mov_b32 m0, s10
	ds_read_b128 v[178:181], v149 offset:49152
	ds_read_b128 v[182:185], v149 offset:50176
	ds_read_b128 v[186:189], v149 offset:51200
	ds_read_b128 v[190:193], v149 offset:52224
	ds_read_b128 v[214:217], v149 offset:53248
	ds_read_b128 v[218:221], v149 offset:54272
	ds_read_b128 v[222:225], v149 offset:55296
	ds_read_b128 v[226:229], v149 offset:56320
	global_load_lds_dwordx4 v[144:145], off
	s_add_i32 m0, s10, 0x2000
	s_add_u32 s6, s6, 0x40080
	v_lshl_add_u64 v[144:145], v[230:231], 0, s[66:67]
	s_addc_u32 s7, s7, 0
	s_add_i32 s10, s23, s12
	global_load_lds_dwordx4 v[144:145], off
	v_lshl_add_u64 v[144:145], s[6:7], 0, v[64:65]
	s_mov_b32 m0, s10
	s_nop 0
	global_load_lds_dwordx4 v[144:145], off
	v_lshl_add_u64 v[144:145], s[6:7], 0, v[134:135]
	s_add_i32 m0, s10, 0x2000
	s_nop 0
	global_load_lds_dwordx4 v[144:145], off
	v_lshl_add_u64 v[144:145], v[232:233], 0, s[66:67]
	s_mov_b32 m0, s18
	s_nop 0
	global_load_lds_dwordx4 v[144:145], off
	v_lshl_add_u64 v[144:145], v[234:235], 0, s[66:67]
	s_mov_b32 m0, s19
	s_nop 0
	global_load_lds_dwordx4 v[144:145], off
	s_waitcnt vmcnt(8) lgkmcnt(0)
	s_barrier
	s_setprio 1
	v_mfma_f32_16x16x32_bf16 v[60:63], v[140:143], v[178:181], v[60:63]
	v_mfma_f32_16x16x32_bf16 v[56:59], v[154:157], v[178:181], v[56:59]
	v_mfma_f32_16x16x32_bf16 v[44:47], v[140:143], v[186:189], v[44:47]
	v_mfma_f32_16x16x32_bf16 v[40:43], v[154:157], v[186:189], v[40:43]
	v_mfma_f32_16x16x32_bf16 v[28:31], v[140:143], v[214:217], v[28:31]
	v_mfma_f32_16x16x32_bf16 v[24:27], v[154:157], v[214:217], v[24:27]
	v_mfma_f32_16x16x32_bf16 v[12:15], v[140:143], v[222:225], v[12:15]
	v_mfma_f32_16x16x32_bf16 v[8:11], v[154:157], v[222:225], v[8:11]
	v_mfma_f32_16x16x32_bf16 v[60:63], v[150:153], v[182:185], v[60:63]
	v_mfma_f32_16x16x32_bf16 v[56:59], v[158:161], v[182:185], v[56:59]
	v_mfma_f32_16x16x32_bf16 v[44:47], v[150:153], v[190:193], v[44:47]
	v_mfma_f32_16x16x32_bf16 v[40:43], v[158:161], v[190:193], v[40:43]
	v_mfma_f32_16x16x32_bf16 v[28:31], v[150:153], v[218:221], v[28:31]
	v_mfma_f32_16x16x32_bf16 v[24:27], v[158:161], v[218:221], v[24:27]
	v_mfma_f32_16x16x32_bf16 v[12:15], v[150:153], v[226:229], v[12:15]
	v_mfma_f32_16x16x32_bf16 v[8:11], v[158:161], v[226:229], v[8:11]
	v_mfma_f32_16x16x32_bf16 v[52:55], v[162:165], v[178:181], v[52:55]
	v_mfma_f32_16x16x32_bf16 v[48:51], v[170:173], v[178:181], v[48:51]
	v_mfma_f32_16x16x32_bf16 v[36:39], v[162:165], v[186:189], v[36:39]
	v_mfma_f32_16x16x32_bf16 v[32:35], v[170:173], v[186:189], v[32:35]
	v_mfma_f32_16x16x32_bf16 v[20:23], v[162:165], v[214:217], v[20:23]
	v_mfma_f32_16x16x32_bf16 v[16:19], v[170:173], v[214:217], v[16:19]
	v_mfma_f32_16x16x32_bf16 v[4:7], v[162:165], v[222:225], v[4:7]
	v_mfma_f32_16x16x32_bf16 v[0:3], v[170:173], v[222:225], v[0:3]
	v_mfma_f32_16x16x32_bf16 v[52:55], v[166:169], v[182:185], v[52:55]
	v_mfma_f32_16x16x32_bf16 v[48:51], v[174:177], v[182:185], v[48:51]
	v_mfma_f32_16x16x32_bf16 v[36:39], v[166:169], v[190:193], v[36:39]
	v_mfma_f32_16x16x32_bf16 v[32:35], v[174:177], v[190:193], v[32:35]
	v_mfma_f32_16x16x32_bf16 v[20:23], v[166:169], v[218:221], v[20:23]
	v_mfma_f32_16x16x32_bf16 v[16:19], v[174:177], v[218:221], v[16:19]
	v_mfma_f32_16x16x32_bf16 v[4:7], v[166:169], v[226:229], v[4:7]
	v_mfma_f32_16x16x32_bf16 v[0:3], v[174:177], v[226:229], v[0:3]
	s_setprio 0
	s_barrier
	s_add_i32 s21, s21, 2
	s_add_u32 s76, s76, 0x100
	s_addc_u32 s20, s20, 0
	s_add_u32 s92, s92, 0x100
	s_addc_u32 s93, s93, 0
	s_cmp_gt_u32 s21, 13
	s_cbranch_scc0 .LBB0_955
	s_and_b64 vcc, exec, s[60:61]
	s_cbranch_vccz .LBB0_958
	s_barrier

; #define PG8_STAGE(bufoff, gbase, voff) do { _Pragma("unroll") for (int _i = 0; _i < 2; ++_i) \
;         __builtin_amdgcn_global_load_lds((const unsigned*)((const char*)(gbase) + (voff)[_i]), (LAS unsigned*)(lds + (bufoff) + ldsw + _i * 8192), 16, 0, 0); } while (0)
; #define PG8_LDA(dst, b, h) do { _Pragma("unroll") for (int m = 0; m < 4; ++m) _Pragma("unroll") for (int k = 0; k < 2; ++k) dst[m][k] = *(const LAS bf16x8*)(lds + PG8_SA(b, h) + aoff + m * 2048 + k * 1024); } while (0)
; #define PG8_LDB(dst, b, h) do { _Pragma("unroll") for (int n = 0; n < 2; ++n) _Pragma("unroll") for (int k = 0; k < 2; ++k) dst[n][k] = *(const LAS bf16x8*)(lds + PG8_SB(b, h) + boff + n * 2048 + k * 1024); } while (0)
; #define PG8_MMA(ai, bj, At, Bt) do { __builtin_amdgcn_s_setprio(1); _Pragma("unroll") for (int m = 0; m < 4; ++m) _Pragma("unroll") for (int n = 0; n < 2; ++n) _Pragma("unroll") for (int k = 0; k < 2; ++k) \
;         acc[ai][bj][m][n] = __builtin_amdgcn_mfma_f32_16x16x32_bf16(Bt[n][k], At[m][k], acc[ai][bj][m][n], 0, 0, 0); __builtin_amdgcn_s_setprio(0); } while (0)
; #define PG8_WAIT_V(n) asm volatile("s_waitcnt vmcnt(" #n ")" ::: "memory")
; #define PG8_WAIT_L(n) asm volatile("s_waitcnt lgkmcnt(" #n ")" ::: "memory")
; #define PG8_BAR __builtin_amdgcn_s_barrier()
; template <class Epi, bool SP2, class Sched>
; __device__ __forceinline__ void gemm_phase(LAS unsigned char* lds, const Gemm g, const Sched& S, const Epi& E) {
;     ...
;             const bool last = (t == nt - 2);
;             const char* a1 = cA + (size_t)(t + 1) * kstep;
;             const char* a2 = last ? nA : cA + (size_t)(t + 2) * kstep; const char* b2 = last ? nB : cB + (size_t)(t + 2) * kstep;
;             const char* a3 = a2 + kstep; const char* b3 = b2 + kstep;
;             if constexpr (Epi::MID) { if (t == (nt >> 1)) E.mid(acc, cur, wr, fr); }
;             if constexpr (SP2) {
;             PG8_LDB(B0, 0, 0); PG8_LDB(B1, 0, 1); PG8_SCHED; PG8_LDA(At, 0, 0); PG8_STAGE(PG8_SA(1, 1), a1 + hstep, voffA);
;             PG8_WAIT_V(8); PG8_WAIT_L(0); PG8_BAR; PG8_MMA(0, 0, At, B0); PG8_MMA(0, 1, At, B1); PG8_BAR; PG8_SCHED;
;             PG8_LDA(At, 0, 1); PG8_STAGE(PG8_SB(0, 0), b2, voffB); PG8_STAGE(PG8_SB(0, 1), b2 + hstepB, voffB); PG8_STAGE(PG8_SA(0, 0), a2, voffA);
;             PG8_WAIT_V(8); PG8_WAIT_L(0); PG8_BAR; PG8_MMA(1, 0, At, B0); PG8_MMA(1, 1, At, B1); PG8_BAR; PG8_SCHED;
.LBB0_1039:
	s_add_u32 s6, s16, 0xfffc0080
	s_addc_u32 s7, s17, -1
	s_add_i32 s19, 0, 0x10000
	s_cmp_eq_u32 s18, 12
	s_cselect_b32 s11, s8, s7
	s_cselect_b32 s10, s9, s6
	s_cselect_b32 s7, s12, s15
	s_cselect_b32 s6, s13, s14
	s_add_i32 s22, 0, 0x14000
	v_add_u32_e32 v156, s19, v145
	v_add_u32_e32 v172, s22, v145
	ds_read_b128 v[140:143], v156
	ds_read_b128 v[148:151], v156 offset:1024
	ds_read_b128 v[152:155], v156 offset:2048
	ds_read_b128 v[156:159], v156 offset:3072
	ds_read_b128 v[160:163], v172
	ds_read_b128 v[164:167], v172 offset:1024
	ds_read_b128 v[168:171], v172 offset:2048
	ds_read_b128 v[172:175], v172 offset:3072
	v_lshl_add_u64 v[192:193], s[16:17], 0, v[138:139]
	s_add_i32 m0, s83, 0xc000
	ds_read_b128 v[176:179], v147
	ds_read_b128 v[180:183], v147 offset:1024
	ds_read_b128 v[184:187], v147 offset:2048
	ds_read_b128 v[188:191], v147 offset:3072
	ds_read_b128 v[214:217], v147 offset:4096
	ds_read_b128 v[218:221], v147 offset:5120
	ds_read_b128 v[222:225], v147 offset:6144
	ds_read_b128 v[226:229], v147 offset:7168
	global_load_lds_dwordx4 v[192:193], off
	v_lshl_add_u64 v[192:193], s[16:17], 0, v[136:137]
	s_add_i32 m0, s83, 0xe000
	s_nop 0
	global_load_lds_dwordx4 v[192:193], off
	s_waitcnt vmcnt(8) lgkmcnt(0)
	s_barrier
	s_setprio 1
	v_mfma_f32_16x16x32_bf16 v[126:129], v[140:143], v[176:179], v[126:129]
	v_mfma_f32_16x16x32_bf16 v[122:125], v[152:155], v[176:179], v[122:125]
	v_mfma_f32_16x16x32_bf16 v[110:113], v[140:143], v[184:187], v[110:113]
	v_mfma_f32_16x16x32_bf16 v[106:109], v[152:155], v[184:187], v[106:109]
	v_mfma_f32_16x16x32_bf16 v[94:97], v[140:143], v[214:217], v[94:97]
	v_mfma_f32_16x16x32_bf16 v[90:93], v[152:155], v[214:217], v[90:93]
	v_mfma_f32_16x16x32_bf16 v[78:81], v[140:143], v[222:225], v[78:81]
	v_mfma_f32_16x16x32_bf16 v[74:77], v[152:155], v[222:225], v[74:77]
	v_mfma_f32_16x16x32_bf16 v[126:129], v[148:151], v[180:183], v[126:129]
	v_mfma_f32_16x16x32_bf16 v[122:125], v[156:159], v[180:183], v[122:125]
	v_mfma_f32_16x16x32_bf16 v[110:113], v[148:151], v[188:191], v[110:113]
	v_mfma_f32_16x16x32_bf16 v[106:109], v[156:159], v[188:191], v[106:109]
	v_mfma_f32_16x16x32_bf16 v[94:97], v[148:151], v[218:221], v[94:97]
	v_mfma_f32_16x16x32_bf16 v[90:93], v[156:159], v[218:221], v[90:93]
	v_mfma_f32_16x16x32_bf16 v[78:81], v[148:151], v[226:229], v[78:81]
	v_mfma_f32_16x16x32_bf16 v[74:77], v[156:159], v[226:229], v[74:77]
	v_mfma_f32_16x16x32_bf16 v[118:121], v[160:163], v[176:179], v[118:121]
	v_mfma_f32_16x16x32_bf16 v[114:117], v[168:171], v[176:179], v[114:117]
	v_mfma_f32_16x16x32_bf16 v[102:105], v[160:163], v[184:187], v[102:105]
	v_mfma_f32_16x16x32_bf16 v[98:101], v[168:171], v[184:187], v[98:101]
	v_mfma_f32_16x16x32_bf16 v[86:89], v[160:163], v[214:217], v[86:89]
	v_mfma_f32_16x16x32_bf16 v[82:85], v[168:171], v[214:217], v[82:85]
	v_mfma_f32_16x16x32_bf16 v[70:73], v[160:163], v[222:225], v[70:73]
	v_mfma_f32_16x16x32_bf16 v[66:69], v[168:171], v[222:225], v[66:69]
	v_mfma_f32_16x16x32_bf16 v[118:121], v[164:167], v[180:183], v[118:121]
	v_mfma_f32_16x16x32_bf16 v[114:117], v[172:175], v[180:183], v[114:117]
	v_mfma_f32_16x16x32_bf16 v[102:105], v[164:167], v[188:191], v[102:105]
	v_mfma_f32_16x16x32_bf16 v[98:101], v[172:175], v[188:191], v[98:101]
	v_mfma_f32_16x16x32_bf16 v[86:89], v[164:167], v[218:221], v[86:89]
	v_mfma_f32_16x16x32_bf16 v[82:85], v[172:175], v[218:221], v[82:85]
	v_mfma_f32_16x16x32_bf16 v[70:73], v[164:167], v[226:229], v[70:73]
	v_mfma_f32_16x16x32_bf16 v[66:69], v[172:175], v[226:229], v[66:69]
	s_setprio 0
	s_barrier
	s_add_i32 s19, s19, s79
	v_lshl_add_u64 v[192:193], s[6:7], 0, v[64:65]
	s_mov_b32 m0, s19
	ds_read_b128 v[176:179], v147 offset:16384
	ds_read_b128 v[180:183], v147 offset:17408
	ds_read_b128 v[184:187], v147 offset:18432
	ds_read_b128 v[188:191], v147 offset:19456
	ds_read_b128 v[214:217], v147 offset:20480
	ds_read_b128 v[218:221], v147 offset:21504
	ds_read_b128 v[222:225], v147 offset:22528
	ds_read_b128 v[226:229], v147 offset:23552
	global_load_lds_dwordx4 v[192:193], off
	s_add_i32 m0, s19, 0x2000
	s_add_u32 s20, s6, 0x40000
	v_lshl_add_u64 v[230:231], s[6:7], 0, v[130:131]
	s_addc_u32 s21, s7, 0
	s_add_i32 s19, s22, s79
	global_load_lds_dwordx4 v[230:231], off
	v_lshl_add_u64 v[232:233], s[20:21], 0, v[64:65]
	s_mov_b32 m0, s19
	v_lshl_add_u64 v[234:235], s[10:11], 0, v[132:133]
	global_load_lds_dwordx4 v[232:233], off
	v_lshl_add_u64 v[232:233], s[20:21], 0, v[130:131]
	s_add_i32 m0, s19, 0x2000
	s_nop 0
	global_load_lds_dwordx4 v[232:233], off
	v_lshl_add_u64 v[232:233], s[10:11], 0, v[134:135]
	s_mov_b32 m0, s83
	s_nop 0
	global_load_lds_dwordx4 v[232:233], off
	s_mov_b32 m0, s90
	s_nop 0
	global_load_lds_dwordx4 v[234:235], off
	s_waitcnt vmcnt(8) lgkmcnt(0)
	s_barrier
; #define PG8_STAGE(bufoff, gbase, voff) do { _Pragma("unroll") for (int _i = 0; _i < 2; ++_i) \
;         __builtin_amdgcn_global_load_lds((const unsigned*)((const char*)(gbase) + (voff)[_i]), (LAS unsigned*)(lds + (bufoff) + ldsw + _i * 8192), 16, 0, 0); } while (0)
; #define PG8_LDA(dst, b, h) do { _Pragma("unroll") for (int m = 0; m < 4; ++m) _Pragma("unroll") for (int k = 0; k < 2; ++k) dst[m][k] = *(const LAS bf16x8*)(lds + PG8_SA(b, h) + aoff + m * 2048 + k * 1024); } while (0)
; #define PG8_LDB(dst, b, h) do { _Pragma("unroll") for (int n = 0; n < 2; ++n) _Pragma("unroll") for (int k = 0; k < 2; ++k) dst[n][k] = *(const LAS bf16x8*)(lds + PG8_SB(b, h) + boff + n * 2048 + k * 1024); } while (0)
; #define PG8_MMA(ai, bj, At, Bt) do { __builtin_amdgcn_s_setprio(1); _Pragma("unroll") for (int m = 0; m < 4; ++m) _Pragma("unroll") for (int n = 0; n < 2; ++n) _Pragma("unroll") for (int k = 0; k < 2; ++k) \
;         acc[ai][bj][m][n] = __builtin_amdgcn_mfma_f32_16x16x32_bf16(Bt[n][k], At[m][k], acc[ai][bj][m][n], 0, 0, 0); __builtin_amdgcn_s_setprio(0); } while (0)
; #define PG8_WAIT_V(n) asm volatile("s_waitcnt vmcnt(" #n ")" ::: "memory")
; #define PG8_WAIT_L(n) asm volatile("s_waitcnt lgkmcnt(" #n ")" ::: "memory")
; #define PG8_BAR __builtin_amdgcn_s_barrier()
; #define PG8_SCHED __builtin_amdgcn_sched_barrier(0)
; template <class Epi, bool SP2, class Sched>
; __device__ __forceinline__ void gemm_phase(LAS unsigned char* lds, const Gemm g, const Sched& S, const Epi& E) {
;     ...
;             PG8_WAIT_V(8); PG8_WAIT_L(0); PG8_BAR; PG8_MMA(1, 0, At, B0); PG8_MMA(1, 1, At, B1); PG8_BAR; PG8_SCHED;
;             PG8_LDB(B0, 1, 0); PG8_LDB(B1, 1, 1); PG8_SCHED; PG8_LDA(At, 1, 0); PG8_STAGE(PG8_SA(0, 1), a2 + hstep, voffA);
;             PG8_WAIT_V(8); PG8_WAIT_L(0); PG8_BAR; PG8_MMA(0, 0, At, B0); PG8_MMA(0, 1, At, B1); PG8_BAR; PG8_SCHED;
	s_setprio 1
	v_mfma_f32_16x16x32_bf16 v[60:63], v[140:143], v[176:179], v[60:63]
	v_mfma_f32_16x16x32_bf16 v[56:59], v[152:155], v[176:179], v[56:59]
	v_mfma_f32_16x16x32_bf16 v[44:47], v[140:143], v[184:187], v[44:47]
	v_mfma_f32_16x16x32_bf16 v[40:43], v[152:155], v[184:187], v[40:43]
	v_mfma_f32_16x16x32_bf16 v[28:31], v[140:143], v[214:217], v[28:31]
	v_mfma_f32_16x16x32_bf16 v[24:27], v[152:155], v[214:217], v[24:27]
	v_mfma_f32_16x16x32_bf16 v[12:15], v[140:143], v[222:225], v[12:15]
	v_mfma_f32_16x16x32_bf16 v[8:11], v[152:155], v[222:225], v[8:11]
	v_mfma_f32_16x16x32_bf16 v[60:63], v[148:151], v[180:183], v[60:63]
	v_mfma_f32_16x16x32_bf16 v[56:59], v[156:159], v[180:183], v[56:59]
	v_mfma_f32_16x16x32_bf16 v[44:47], v[148:151], v[188:191], v[44:47]
	v_mfma_f32_16x16x32_bf16 v[40:43], v[156:159], v[188:191], v[40:43]
	v_mfma_f32_16x16x32_bf16 v[28:31], v[148:151], v[218:221], v[28:31]
	v_mfma_f32_16x16x32_bf16 v[24:27], v[156:159], v[218:221], v[24:27]
	v_mfma_f32_16x16x32_bf16 v[12:15], v[148:151], v[226:229], v[12:15]
	v_mfma_f32_16x16x32_bf16 v[8:11], v[156:159], v[226:229], v[8:11]
	v_mfma_f32_16x16x32_bf16 v[52:55], v[160:163], v[176:179], v[52:55]
	v_mfma_f32_16x16x32_bf16 v[48:51], v[168:171], v[176:179], v[48:51]
	v_mfma_f32_16x16x32_bf16 v[36:39], v[160:163], v[184:187], v[36:39]
	v_mfma_f32_16x16x32_bf16 v[32:35], v[168:171], v[184:187], v[32:35]
	v_mfma_f32_16x16x32_bf16 v[20:23], v[160:163], v[214:217], v[20:23]
	v_mfma_f32_16x16x32_bf16 v[16:19], v[168:171], v[214:217], v[16:19]
	v_mfma_f32_16x16x32_bf16 v[4:7], v[160:163], v[222:225], v[4:7]
	v_mfma_f32_16x16x32_bf16 v[0:3], v[168:171], v[222:225], v[0:3]
	v_mfma_f32_16x16x32_bf16 v[52:55], v[164:167], v[180:183], v[52:55]
	v_mfma_f32_16x16x32_bf16 v[48:51], v[172:175], v[180:183], v[48:51]
	v_mfma_f32_16x16x32_bf16 v[36:39], v[164:167], v[188:191], v[36:39]
	v_mfma_f32_16x16x32_bf16 v[32:35], v[172:175], v[188:191], v[32:35]
	v_mfma_f32_16x16x32_bf16 v[20:23], v[164:167], v[218:221], v[20:23]
	v_mfma_f32_16x16x32_bf16 v[16:19], v[172:175], v[218:221], v[16:19]
	v_mfma_f32_16x16x32_bf16 v[4:7], v[164:167], v[226:229], v[4:7]
	v_mfma_f32_16x16x32_bf16 v[0:3], v[172:175], v[226:229], v[0:3]
	s_setprio 0
	s_barrier
	s_add_i32 s19, 0, 0x18000
	s_add_i32 s20, 0, 0x1c000
	v_add_u32_e32 v156, s19, v145
	v_add_u32_e32 v172, s20, v145
	ds_read_b128 v[140:143], v156
	ds_read_b128 v[148:151], v156 offset:1024
	ds_read_b128 v[152:155], v156 offset:2048
	ds_read_b128 v[156:159], v156 offset:3072
	ds_read_b128 v[160:163], v172
	ds_read_b128 v[164:167], v172 offset:1024
	ds_read_b128 v[168:171], v172 offset:2048
	ds_read_b128 v[172:175], v172 offset:3072
	s_add_u32 s10, s10, 0x40000
	s_addc_u32 s11, s11, 0
	s_mov_b32 m0, s91
	v_lshl_add_u64 v[236:237], s[10:11], 0, v[134:135]
	ds_read_b128 v[176:179], v147 offset:32768
	ds_read_b128 v[180:183], v147 offset:33792
	ds_read_b128 v[184:187], v147 offset:34816
	ds_read_b128 v[188:191], v147 offset:35840
	ds_read_b128 v[214:217], v147 offset:36864
	ds_read_b128 v[218:221], v147 offset:37888
	ds_read_b128 v[222:225], v147 offset:38912
	ds_read_b128 v[226:229], v147 offset:39936
	global_load_lds_dwordx4 v[236:237], off
	v_lshl_add_u64 v[236:237], s[10:11], 0, v[132:133]
	s_mov_b32 m0, s92
	s_nop 0
	global_load_lds_dwordx4 v[236:237], off
	s_waitcnt vmcnt(8) lgkmcnt(0)
	s_barrier
	s_setprio 1
	v_mfma_f32_16x16x32_bf16 v[126:129], v[140:143], v[176:179], v[126:129]
	v_mfma_f32_16x16x32_bf16 v[122:125], v[152:155], v[176:179], v[122:125]
	v_mfma_f32_16x16x32_bf16 v[110:113], v[140:143], v[184:187], v[110:113]
	v_mfma_f32_16x16x32_bf16 v[106:109], v[152:155], v[184:187], v[106:109]
	v_mfma_f32_16x16x32_bf16 v[94:97], v[140:143], v[214:217], v[94:97]
	v_mfma_f32_16x16x32_bf16 v[90:93], v[152:155], v[214:217], v[90:93]
	v_mfma_f32_16x16x32_bf16 v[78:81], v[140:143], v[222:225], v[78:81]
	v_mfma_f32_16x16x32_bf16 v[74:77], v[152:155], v[222:225], v[74:77]
	v_mfma_f32_16x16x32_bf16 v[126:129], v[148:151], v[180:183], v[126:129]
	v_mfma_f32_16x16x32_bf16 v[122:125], v[156:159], v[180:183], v[122:125]
	v_mfma_f32_16x16x32_bf16 v[110:113], v[148:151], v[188:191], v[110:113]
	v_mfma_f32_16x16x32_bf16 v[106:109], v[156:159], v[188:191], v[106:109]
	v_mfma_f32_16x16x32_bf16 v[94:97], v[148:151], v[218:221], v[94:97]
	v_mfma_f32_16x16x32_bf16 v[90:93], v[156:159], v[218:221], v[90:93]
	v_mfma_f32_16x16x32_bf16 v[78:81], v[148:151], v[226:229], v[78:81]
	v_mfma_f32_16x16x32_bf16 v[74:77], v[156:159], v[226:229], v[74:77]
	v_mfma_f32_16x16x32_bf16 v[118:121], v[160:163], v[176:179], v[118:121]
	v_mfma_f32_16x16x32_bf16 v[114:117], v[168:171], v[176:179], v[114:117]
	v_mfma_f32_16x16x32_bf16 v[102:105], v[160:163], v[184:187], v[102:105]
	v_mfma_f32_16x16x32_bf16 v[98:101], v[168:171], v[184:187], v[98:101]
	v_mfma_f32_16x16x32_bf16 v[86:89], v[160:163], v[214:217], v[86:89]
	v_mfma_f32_16x16x32_bf16 v[82:85], v[168:171], v[214:217], v[82:85]
	v_mfma_f32_16x16x32_bf16 v[70:73], v[160:163], v[222:225], v[70:73]
	v_mfma_f32_16x16x32_bf16 v[66:69], v[168:171], v[222:225], v[66:69]
	v_mfma_f32_16x16x32_bf16 v[118:121], v[164:167], v[180:183], v[118:121]
	v_mfma_f32_16x16x32_bf16 v[114:117], v[172:175], v[180:183], v[114:117]
	v_mfma_f32_16x16x32_bf16 v[102:105], v[164:167], v[188:191], v[102:105]
	v_mfma_f32_16x16x32_bf16 v[98:101], v[172:175], v[188:191], v[98:101]
	v_mfma_f32_16x16x32_bf16 v[86:89], v[164:167], v[218:221], v[86:89]
	v_mfma_f32_16x16x32_bf16 v[82:85], v[172:175], v[218:221], v[82:85]
	v_mfma_f32_16x16x32_bf16 v[70:73], v[164:167], v[226:229], v[70:73]
	v_mfma_f32_16x16x32_bf16 v[66:69], v[172:175], v[226:229], v[66:69]
	s_setprio 0
	s_barrier
; #define PG8_STAGE(bufoff, gbase, voff) do { _Pragma("unroll") for (int _i = 0; _i < 2; ++_i) \
;         __builtin_amdgcn_global_load_lds((const unsigned*)((const char*)(gbase) + (voff)[_i]), (LAS unsigned*)(lds + (bufoff) + ldsw + _i * 8192), 16, 0, 0); } while (0)
; #define PG8_LDA(dst, b, h) do { _Pragma("unroll") for (int m = 0; m < 4; ++m) _Pragma("unroll") for (int k = 0; k < 2; ++k) dst[m][k] = *(const LAS bf16x8*)(lds + PG8_SA(b, h) + aoff + m * 2048 + k * 1024); } while (0)
; #define PG8_MMA(ai, bj, At, Bt) do { __builtin_amdgcn_s_setprio(1); _Pragma("unroll") for (int m = 0; m < 4; ++m) _Pragma("unroll") for (int n = 0; n < 2; ++n) _Pragma("unroll") for (int k = 0; k < 2; ++k) \
;         acc[ai][bj][m][n] = __builtin_amdgcn_mfma_f32_16x16x32_bf16(Bt[n][k], At[m][k], acc[ai][bj][m][n], 0, 0, 0); __builtin_amdgcn_s_setprio(0); } while (0)
; #define PG8_WAIT_V(n) asm volatile("s_waitcnt vmcnt(" #n ")" ::: "memory")
; #define PG8_WAIT_L(n) asm volatile("s_waitcnt lgkmcnt(" #n ")" ::: "memory")
; #define PG8_BAR __builtin_amdgcn_s_barrier()
; #define PG8_SCHED __builtin_amdgcn_sched_barrier(0)
; template <class Epi, bool SP2, class Sched>
; __device__ __forceinline__ void gemm_phase(LAS unsigned char* lds, const Gemm g, const Sched& S, const Epi& E) {
;     ...
;             PG8_LDA(At, 1, 1); PG8_STAGE(PG8_SB(1, 0), b3, voffB); PG8_STAGE(PG8_SB(1, 1), b3 + hstepB, voffB); PG8_STAGE(PG8_SA(1, 0), a3, voffA);
;             PG8_WAIT_V(8); PG8_WAIT_L(0); PG8_BAR; PG8_MMA(1, 0, At, B0); PG8_MMA(1, 1, At, B1); PG8_BAR; PG8_SCHED;
;     ...
;         if (wr == 0) PG8_BAR;
	s_add_i32 s10, s19, s79
	v_lshl_add_u64 v[192:193], v[192:193], 0, s[66:67]
	s_mov_b32 m0, s10
	ds_read_b128 v[176:179], v147 offset:49152
	ds_read_b128 v[180:183], v147 offset:50176
	ds_read_b128 v[184:187], v147 offset:51200
	ds_read_b128 v[188:191], v147 offset:52224
	ds_read_b128 v[214:217], v147 offset:53248
	ds_read_b128 v[218:221], v147 offset:54272
	ds_read_b128 v[222:225], v147 offset:55296
	ds_read_b128 v[226:229], v147 offset:56320
	global_load_lds_dwordx4 v[192:193], off
	s_add_i32 m0, s10, 0x2000
	s_add_u32 s6, s6, 0x40080
	v_lshl_add_u64 v[192:193], v[230:231], 0, s[66:67]
	s_addc_u32 s7, s7, 0
	s_add_i32 s10, s20, s79
	global_load_lds_dwordx4 v[192:193], off
	v_lshl_add_u64 v[192:193], s[6:7], 0, v[64:65]
	s_mov_b32 m0, s10
	s_nop 0
	global_load_lds_dwordx4 v[192:193], off
	v_lshl_add_u64 v[192:193], s[6:7], 0, v[130:131]
	s_add_i32 m0, s10, 0x2000
	s_nop 0
	global_load_lds_dwordx4 v[192:193], off
	v_lshl_add_u64 v[192:193], v[232:233], 0, s[66:67]
	s_mov_b32 m0, s94
	s_nop 0
	global_load_lds_dwordx4 v[192:193], off
	v_lshl_add_u64 v[192:193], v[234:235], 0, s[66:67]
	s_mov_b32 m0, s95
	s_nop 0
	global_load_lds_dwordx4 v[192:193], off
	s_waitcnt vmcnt(8) lgkmcnt(0)
	s_barrier
	s_setprio 1
	v_mfma_f32_16x16x32_bf16 v[60:63], v[140:143], v[176:179], v[60:63]
	v_mfma_f32_16x16x32_bf16 v[56:59], v[152:155], v[176:179], v[56:59]
	v_mfma_f32_16x16x32_bf16 v[44:47], v[140:143], v[184:187], v[44:47]
	v_mfma_f32_16x16x32_bf16 v[40:43], v[152:155], v[184:187], v[40:43]
	v_mfma_f32_16x16x32_bf16 v[28:31], v[140:143], v[214:217], v[28:31]
	v_mfma_f32_16x16x32_bf16 v[24:27], v[152:155], v[214:217], v[24:27]
	v_mfma_f32_16x16x32_bf16 v[12:15], v[140:143], v[222:225], v[12:15]
	v_mfma_f32_16x16x32_bf16 v[8:11], v[152:155], v[222:225], v[8:11]
	v_mfma_f32_16x16x32_bf16 v[60:63], v[148:151], v[180:183], v[60:63]
	v_mfma_f32_16x16x32_bf16 v[56:59], v[156:159], v[180:183], v[56:59]
	v_mfma_f32_16x16x32_bf16 v[44:47], v[148:151], v[188:191], v[44:47]
	v_mfma_f32_16x16x32_bf16 v[40:43], v[156:159], v[188:191], v[40:43]
	v_mfma_f32_16x16x32_bf16 v[28:31], v[148:151], v[218:221], v[28:31]
	v_mfma_f32_16x16x32_bf16 v[24:27], v[156:159], v[218:221], v[24:27]
	v_mfma_f32_16x16x32_bf16 v[12:15], v[148:151], v[226:229], v[12:15]
	v_mfma_f32_16x16x32_bf16 v[8:11], v[156:159], v[226:229], v[8:11]
	v_mfma_f32_16x16x32_bf16 v[52:55], v[160:163], v[176:179], v[52:55]
	v_mfma_f32_16x16x32_bf16 v[48:51], v[168:171], v[176:179], v[48:51]
	v_mfma_f32_16x16x32_bf16 v[36:39], v[160:163], v[184:187], v[36:39]
	v_mfma_f32_16x16x32_bf16 v[32:35], v[168:171], v[184:187], v[32:35]
	v_mfma_f32_16x16x32_bf16 v[20:23], v[160:163], v[214:217], v[20:23]
	v_mfma_f32_16x16x32_bf16 v[16:19], v[168:171], v[214:217], v[16:19]
	v_mfma_f32_16x16x32_bf16 v[4:7], v[160:163], v[222:225], v[4:7]
	v_mfma_f32_16x16x32_bf16 v[0:3], v[168:171], v[222:225], v[0:3]
	v_mfma_f32_16x16x32_bf16 v[52:55], v[164:167], v[180:183], v[52:55]
	v_mfma_f32_16x16x32_bf16 v[48:51], v[172:175], v[180:183], v[48:51]
	v_mfma_f32_16x16x32_bf16 v[36:39], v[164:167], v[188:191], v[36:39]
	v_mfma_f32_16x16x32_bf16 v[32:35], v[172:175], v[188:191], v[32:35]
	v_mfma_f32_16x16x32_bf16 v[20:23], v[164:167], v[218:221], v[20:23]
	v_mfma_f32_16x16x32_bf16 v[16:19], v[172:175], v[218:221], v[16:19]
	v_mfma_f32_16x16x32_bf16 v[4:7], v[164:167], v[226:229], v[4:7]
	v_mfma_f32_16x16x32_bf16 v[0:3], v[172:175], v[226:229], v[0:3]
	s_setprio 0
	s_barrier
	s_add_i32 s18, s18, 2
	s_add_u32 s14, s14, 0x100
	s_addc_u32 s15, s15, 0
	s_add_u32 s16, s16, 0x100
	s_addc_u32 s17, s17, 0
	s_cmp_gt_u32 s18, 13
	s_cbranch_scc0 .LBB0_1039
	s_and_b64 vcc, exec, s[58:59]
	s_cbranch_vccz .LBB0_1042
	s_barrier

; #define PG8_STAGE(bufoff, gbase, voff) do { _Pragma("unroll") for (int _i = 0; _i < 2; ++_i) \
;         __builtin_amdgcn_global_load_lds((const unsigned*)((const char*)(gbase) + (voff)[_i]), (LAS unsigned*)(lds + (bufoff) + ldsw + _i * 8192), 16, 0, 0); } while (0)
; #define PG8_LDA(dst, b, h) do { _Pragma("unroll") for (int m = 0; m < 4; ++m) _Pragma("unroll") for (int k = 0; k < 2; ++k) dst[m][k] = *(const LAS bf16x8*)(lds + PG8_SA(b, h) + aoff + m * 2048 + k * 1024); } while (0)
; #define PG8_LDB(dst, b, h) do { _Pragma("unroll") for (int n = 0; n < 2; ++n) _Pragma("unroll") for (int k = 0; k < 2; ++k) dst[n][k] = *(const LAS bf16x8*)(lds + PG8_SB(b, h) + boff + n * 2048 + k * 1024); } while (0)
; #define PG8_MMA(ai, bj, At, Bt) do { __builtin_amdgcn_s_setprio(1); _Pragma("unroll") for (int m = 0; m < 4; ++m) _Pragma("unroll") for (int n = 0; n < 2; ++n) _Pragma("unroll") for (int k = 0; k < 2; ++k) \
;         acc[ai][bj][m][n] = __builtin_amdgcn_mfma_f32_16x16x32_bf16(Bt[n][k], At[m][k], acc[ai][bj][m][n], 0, 0, 0); __builtin_amdgcn_s_setprio(0); } while (0)
; #define PG8_WAIT_V(n) asm volatile("s_waitcnt vmcnt(" #n ")" ::: "memory")
; #define PG8_WAIT_L(n) asm volatile("s_waitcnt lgkmcnt(" #n ")" ::: "memory")
; #define PG8_BAR __builtin_amdgcn_s_barrier()
; template <class Epi, bool SP2, class Sched>
; __device__ __forceinline__ void gemm_phase(LAS unsigned char* lds, const Gemm g, const Sched& S, const Epi& E) {
;     ...
;             const bool last = (t == nt - 2);
;             const char* a1 = cA + (size_t)(t + 1) * kstep;
;             const char* a2 = last ? nA : cA + (size_t)(t + 2) * kstep; const char* b2 = last ? nB : cB + (size_t)(t + 2) * kstep;
;             const char* a3 = a2 + kstep; const char* b3 = b2 + kstep;
;             if constexpr (Epi::MID) { if (t == (nt >> 1)) E.mid(acc, cur, wr, fr); }
;             if constexpr (SP2) {
;             PG8_LDB(B0, 0, 0); PG8_LDB(B1, 0, 1); PG8_SCHED; PG8_LDA(At, 0, 0); PG8_STAGE(PG8_SA(1, 1), a1 + hstep, voffA);
;             PG8_WAIT_V(8); PG8_WAIT_L(0); PG8_BAR; PG8_MMA(0, 0, At, B0); PG8_MMA(0, 1, At, B1); PG8_BAR; PG8_SCHED;
;             PG8_LDA(At, 0, 1); PG8_STAGE(PG8_SB(0, 0), b2, voffB); PG8_STAGE(PG8_SB(0, 1), b2 + hstepB, voffB); PG8_STAGE(PG8_SA(0, 0), a2, voffA);
;             PG8_WAIT_V(8); PG8_WAIT_L(0); PG8_BAR; PG8_MMA(1, 0, At, B0); PG8_MMA(1, 1, At, B1); PG8_BAR; PG8_SCHED;
.LBB0_1118:
	s_add_u32 s6, s92, 0xfff00080
	s_addc_u32 s7, s93, -1
	s_add_i32 s22, 0, 0x10000
	s_cmp_eq_u32 s21, 60
	s_cselect_b32 s11, s73, s7
	s_cselect_b32 s10, s74, s6
	v_add_u32_e32 v144, s22, v147
	s_cselect_b32 s7, s5, s20
	s_cselect_b32 s6, s75, s76
	s_add_i32 s24, 0, 0x14000
	ds_read_b128 v[140:143], v144
	ds_read_b128 v[150:153], v144 offset:1024
	ds_read_b128 v[154:157], v144 offset:2048
	ds_read_b128 v[158:161], v144 offset:3072
	v_add_u32_e32 v144, s24, v147
	ds_read_b128 v[162:165], v144
	ds_read_b128 v[166:169], v144 offset:1024
	ds_read_b128 v[170:173], v144 offset:2048
	ds_read_b128 v[174:177], v144 offset:3072
	v_lshl_add_u64 v[144:145], s[92:93], 0, v[138:139]
	s_add_i32 m0, s13, 0xc000
	ds_read_b128 v[178:181], v149
	ds_read_b128 v[182:185], v149 offset:1024
	ds_read_b128 v[186:189], v149 offset:2048
	ds_read_b128 v[190:193], v149 offset:3072
	ds_read_b128 v[214:217], v149 offset:4096
	ds_read_b128 v[218:221], v149 offset:5120
	ds_read_b128 v[222:225], v149 offset:6144
	ds_read_b128 v[226:229], v149 offset:7168
	global_load_lds_dwordx4 v[144:145], off
	v_lshl_add_u64 v[144:145], s[92:93], 0, v[136:137]
	s_add_i32 m0, s13, 0xe000
	s_nop 0
	global_load_lds_dwordx4 v[144:145], off
	s_waitcnt vmcnt(8) lgkmcnt(0)
	s_barrier
	s_setprio 1
	v_mfma_f32_16x16x32_bf16 v[126:129], v[140:143], v[178:181], v[126:129]
	v_mfma_f32_16x16x32_bf16 v[122:125], v[154:157], v[178:181], v[122:125]
	v_mfma_f32_16x16x32_bf16 v[110:113], v[140:143], v[186:189], v[110:113]
	v_mfma_f32_16x16x32_bf16 v[106:109], v[154:157], v[186:189], v[106:109]
	v_mfma_f32_16x16x32_bf16 v[94:97], v[140:143], v[214:217], v[94:97]
	v_mfma_f32_16x16x32_bf16 v[90:93], v[154:157], v[214:217], v[90:93]
	v_mfma_f32_16x16x32_bf16 v[78:81], v[140:143], v[222:225], v[78:81]
	v_mfma_f32_16x16x32_bf16 v[74:77], v[154:157], v[222:225], v[74:77]
	v_mfma_f32_16x16x32_bf16 v[126:129], v[150:153], v[182:185], v[126:129]
	v_mfma_f32_16x16x32_bf16 v[122:125], v[158:161], v[182:185], v[122:125]
	v_mfma_f32_16x16x32_bf16 v[110:113], v[150:153], v[190:193], v[110:113]
	v_mfma_f32_16x16x32_bf16 v[106:109], v[158:161], v[190:193], v[106:109]
	v_mfma_f32_16x16x32_bf16 v[94:97], v[150:153], v[218:221], v[94:97]
	v_mfma_f32_16x16x32_bf16 v[90:93], v[158:161], v[218:221], v[90:93]
	v_mfma_f32_16x16x32_bf16 v[78:81], v[150:153], v[226:229], v[78:81]
	v_mfma_f32_16x16x32_bf16 v[74:77], v[158:161], v[226:229], v[74:77]
	v_mfma_f32_16x16x32_bf16 v[118:121], v[162:165], v[178:181], v[118:121]
	v_mfma_f32_16x16x32_bf16 v[114:117], v[170:173], v[178:181], v[114:117]
	v_mfma_f32_16x16x32_bf16 v[102:105], v[162:165], v[186:189], v[102:105]
	v_mfma_f32_16x16x32_bf16 v[98:101], v[170:173], v[186:189], v[98:101]
	v_mfma_f32_16x16x32_bf16 v[86:89], v[162:165], v[214:217], v[86:89]
	v_mfma_f32_16x16x32_bf16 v[82:85], v[170:173], v[214:217], v[82:85]
	v_mfma_f32_16x16x32_bf16 v[70:73], v[162:165], v[222:225], v[70:73]
	v_mfma_f32_16x16x32_bf16 v[66:69], v[170:173], v[222:225], v[66:69]
	v_mfma_f32_16x16x32_bf16 v[118:121], v[166:169], v[182:185], v[118:121]
	v_mfma_f32_16x16x32_bf16 v[114:117], v[174:177], v[182:185], v[114:117]
	v_mfma_f32_16x16x32_bf16 v[102:105], v[166:169], v[190:193], v[102:105]
	v_mfma_f32_16x16x32_bf16 v[98:101], v[174:177], v[190:193], v[98:101]
	v_mfma_f32_16x16x32_bf16 v[86:89], v[166:169], v[218:221], v[86:89]
	v_mfma_f32_16x16x32_bf16 v[82:85], v[174:177], v[218:221], v[82:85]
	v_mfma_f32_16x16x32_bf16 v[70:73], v[166:169], v[226:229], v[70:73]
	v_mfma_f32_16x16x32_bf16 v[66:69], v[174:177], v[226:229], v[66:69]
	s_setprio 0
	s_barrier
	s_add_i32 s22, s22, s12
	v_lshl_add_u64 v[144:145], s[6:7], 0, v[64:65]
	s_mov_b32 m0, s22
	ds_read_b128 v[178:181], v149 offset:16384
	ds_read_b128 v[182:185], v149 offset:17408
	ds_read_b128 v[186:189], v149 offset:18432
	ds_read_b128 v[190:193], v149 offset:19456
	ds_read_b128 v[214:217], v149 offset:20480
	ds_read_b128 v[218:221], v149 offset:21504
	ds_read_b128 v[222:225], v149 offset:22528
	ds_read_b128 v[226:229], v149 offset:23552
	global_load_lds_dwordx4 v[144:145], off
	s_add_i32 m0, s22, 0x2000
	s_add_u32 s22, s6, 0x100000
	v_lshl_add_u64 v[230:231], s[6:7], 0, v[134:135]
	s_addc_u32 s23, s7, 0
	s_add_i32 s24, s24, s12
	global_load_lds_dwordx4 v[230:231], off
	v_lshl_add_u64 v[232:233], s[22:23], 0, v[64:65]
	s_mov_b32 m0, s24
	v_lshl_add_u64 v[234:235], s[10:11], 0, v[132:133]
	global_load_lds_dwordx4 v[232:233], off
	v_lshl_add_u64 v[232:233], s[22:23], 0, v[134:135]
	s_add_i32 m0, s24, 0x2000
	s_nop 0
	global_load_lds_dwordx4 v[232:233], off
	v_lshl_add_u64 v[232:233], s[10:11], 0, v[130:131]
	s_mov_b32 m0, s13
	s_nop 0
	global_load_lds_dwordx4 v[232:233], off
	s_mov_b32 m0, s14
	s_nop 0
	global_load_lds_dwordx4 v[234:235], off
	s_waitcnt vmcnt(8) lgkmcnt(0)
	s_barrier
; #define PG8_STAGE(bufoff, gbase, voff) do { _Pragma("unroll") for (int _i = 0; _i < 2; ++_i) \
;         __builtin_amdgcn_global_load_lds((const unsigned*)((const char*)(gbase) + (voff)[_i]), (LAS unsigned*)(lds + (bufoff) + ldsw + _i * 8192), 16, 0, 0); } while (0)
; #define PG8_LDA(dst, b, h) do { _Pragma("unroll") for (int m = 0; m < 4; ++m) _Pragma("unroll") for (int k = 0; k < 2; ++k) dst[m][k] = *(const LAS bf16x8*)(lds + PG8_SA(b, h) + aoff + m * 2048 + k * 1024); } while (0)
; #define PG8_LDB(dst, b, h) do { _Pragma("unroll") for (int n = 0; n < 2; ++n) _Pragma("unroll") for (int k = 0; k < 2; ++k) dst[n][k] = *(const LAS bf16x8*)(lds + PG8_SB(b, h) + boff + n * 2048 + k * 1024); } while (0)
; #define PG8_MMA(ai, bj, At, Bt) do { __builtin_amdgcn_s_setprio(1); _Pragma("unroll") for (int m = 0; m < 4; ++m) _Pragma("unroll") for (int n = 0; n < 2; ++n) _Pragma("unroll") for (int k = 0; k < 2; ++k) \
;         acc[ai][bj][m][n] = __builtin_amdgcn_mfma_f32_16x16x32_bf16(Bt[n][k], At[m][k], acc[ai][bj][m][n], 0, 0, 0); __builtin_amdgcn_s_setprio(0); } while (0)
; #define PG8_WAIT_V(n) asm volatile("s_waitcnt vmcnt(" #n ")" ::: "memory")
; #define PG8_WAIT_L(n) asm volatile("s_waitcnt lgkmcnt(" #n ")" ::: "memory")
; #define PG8_BAR __builtin_amdgcn_s_barrier()
; #define PG8_SCHED __builtin_amdgcn_sched_barrier(0)
; template <class Epi, bool SP2, class Sched>
; __device__ __forceinline__ void gemm_phase(LAS unsigned char* lds, const Gemm g, const Sched& S, const Epi& E) {
;     ...
;             PG8_WAIT_V(8); PG8_WAIT_L(0); PG8_BAR; PG8_MMA(1, 0, At, B0); PG8_MMA(1, 1, At, B1); PG8_BAR; PG8_SCHED;
;             PG8_LDB(B0, 1, 0); PG8_LDB(B1, 1, 1); PG8_SCHED; PG8_LDA(At, 1, 0); PG8_STAGE(PG8_SA(0, 1), a2 + hstep, voffA);
;             PG8_WAIT_V(8); PG8_WAIT_L(0); PG8_BAR; PG8_MMA(0, 0, At, B0); PG8_MMA(0, 1, At, B1); PG8_BAR; PG8_SCHED;
	s_setprio 1
	v_mfma_f32_16x16x32_bf16 v[60:63], v[140:143], v[178:181], v[60:63]
	v_mfma_f32_16x16x32_bf16 v[56:59], v[154:157], v[178:181], v[56:59]
	v_mfma_f32_16x16x32_bf16 v[44:47], v[140:143], v[186:189], v[44:47]
	v_mfma_f32_16x16x32_bf16 v[40:43], v[154:157], v[186:189], v[40:43]
	v_mfma_f32_16x16x32_bf16 v[28:31], v[140:143], v[214:217], v[28:31]
	v_mfma_f32_16x16x32_bf16 v[24:27], v[154:157], v[214:217], v[24:27]
	v_mfma_f32_16x16x32_bf16 v[12:15], v[140:143], v[222:225], v[12:15]
	v_mfma_f32_16x16x32_bf16 v[8:11], v[154:157], v[222:225], v[8:11]
	v_mfma_f32_16x16x32_bf16 v[60:63], v[150:153], v[182:185], v[60:63]
	v_mfma_f32_16x16x32_bf16 v[56:59], v[158:161], v[182:185], v[56:59]
	v_mfma_f32_16x16x32_bf16 v[44:47], v[150:153], v[190:193], v[44:47]
	v_mfma_f32_16x16x32_bf16 v[40:43], v[158:161], v[190:193], v[40:43]
	v_mfma_f32_16x16x32_bf16 v[28:31], v[150:153], v[218:221], v[28:31]
	v_mfma_f32_16x16x32_bf16 v[24:27], v[158:161], v[218:221], v[24:27]
	v_mfma_f32_16x16x32_bf16 v[12:15], v[150:153], v[226:229], v[12:15]
	v_mfma_f32_16x16x32_bf16 v[8:11], v[158:161], v[226:229], v[8:11]
	v_mfma_f32_16x16x32_bf16 v[52:55], v[162:165], v[178:181], v[52:55]
	v_mfma_f32_16x16x32_bf16 v[48:51], v[170:173], v[178:181], v[48:51]
	v_mfma_f32_16x16x32_bf16 v[36:39], v[162:165], v[186:189], v[36:39]
	v_mfma_f32_16x16x32_bf16 v[32:35], v[170:173], v[186:189], v[32:35]
	v_mfma_f32_16x16x32_bf16 v[20:23], v[162:165], v[214:217], v[20:23]
	v_mfma_f32_16x16x32_bf16 v[16:19], v[170:173], v[214:217], v[16:19]
	v_mfma_f32_16x16x32_bf16 v[4:7], v[162:165], v[222:225], v[4:7]
	v_mfma_f32_16x16x32_bf16 v[0:3], v[170:173], v[222:225], v[0:3]
	v_mfma_f32_16x16x32_bf16 v[52:55], v[166:169], v[182:185], v[52:55]
	v_mfma_f32_16x16x32_bf16 v[48:51], v[174:177], v[182:185], v[48:51]
	v_mfma_f32_16x16x32_bf16 v[36:39], v[166:169], v[190:193], v[36:39]
	v_mfma_f32_16x16x32_bf16 v[32:35], v[174:177], v[190:193], v[32:35]
	v_mfma_f32_16x16x32_bf16 v[20:23], v[166:169], v[218:221], v[20:23]
	v_mfma_f32_16x16x32_bf16 v[16:19], v[174:177], v[218:221], v[16:19]
	v_mfma_f32_16x16x32_bf16 v[4:7], v[166:169], v[226:229], v[4:7]
	v_mfma_f32_16x16x32_bf16 v[0:3], v[174:177], v[226:229], v[0:3]
	s_setprio 0
	s_barrier
	s_add_i32 s22, 0, 0x18000
	s_add_i32 s23, 0, 0x1c000
	v_add_u32_e32 v158, s22, v147
	v_add_u32_e32 v174, s23, v147
	ds_read_b128 v[140:143], v158
	ds_read_b128 v[150:153], v158 offset:1024
	ds_read_b128 v[154:157], v158 offset:2048
	ds_read_b128 v[158:161], v158 offset:3072
	ds_read_b128 v[162:165], v174
	ds_read_b128 v[166:169], v174 offset:1024
	ds_read_b128 v[170:173], v174 offset:2048
	ds_read_b128 v[174:177], v174 offset:3072
	s_add_u32 s10, s10, 0x100000
	s_addc_u32 s11, s11, 0
	s_mov_b32 m0, s15
	v_lshl_add_u64 v[236:237], s[10:11], 0, v[130:131]
	ds_read_b128 v[178:181], v149 offset:32768
	ds_read_b128 v[182:185], v149 offset:33792
	ds_read_b128 v[186:189], v149 offset:34816
	ds_read_b128 v[190:193], v149 offset:35840
	ds_read_b128 v[214:217], v149 offset:36864
	ds_read_b128 v[218:221], v149 offset:37888
	ds_read_b128 v[222:225], v149 offset:38912
	ds_read_b128 v[226:229], v149 offset:39936
	global_load_lds_dwordx4 v[236:237], off
	v_lshl_add_u64 v[236:237], s[10:11], 0, v[132:133]
	s_mov_b32 m0, s17
	s_nop 0
	global_load_lds_dwordx4 v[236:237], off
	s_waitcnt vmcnt(8) lgkmcnt(0)
	s_barrier
	s_setprio 1
	v_mfma_f32_16x16x32_bf16 v[126:129], v[140:143], v[178:181], v[126:129]
	v_mfma_f32_16x16x32_bf16 v[122:125], v[154:157], v[178:181], v[122:125]
	v_mfma_f32_16x16x32_bf16 v[110:113], v[140:143], v[186:189], v[110:113]
	v_mfma_f32_16x16x32_bf16 v[106:109], v[154:157], v[186:189], v[106:109]
	v_mfma_f32_16x16x32_bf16 v[94:97], v[140:143], v[214:217], v[94:97]
	v_mfma_f32_16x16x32_bf16 v[90:93], v[154:157], v[214:217], v[90:93]
	v_mfma_f32_16x16x32_bf16 v[78:81], v[140:143], v[222:225], v[78:81]
	v_mfma_f32_16x16x32_bf16 v[74:77], v[154:157], v[222:225], v[74:77]
	v_mfma_f32_16x16x32_bf16 v[126:129], v[150:153], v[182:185], v[126:129]
	v_mfma_f32_16x16x32_bf16 v[122:125], v[158:161], v[182:185], v[122:125]
	v_mfma_f32_16x16x32_bf16 v[110:113], v[150:153], v[190:193], v[110:113]
	v_mfma_f32_16x16x32_bf16 v[106:109], v[158:161], v[190:193], v[106:109]
	v_mfma_f32_16x16x32_bf16 v[94:97], v[150:153], v[218:221], v[94:97]
	v_mfma_f32_16x16x32_bf16 v[90:93], v[158:161], v[218:221], v[90:93]
	v_mfma_f32_16x16x32_bf16 v[78:81], v[150:153], v[226:229], v[78:81]
	v_mfma_f32_16x16x32_bf16 v[74:77], v[158:161], v[226:229], v[74:77]
	v_mfma_f32_16x16x32_bf16 v[118:121], v[162:165], v[178:181], v[118:121]
	v_mfma_f32_16x16x32_bf16 v[114:117], v[170:173], v[178:181], v[114:117]
	v_mfma_f32_16x16x32_bf16 v[102:105], v[162:165], v[186:189], v[102:105]
	v_mfma_f32_16x16x32_bf16 v[98:101], v[170:173], v[186:189], v[98:101]
	v_mfma_f32_16x16x32_bf16 v[86:89], v[162:165], v[214:217], v[86:89]
	v_mfma_f32_16x16x32_bf16 v[82:85], v[170:173], v[214:217], v[82:85]
	v_mfma_f32_16x16x32_bf16 v[70:73], v[162:165], v[222:225], v[70:73]
	v_mfma_f32_16x16x32_bf16 v[66:69], v[170:173], v[222:225], v[66:69]
	v_mfma_f32_16x16x32_bf16 v[118:121], v[166:169], v[182:185], v[118:121]
	v_mfma_f32_16x16x32_bf16 v[114:117], v[174:177], v[182:185], v[114:117]
	v_mfma_f32_16x16x32_bf16 v[102:105], v[166:169], v[190:193], v[102:105]
	v_mfma_f32_16x16x32_bf16 v[98:101], v[174:177], v[190:193], v[98:101]
	v_mfma_f32_16x16x32_bf16 v[86:89], v[166:169], v[218:221], v[86:89]
	v_mfma_f32_16x16x32_bf16 v[82:85], v[174:177], v[218:221], v[82:85]
	v_mfma_f32_16x16x32_bf16 v[70:73], v[166:169], v[226:229], v[70:73]
	v_mfma_f32_16x16x32_bf16 v[66:69], v[174:177], v[226:229], v[66:69]
	s_setprio 0
	s_barrier
; #define PG8_STAGE(bufoff, gbase, voff) do { _Pragma("unroll") for (int _i = 0; _i < 2; ++_i) \
;         __builtin_amdgcn_global_load_lds((const unsigned*)((const char*)(gbase) + (voff)[_i]), (LAS unsigned*)(lds + (bufoff) + ldsw + _i * 8192), 16, 0, 0); } while (0)
; #define PG8_LDA(dst, b, h) do { _Pragma("unroll") for (int m = 0; m < 4; ++m) _Pragma("unroll") for (int k = 0; k < 2; ++k) dst[m][k] = *(const LAS bf16x8*)(lds + PG8_SA(b, h) + aoff + m * 2048 + k * 1024); } while (0)
; #define PG8_MMA(ai, bj, At, Bt) do { __builtin_amdgcn_s_setprio(1); _Pragma("unroll") for (int m = 0; m < 4; ++m) _Pragma("unroll") for (int n = 0; n < 2; ++n) _Pragma("unroll") for (int k = 0; k < 2; ++k) \
;         acc[ai][bj][m][n] = __builtin_amdgcn_mfma_f32_16x16x32_bf16(Bt[n][k], At[m][k], acc[ai][bj][m][n], 0, 0, 0); __builtin_amdgcn_s_setprio(0); } while (0)
; #define PG8_WAIT_V(n) asm volatile("s_waitcnt vmcnt(" #n ")" ::: "memory")
; #define PG8_WAIT_L(n) asm volatile("s_waitcnt lgkmcnt(" #n ")" ::: "memory")
; #define PG8_BAR __builtin_amdgcn_s_barrier()
; #define PG8_SCHED __builtin_amdgcn_sched_barrier(0)
; template <class Epi, bool SP2, class Sched>
; __device__ __forceinline__ void gemm_phase(LAS unsigned char* lds, const Gemm g, const Sched& S, const Epi& E) {
;     ...
;             PG8_LDA(At, 1, 1); PG8_STAGE(PG8_SB(1, 0), b3, voffB); PG8_STAGE(PG8_SB(1, 1), b3 + hstepB, voffB); PG8_STAGE(PG8_SA(1, 0), a3, voffA);
;             PG8_WAIT_V(8); PG8_WAIT_L(0); PG8_BAR; PG8_MMA(1, 0, At, B0); PG8_MMA(1, 1, At, B1); PG8_BAR; PG8_SCHED;
;     ...
;         if (wr == 0) PG8_BAR;
	s_add_i32 s10, s22, s12
	v_lshl_add_u64 v[144:145], v[144:145], 0, s[66:67]
	s_mov_b32 m0, s10
	ds_read_b128 v[178:181], v149 offset:49152
	ds_read_b128 v[182:185], v149 offset:50176
	ds_read_b128 v[186:189], v149 offset:51200
	ds_read_b128 v[190:193], v149 offset:52224
	ds_read_b128 v[214:217], v149 offset:53248
	ds_read_b128 v[218:221], v149 offset:54272
	ds_read_b128 v[222:225], v149 offset:55296
	ds_read_b128 v[226:229], v149 offset:56320
	global_load_lds_dwordx4 v[144:145], off
	s_add_i32 m0, s10, 0x2000
	s_add_u32 s6, s6, 0x100080
	v_lshl_add_u64 v[144:145], v[230:231], 0, s[66:67]
	s_addc_u32 s7, s7, 0
	s_add_i32 s10, s23, s12
	global_load_lds_dwordx4 v[144:145], off
	v_lshl_add_u64 v[144:145], s[6:7], 0, v[64:65]
	s_mov_b32 m0, s10
	s_nop 0
	global_load_lds_dwordx4 v[144:145], off
	v_lshl_add_u64 v[144:145], s[6:7], 0, v[134:135]
	s_add_i32 m0, s10, 0x2000
	s_nop 0
	global_load_lds_dwordx4 v[144:145], off
	v_lshl_add_u64 v[144:145], v[232:233], 0, s[66:67]
	s_mov_b32 m0, s18
	s_nop 0
	global_load_lds_dwordx4 v[144:145], off
	v_lshl_add_u64 v[144:145], v[234:235], 0, s[66:67]
	s_mov_b32 m0, s19
	s_nop 0
	global_load_lds_dwordx4 v[144:145], off
	s_waitcnt vmcnt(8) lgkmcnt(0)
	s_barrier
	s_setprio 1
	v_mfma_f32_16x16x32_bf16 v[60:63], v[140:143], v[178:181], v[60:63]
	v_mfma_f32_16x16x32_bf16 v[56:59], v[154:157], v[178:181], v[56:59]
	v_mfma_f32_16x16x32_bf16 v[44:47], v[140:143], v[186:189], v[44:47]
	v_mfma_f32_16x16x32_bf16 v[40:43], v[154:157], v[186:189], v[40:43]
	v_mfma_f32_16x16x32_bf16 v[28:31], v[140:143], v[214:217], v[28:31]
	v_mfma_f32_16x16x32_bf16 v[24:27], v[154:157], v[214:217], v[24:27]
	v_mfma_f32_16x16x32_bf16 v[12:15], v[140:143], v[222:225], v[12:15]
	v_mfma_f32_16x16x32_bf16 v[8:11], v[154:157], v[222:225], v[8:11]
	v_mfma_f32_16x16x32_bf16 v[60:63], v[150:153], v[182:185], v[60:63]
	v_mfma_f32_16x16x32_bf16 v[56:59], v[158:161], v[182:185], v[56:59]
	v_mfma_f32_16x16x32_bf16 v[44:47], v[150:153], v[190:193], v[44:47]
	v_mfma_f32_16x16x32_bf16 v[40:43], v[158:161], v[190:193], v[40:43]
	v_mfma_f32_16x16x32_bf16 v[28:31], v[150:153], v[218:221], v[28:31]
	v_mfma_f32_16x16x32_bf16 v[24:27], v[158:161], v[218:221], v[24:27]
	v_mfma_f32_16x16x32_bf16 v[12:15], v[150:153], v[226:229], v[12:15]
	v_mfma_f32_16x16x32_bf16 v[8:11], v[158:161], v[226:229], v[8:11]
	v_mfma_f32_16x16x32_bf16 v[52:55], v[162:165], v[178:181], v[52:55]
	v_mfma_f32_16x16x32_bf16 v[48:51], v[170:173], v[178:181], v[48:51]
	v_mfma_f32_16x16x32_bf16 v[36:39], v[162:165], v[186:189], v[36:39]
	v_mfma_f32_16x16x32_bf16 v[32:35], v[170:173], v[186:189], v[32:35]
	v_mfma_f32_16x16x32_bf16 v[20:23], v[162:165], v[214:217], v[20:23]
	v_mfma_f32_16x16x32_bf16 v[16:19], v[170:173], v[214:217], v[16:19]
	v_mfma_f32_16x16x32_bf16 v[4:7], v[162:165], v[222:225], v[4:7]
	v_mfma_f32_16x16x32_bf16 v[0:3], v[170:173], v[222:225], v[0:3]
	v_mfma_f32_16x16x32_bf16 v[52:55], v[166:169], v[182:185], v[52:55]
	v_mfma_f32_16x16x32_bf16 v[48:51], v[174:177], v[182:185], v[48:51]
	v_mfma_f32_16x16x32_bf16 v[36:39], v[166:169], v[190:193], v[36:39]
	v_mfma_f32_16x16x32_bf16 v[32:35], v[174:177], v[190:193], v[32:35]
	v_mfma_f32_16x16x32_bf16 v[20:23], v[166:169], v[218:221], v[20:23]
	v_mfma_f32_16x16x32_bf16 v[16:19], v[174:177], v[218:221], v[16:19]
	v_mfma_f32_16x16x32_bf16 v[4:7], v[166:169], v[226:229], v[4:7]
	v_mfma_f32_16x16x32_bf16 v[0:3], v[174:177], v[226:229], v[0:3]
	s_setprio 0
	s_barrier
	s_add_i32 s21, s21, 2
	s_add_u32 s76, s76, 0x100
	s_addc_u32 s20, s20, 0
	s_add_u32 s92, s92, 0x100
	s_addc_u32 s93, s93, 0
	s_cmp_gt_u32 s21, 61
	s_cbranch_scc0 .LBB0_1118
	s_and_b64 vcc, exec, s[60:61]
	s_cbranch_vccz .LBB0_1121
	s_barrier

; #define PG8_STAGE(bufoff, gbase, voff) do { _Pragma("unroll") for (int _i = 0; _i < 2; ++_i) \
;         __builtin_amdgcn_global_load_lds((const unsigned*)((const char*)(gbase) + (voff)[_i]), (LAS unsigned*)(lds + (bufoff) + ldsw + _i * 8192), 16, 0, 0); } while (0)
; #define PG8_LDA(dst, b, h) do { _Pragma("unroll") for (int m = 0; m < 4; ++m) _Pragma("unroll") for (int k = 0; k < 2; ++k) dst[m][k] = *(const LAS bf16x8*)(lds + PG8_SA(b, h) + aoff + m * 2048 + k * 1024); } while (0)
; #define PG8_LDB(dst, b, h) do { _Pragma("unroll") for (int n = 0; n < 2; ++n) _Pragma("unroll") for (int k = 0; k < 2; ++k) dst[n][k] = *(const LAS bf16x8*)(lds + PG8_SB(b, h) + boff + n * 2048 + k * 1024); } while (0)
; #define PG8_MMA(ai, bj, At, Bt) do { __builtin_amdgcn_s_setprio(1); _Pragma("unroll") for (int m = 0; m < 4; ++m) _Pragma("unroll") for (int n = 0; n < 2; ++n) _Pragma("unroll") for (int k = 0; k < 2; ++k) \
;         acc[ai][bj][m][n] = __builtin_amdgcn_mfma_f32_16x16x32_bf16(Bt[n][k], At[m][k], acc[ai][bj][m][n], 0, 0, 0); __builtin_amdgcn_s_setprio(0); } while (0)
; #define PG8_WAIT_V(n) asm volatile("s_waitcnt vmcnt(" #n ")" ::: "memory")
; #define PG8_WAIT_L(n) asm volatile("s_waitcnt lgkmcnt(" #n ")" ::: "memory")
; #define PG8_BAR __builtin_amdgcn_s_barrier()
; template <class Epi, bool SP2, class Sched>
; __device__ __forceinline__ void gemm_phase(LAS unsigned char* lds, const Gemm g, const Sched& S, const Epi& E) {
;     ...
;             const bool last = (t == nt - 2);
;             const char* a1 = cA + (size_t)(t + 1) * kstep;
;             const char* a2 = last ? nA : cA + (size_t)(t + 2) * kstep; const char* b2 = last ? nB : cB + (size_t)(t + 2) * kstep;
;             const char* a3 = a2 + kstep; const char* b3 = b2 + kstep;
;             if constexpr (Epi::MID) { if (t == (nt >> 1)) E.mid(acc, cur, wr, fr); }
;             if constexpr (SP2) {
;             PG8_LDB(B0, 0, 0); PG8_LDB(B1, 0, 1); PG8_SCHED; PG8_LDA(At, 0, 0); PG8_STAGE(PG8_SA(1, 1), a1 + hstep, voffA);
;             PG8_WAIT_V(8); PG8_WAIT_L(0); PG8_BAR; PG8_MMA(0, 0, At, B0); PG8_MMA(0, 1, At, B1); PG8_BAR; PG8_SCHED;
;             PG8_LDA(At, 0, 1); PG8_STAGE(PG8_SB(0, 0), b2, voffB); PG8_STAGE(PG8_SB(0, 1), b2 + hstepB, voffB); PG8_STAGE(PG8_SA(0, 0), a2, voffA);
;             PG8_WAIT_V(8); PG8_WAIT_L(0); PG8_BAR; PG8_MMA(1, 0, At, B0); PG8_MMA(1, 1, At, B1); PG8_BAR; PG8_SCHED;
.LBB0_1150:
	s_add_u32 s6, s86, 0xfff00080
	s_addc_u32 s7, s87, -1
	s_add_i32 s22, 0, 0x10000
	s_cmp_eq_u32 s21, 12
	s_cselect_b32 s11, s3, s7
	s_cselect_b32 s10, s57, s6
	s_cselect_b32 s7, s53, s20
	s_cselect_b32 s6, s77, s79
	s_add_i32 s24, 0, 0x14000
	v_add_u32_e32 v152, s22, v137
	v_add_u32_e32 v168, s24, v137
	ds_read_b128 v[140:143], v152
	ds_read_b128 v[144:147], v152 offset:1024
	ds_read_b128 v[148:151], v152 offset:2048
	ds_read_b128 v[152:155], v152 offset:3072
	ds_read_b128 v[156:159], v168
	ds_read_b128 v[160:163], v168 offset:1024
	ds_read_b128 v[164:167], v168 offset:2048
	ds_read_b128 v[168:171], v168 offset:3072
	v_lshl_add_u64 v[192:193], s[86:87], 0, v[134:135]
	s_add_i32 m0, s5, 0xc000
	ds_read_b128 v[172:175], v139
	ds_read_b128 v[176:179], v139 offset:1024
	ds_read_b128 v[180:183], v139 offset:2048
	ds_read_b128 v[184:187], v139 offset:3072
	ds_read_b128 v[188:191], v139 offset:4096
	ds_read_b128 v[214:217], v139 offset:5120
	ds_read_b128 v[218:221], v139 offset:6144
	ds_read_b128 v[222:225], v139 offset:7168
	global_load_lds_dwordx4 v[192:193], off
	v_lshl_add_u64 v[192:193], s[86:87], 0, v[132:133]
	s_add_i32 m0, s5, 0xe000
	s_nop 0
	global_load_lds_dwordx4 v[192:193], off
	s_waitcnt vmcnt(8) lgkmcnt(0)
	s_barrier
	s_setprio 1
	v_mfma_f32_16x16x32_bf16 v[126:129], v[140:143], v[172:175], v[126:129]
	v_mfma_f32_16x16x32_bf16 v[122:125], v[148:151], v[172:175], v[122:125]
	v_mfma_f32_16x16x32_bf16 v[118:121], v[140:143], v[180:183], v[118:121]
	v_mfma_f32_16x16x32_bf16 v[114:117], v[148:151], v[180:183], v[114:117]
	v_mfma_f32_16x16x32_bf16 v[106:109], v[140:143], v[188:191], v[106:109]
	v_mfma_f32_16x16x32_bf16 v[98:101], v[148:151], v[188:191], v[98:101]
	v_mfma_f32_16x16x32_bf16 v[90:93], v[140:143], v[218:221], v[90:93]
	v_mfma_f32_16x16x32_bf16 v[82:85], v[148:151], v[218:221], v[82:85]
	v_mfma_f32_16x16x32_bf16 v[126:129], v[144:147], v[176:179], v[126:129]
	v_mfma_f32_16x16x32_bf16 v[122:125], v[152:155], v[176:179], v[122:125]
	v_mfma_f32_16x16x32_bf16 v[118:121], v[144:147], v[184:187], v[118:121]
	v_mfma_f32_16x16x32_bf16 v[114:117], v[152:155], v[184:187], v[114:117]
	v_mfma_f32_16x16x32_bf16 v[106:109], v[144:147], v[214:217], v[106:109]
	v_mfma_f32_16x16x32_bf16 v[98:101], v[152:155], v[214:217], v[98:101]
	v_mfma_f32_16x16x32_bf16 v[90:93], v[144:147], v[222:225], v[90:93]
	v_mfma_f32_16x16x32_bf16 v[82:85], v[152:155], v[222:225], v[82:85]
	v_mfma_f32_16x16x32_bf16 v[110:113], v[156:159], v[172:175], v[110:113]
	v_mfma_f32_16x16x32_bf16 v[102:105], v[164:167], v[172:175], v[102:105]
	v_mfma_f32_16x16x32_bf16 v[94:97], v[156:159], v[180:183], v[94:97]
	v_mfma_f32_16x16x32_bf16 v[86:89], v[164:167], v[180:183], v[86:89]
	v_mfma_f32_16x16x32_bf16 v[78:81], v[156:159], v[188:191], v[78:81]
	v_mfma_f32_16x16x32_bf16 v[74:77], v[164:167], v[188:191], v[74:77]
	v_mfma_f32_16x16x32_bf16 v[70:73], v[156:159], v[218:221], v[70:73]
	v_mfma_f32_16x16x32_bf16 v[66:69], v[164:167], v[218:221], v[66:69]
	v_mfma_f32_16x16x32_bf16 v[110:113], v[160:163], v[176:179], v[110:113]
	v_mfma_f32_16x16x32_bf16 v[102:105], v[168:171], v[176:179], v[102:105]
	v_mfma_f32_16x16x32_bf16 v[94:97], v[160:163], v[184:187], v[94:97]
	v_mfma_f32_16x16x32_bf16 v[86:89], v[168:171], v[184:187], v[86:89]
	v_mfma_f32_16x16x32_bf16 v[78:81], v[160:163], v[214:217], v[78:81]
	v_mfma_f32_16x16x32_bf16 v[74:77], v[168:171], v[214:217], v[74:77]
	v_mfma_f32_16x16x32_bf16 v[70:73], v[160:163], v[222:225], v[70:73]
	v_mfma_f32_16x16x32_bf16 v[66:69], v[168:171], v[222:225], v[66:69]
	s_setprio 0
	s_barrier
	s_add_i32 s22, s22, s18
	v_lshl_add_u64 v[192:193], s[6:7], 0, v[64:65]
	s_mov_b32 m0, s22
	ds_read_b128 v[172:175], v139 offset:16384
	ds_read_b128 v[176:179], v139 offset:17408
	ds_read_b128 v[180:183], v139 offset:18432
	ds_read_b128 v[184:187], v139 offset:19456
	ds_read_b128 v[188:191], v139 offset:20480
	ds_read_b128 v[214:217], v139 offset:21504
	ds_read_b128 v[218:221], v139 offset:22528
	ds_read_b128 v[222:225], v139 offset:23552
	global_load_lds_dwordx4 v[192:193], off
	s_add_i32 m0, s22, 0x2000
	s_add_u32 s22, s6, 0x100000
	v_lshl_add_u64 v[226:227], s[6:7], 0, v[130:131]
	s_addc_u32 s23, s7, 0
	s_add_i32 s24, s24, s18
	global_load_lds_dwordx4 v[226:227], off
	v_lshl_add_u64 v[228:229], s[22:23], 0, v[64:65]
	s_mov_b32 m0, s24
	v_lshl_add_u64 v[230:231], s[10:11], 0, v[130:131]
	global_load_lds_dwordx4 v[228:229], off
	v_lshl_add_u64 v[228:229], s[22:23], 0, v[130:131]
	s_add_i32 m0, s24, 0x2000
	s_nop 0
	global_load_lds_dwordx4 v[228:229], off
	v_lshl_add_u64 v[228:229], s[10:11], 0, v[64:65]
	s_mov_b32 m0, s5
	s_nop 0
	global_load_lds_dwordx4 v[228:229], off
	s_mov_b32 m0, s33
	s_nop 0
	global_load_lds_dwordx4 v[230:231], off
	s_waitcnt vmcnt(8) lgkmcnt(0)
	s_barrier
; #define PG8_STAGE(bufoff, gbase, voff) do { _Pragma("unroll") for (int _i = 0; _i < 2; ++_i) \
;         __builtin_amdgcn_global_load_lds((const unsigned*)((const char*)(gbase) + (voff)[_i]), (LAS unsigned*)(lds + (bufoff) + ldsw + _i * 8192), 16, 0, 0); } while (0)
; #define PG8_LDA(dst, b, h) do { _Pragma("unroll") for (int m = 0; m < 4; ++m) _Pragma("unroll") for (int k = 0; k < 2; ++k) dst[m][k] = *(const LAS bf16x8*)(lds + PG8_SA(b, h) + aoff + m * 2048 + k * 1024); } while (0)
; #define PG8_LDB(dst, b, h) do { _Pragma("unroll") for (int n = 0; n < 2; ++n) _Pragma("unroll") for (int k = 0; k < 2; ++k) dst[n][k] = *(const LAS bf16x8*)(lds + PG8_SB(b, h) + boff + n * 2048 + k * 1024); } while (0)
; #define PG8_MMA(ai, bj, At, Bt) do { __builtin_amdgcn_s_setprio(1); _Pragma("unroll") for (int m = 0; m < 4; ++m) _Pragma("unroll") for (int n = 0; n < 2; ++n) _Pragma("unroll") for (int k = 0; k < 2; ++k) \
;         acc[ai][bj][m][n] = __builtin_amdgcn_mfma_f32_16x16x32_bf16(Bt[n][k], At[m][k], acc[ai][bj][m][n], 0, 0, 0); __builtin_amdgcn_s_setprio(0); } while (0)
; #define PG8_WAIT_V(n) asm volatile("s_waitcnt vmcnt(" #n ")" ::: "memory")
; #define PG8_WAIT_L(n) asm volatile("s_waitcnt lgkmcnt(" #n ")" ::: "memory")
; #define PG8_BAR __builtin_amdgcn_s_barrier()
; #define PG8_SCHED __builtin_amdgcn_sched_barrier(0)
; template <class Epi, bool SP2, class Sched>
; __device__ __forceinline__ void gemm_phase(LAS unsigned char* lds, const Gemm g, const Sched& S, const Epi& E) {
;     ...
;             PG8_WAIT_V(8); PG8_WAIT_L(0); PG8_BAR; PG8_MMA(1, 0, At, B0); PG8_MMA(1, 1, At, B1); PG8_BAR; PG8_SCHED;
;             PG8_LDB(B0, 1, 0); PG8_LDB(B1, 1, 1); PG8_SCHED; PG8_LDA(At, 1, 0); PG8_STAGE(PG8_SA(0, 1), a2 + hstep, voffA);
;             PG8_WAIT_V(8); PG8_WAIT_L(0); PG8_BAR; PG8_MMA(0, 0, At, B0); PG8_MMA(0, 1, At, B1); PG8_BAR; PG8_SCHED;
	s_setprio 1
	v_mfma_f32_16x16x32_bf16 v[60:63], v[140:143], v[172:175], v[60:63]
	v_mfma_f32_16x16x32_bf16 v[56:59], v[148:151], v[172:175], v[56:59]
	v_mfma_f32_16x16x32_bf16 v[52:55], v[140:143], v[180:183], v[52:55]
	v_mfma_f32_16x16x32_bf16 v[48:51], v[148:151], v[180:183], v[48:51]
	v_mfma_f32_16x16x32_bf16 v[36:39], v[140:143], v[188:191], v[36:39]
	v_mfma_f32_16x16x32_bf16 v[32:35], v[148:151], v[188:191], v[32:35]
	v_mfma_f32_16x16x32_bf16 v[20:23], v[140:143], v[218:221], v[20:23]
	v_mfma_f32_16x16x32_bf16 v[16:19], v[148:151], v[218:221], v[16:19]
	v_mfma_f32_16x16x32_bf16 v[60:63], v[144:147], v[176:179], v[60:63]
	v_mfma_f32_16x16x32_bf16 v[56:59], v[152:155], v[176:179], v[56:59]
	v_mfma_f32_16x16x32_bf16 v[52:55], v[144:147], v[184:187], v[52:55]
	v_mfma_f32_16x16x32_bf16 v[48:51], v[152:155], v[184:187], v[48:51]
	v_mfma_f32_16x16x32_bf16 v[36:39], v[144:147], v[214:217], v[36:39]
	v_mfma_f32_16x16x32_bf16 v[32:35], v[152:155], v[214:217], v[32:35]
	v_mfma_f32_16x16x32_bf16 v[20:23], v[144:147], v[222:225], v[20:23]
	v_mfma_f32_16x16x32_bf16 v[16:19], v[152:155], v[222:225], v[16:19]
	v_mfma_f32_16x16x32_bf16 v[44:47], v[156:159], v[172:175], v[44:47]
	v_mfma_f32_16x16x32_bf16 v[40:43], v[164:167], v[172:175], v[40:43]
	v_mfma_f32_16x16x32_bf16 v[28:31], v[156:159], v[180:183], v[28:31]
	v_mfma_f32_16x16x32_bf16 v[24:27], v[164:167], v[180:183], v[24:27]
	v_mfma_f32_16x16x32_bf16 v[12:15], v[156:159], v[188:191], v[12:15]
	v_mfma_f32_16x16x32_bf16 v[8:11], v[164:167], v[188:191], v[8:11]
	v_mfma_f32_16x16x32_bf16 v[4:7], v[156:159], v[218:221], v[4:7]
	v_mfma_f32_16x16x32_bf16 v[0:3], v[164:167], v[218:221], v[0:3]
	v_mfma_f32_16x16x32_bf16 v[44:47], v[160:163], v[176:179], v[44:47]
	v_mfma_f32_16x16x32_bf16 v[40:43], v[168:171], v[176:179], v[40:43]
	v_mfma_f32_16x16x32_bf16 v[28:31], v[160:163], v[184:187], v[28:31]
	v_mfma_f32_16x16x32_bf16 v[24:27], v[168:171], v[184:187], v[24:27]
	v_mfma_f32_16x16x32_bf16 v[12:15], v[160:163], v[214:217], v[12:15]
	v_mfma_f32_16x16x32_bf16 v[8:11], v[168:171], v[214:217], v[8:11]
	v_mfma_f32_16x16x32_bf16 v[4:7], v[160:163], v[222:225], v[4:7]
	v_mfma_f32_16x16x32_bf16 v[0:3], v[168:171], v[222:225], v[0:3]
	s_setprio 0
	s_barrier
	s_add_i32 s22, 0, 0x18000
	s_add_i32 s23, 0, 0x1c000
	v_add_u32_e32 v152, s22, v137
	v_add_u32_e32 v168, s23, v137
	ds_read_b128 v[140:143], v152
	ds_read_b128 v[144:147], v152 offset:1024
	ds_read_b128 v[148:151], v152 offset:2048
	ds_read_b128 v[152:155], v152 offset:3072
	ds_read_b128 v[156:159], v168
	ds_read_b128 v[160:163], v168 offset:1024
	ds_read_b128 v[164:167], v168 offset:2048
	ds_read_b128 v[168:171], v168 offset:3072
	s_add_u32 s10, s10, 0x100000
	s_addc_u32 s11, s11, 0
	s_mov_b32 m0, s62
	v_lshl_add_u64 v[232:233], s[10:11], 0, v[64:65]
	ds_read_b128 v[172:175], v139 offset:32768
	ds_read_b128 v[176:179], v139 offset:33792
	ds_read_b128 v[180:183], v139 offset:34816
	ds_read_b128 v[184:187], v139 offset:35840
	ds_read_b128 v[188:191], v139 offset:36864
	ds_read_b128 v[214:217], v139 offset:37888
	ds_read_b128 v[218:221], v139 offset:38912
	ds_read_b128 v[222:225], v139 offset:39936
	global_load_lds_dwordx4 v[232:233], off
	v_lshl_add_u64 v[232:233], s[10:11], 0, v[130:131]
	s_mov_b32 m0, s64
	s_nop 0
	global_load_lds_dwordx4 v[232:233], off
	s_waitcnt vmcnt(8) lgkmcnt(0)
	s_barrier
	s_setprio 1
	v_mfma_f32_16x16x32_bf16 v[126:129], v[140:143], v[172:175], v[126:129]
	v_mfma_f32_16x16x32_bf16 v[122:125], v[148:151], v[172:175], v[122:125]
	v_mfma_f32_16x16x32_bf16 v[118:121], v[140:143], v[180:183], v[118:121]
	v_mfma_f32_16x16x32_bf16 v[114:117], v[148:151], v[180:183], v[114:117]
	v_mfma_f32_16x16x32_bf16 v[106:109], v[140:143], v[188:191], v[106:109]
	v_mfma_f32_16x16x32_bf16 v[98:101], v[148:151], v[188:191], v[98:101]
	v_mfma_f32_16x16x32_bf16 v[90:93], v[140:143], v[218:221], v[90:93]
	v_mfma_f32_16x16x32_bf16 v[82:85], v[148:151], v[218:221], v[82:85]
	v_mfma_f32_16x16x32_bf16 v[126:129], v[144:147], v[176:179], v[126:129]
	v_mfma_f32_16x16x32_bf16 v[122:125], v[152:155], v[176:179], v[122:125]
	v_mfma_f32_16x16x32_bf16 v[118:121], v[144:147], v[184:187], v[118:121]
	v_mfma_f32_16x16x32_bf16 v[114:117], v[152:155], v[184:187], v[114:117]
	v_mfma_f32_16x16x32_bf16 v[106:109], v[144:147], v[214:217], v[106:109]
	v_mfma_f32_16x16x32_bf16 v[98:101], v[152:155], v[214:217], v[98:101]
	v_mfma_f32_16x16x32_bf16 v[90:93], v[144:147], v[222:225], v[90:93]
	v_mfma_f32_16x16x32_bf16 v[82:85], v[152:155], v[222:225], v[82:85]
	v_mfma_f32_16x16x32_bf16 v[110:113], v[156:159], v[172:175], v[110:113]
	v_mfma_f32_16x16x32_bf16 v[102:105], v[164:167], v[172:175], v[102:105]
	v_mfma_f32_16x16x32_bf16 v[94:97], v[156:159], v[180:183], v[94:97]
	v_mfma_f32_16x16x32_bf16 v[86:89], v[164:167], v[180:183], v[86:89]
	v_mfma_f32_16x16x32_bf16 v[78:81], v[156:159], v[188:191], v[78:81]
	v_mfma_f32_16x16x32_bf16 v[74:77], v[164:167], v[188:191], v[74:77]
	v_mfma_f32_16x16x32_bf16 v[70:73], v[156:159], v[218:221], v[70:73]
	v_mfma_f32_16x16x32_bf16 v[66:69], v[164:167], v[218:221], v[66:69]
	v_mfma_f32_16x16x32_bf16 v[110:113], v[160:163], v[176:179], v[110:113]
	v_mfma_f32_16x16x32_bf16 v[102:105], v[168:171], v[176:179], v[102:105]
	v_mfma_f32_16x16x32_bf16 v[94:97], v[160:163], v[184:187], v[94:97]
	v_mfma_f32_16x16x32_bf16 v[86:89], v[168:171], v[184:187], v[86:89]
	v_mfma_f32_16x16x32_bf16 v[78:81], v[160:163], v[214:217], v[78:81]
	v_mfma_f32_16x16x32_bf16 v[74:77], v[168:171], v[214:217], v[74:77]
	v_mfma_f32_16x16x32_bf16 v[70:73], v[160:163], v[222:225], v[70:73]
	v_mfma_f32_16x16x32_bf16 v[66:69], v[168:171], v[222:225], v[66:69]
	s_setprio 0
	s_barrier
; #define PG8_STAGE(bufoff, gbase, voff) do { _Pragma("unroll") for (int _i = 0; _i < 2; ++_i) \
;         __builtin_amdgcn_global_load_lds((const unsigned*)((const char*)(gbase) + (voff)[_i]), (LAS unsigned*)(lds + (bufoff) + ldsw + _i * 8192), 16, 0, 0); } while (0)
; #define PG8_LDA(dst, b, h) do { _Pragma("unroll") for (int m = 0; m < 4; ++m) _Pragma("unroll") for (int k = 0; k < 2; ++k) dst[m][k] = *(const LAS bf16x8*)(lds + PG8_SA(b, h) + aoff + m * 2048 + k * 1024); } while (0)
; #define PG8_MMA(ai, bj, At, Bt) do { __builtin_amdgcn_s_setprio(1); _Pragma("unroll") for (int m = 0; m < 4; ++m) _Pragma("unroll") for (int n = 0; n < 2; ++n) _Pragma("unroll") for (int k = 0; k < 2; ++k) \
;         acc[ai][bj][m][n] = __builtin_amdgcn_mfma_f32_16x16x32_bf16(Bt[n][k], At[m][k], acc[ai][bj][m][n], 0, 0, 0); __builtin_amdgcn_s_setprio(0); } while (0)
; #define PG8_WAIT_V(n) asm volatile("s_waitcnt vmcnt(" #n ")" ::: "memory")
; #define PG8_WAIT_L(n) asm volatile("s_waitcnt lgkmcnt(" #n ")" ::: "memory")
; #define PG8_BAR __builtin_amdgcn_s_barrier()
; #define PG8_SCHED __builtin_amdgcn_sched_barrier(0)
; template <class Epi, bool SP2, class Sched>
; __device__ __forceinline__ void gemm_phase(LAS unsigned char* lds, const Gemm g, const Sched& S, const Epi& E) {
;     ...
;             PG8_LDA(At, 1, 1); PG8_STAGE(PG8_SB(1, 0), b3, voffB); PG8_STAGE(PG8_SB(1, 1), b3 + hstepB, voffB); PG8_STAGE(PG8_SA(1, 0), a3, voffA);
;             PG8_WAIT_V(8); PG8_WAIT_L(0); PG8_BAR; PG8_MMA(1, 0, At, B0); PG8_MMA(1, 1, At, B1); PG8_BAR; PG8_SCHED;
;     ...
;         if (wr == 0) PG8_BAR;
	s_add_i32 s10, s22, s18
	v_lshl_add_u64 v[192:193], v[192:193], 0, s[66:67]
	s_mov_b32 m0, s10
	ds_read_b128 v[172:175], v139 offset:49152
	ds_read_b128 v[176:179], v139 offset:50176
	ds_read_b128 v[180:183], v139 offset:51200
	ds_read_b128 v[184:187], v139 offset:52224
	ds_read_b128 v[188:191], v139 offset:53248
	ds_read_b128 v[214:217], v139 offset:54272
	ds_read_b128 v[218:221], v139 offset:55296
	ds_read_b128 v[222:225], v139 offset:56320
	global_load_lds_dwordx4 v[192:193], off
	s_add_i32 m0, s10, 0x2000
	s_add_u32 s6, s6, 0x100080
	v_lshl_add_u64 v[192:193], v[226:227], 0, s[66:67]
	s_addc_u32 s7, s7, 0
	s_add_i32 s10, s23, s18
	global_load_lds_dwordx4 v[192:193], off
	v_lshl_add_u64 v[192:193], s[6:7], 0, v[64:65]
	s_mov_b32 m0, s10
	s_nop 0
	global_load_lds_dwordx4 v[192:193], off
	v_lshl_add_u64 v[192:193], s[6:7], 0, v[130:131]
	s_add_i32 m0, s10, 0x2000
	s_nop 0
	global_load_lds_dwordx4 v[192:193], off
	v_lshl_add_u64 v[192:193], v[228:229], 0, s[66:67]
	s_mov_b32 m0, s72
	s_nop 0
	global_load_lds_dwordx4 v[192:193], off
	v_lshl_add_u64 v[192:193], v[230:231], 0, s[66:67]
	s_mov_b32 m0, s73
	s_nop 0
	global_load_lds_dwordx4 v[192:193], off
	s_waitcnt vmcnt(8) lgkmcnt(0)
	s_barrier
	s_setprio 1
	v_mfma_f32_16x16x32_bf16 v[60:63], v[140:143], v[172:175], v[60:63]
	v_mfma_f32_16x16x32_bf16 v[56:59], v[148:151], v[172:175], v[56:59]
	v_mfma_f32_16x16x32_bf16 v[52:55], v[140:143], v[180:183], v[52:55]
	v_mfma_f32_16x16x32_bf16 v[48:51], v[148:151], v[180:183], v[48:51]
	v_mfma_f32_16x16x32_bf16 v[36:39], v[140:143], v[188:191], v[36:39]
	v_mfma_f32_16x16x32_bf16 v[32:35], v[148:151], v[188:191], v[32:35]
	v_mfma_f32_16x16x32_bf16 v[20:23], v[140:143], v[218:221], v[20:23]
	v_mfma_f32_16x16x32_bf16 v[16:19], v[148:151], v[218:221], v[16:19]
	v_mfma_f32_16x16x32_bf16 v[60:63], v[144:147], v[176:179], v[60:63]
	v_mfma_f32_16x16x32_bf16 v[56:59], v[152:155], v[176:179], v[56:59]
	v_mfma_f32_16x16x32_bf16 v[52:55], v[144:147], v[184:187], v[52:55]
	v_mfma_f32_16x16x32_bf16 v[48:51], v[152:155], v[184:187], v[48:51]
	v_mfma_f32_16x16x32_bf16 v[36:39], v[144:147], v[214:217], v[36:39]
	v_mfma_f32_16x16x32_bf16 v[32:35], v[152:155], v[214:217], v[32:35]
	v_mfma_f32_16x16x32_bf16 v[20:23], v[144:147], v[222:225], v[20:23]
	v_mfma_f32_16x16x32_bf16 v[16:19], v[152:155], v[222:225], v[16:19]
	v_mfma_f32_16x16x32_bf16 v[44:47], v[156:159], v[172:175], v[44:47]
	v_mfma_f32_16x16x32_bf16 v[40:43], v[164:167], v[172:175], v[40:43]
	v_mfma_f32_16x16x32_bf16 v[28:31], v[156:159], v[180:183], v[28:31]
	v_mfma_f32_16x16x32_bf16 v[24:27], v[164:167], v[180:183], v[24:27]
	v_mfma_f32_16x16x32_bf16 v[12:15], v[156:159], v[188:191], v[12:15]
	v_mfma_f32_16x16x32_bf16 v[8:11], v[164:167], v[188:191], v[8:11]
	v_mfma_f32_16x16x32_bf16 v[4:7], v[156:159], v[218:221], v[4:7]
	v_mfma_f32_16x16x32_bf16 v[0:3], v[164:167], v[218:221], v[0:3]
	v_mfma_f32_16x16x32_bf16 v[44:47], v[160:163], v[176:179], v[44:47]
	v_mfma_f32_16x16x32_bf16 v[40:43], v[168:171], v[176:179], v[40:43]
	v_mfma_f32_16x16x32_bf16 v[28:31], v[160:163], v[184:187], v[28:31]
	v_mfma_f32_16x16x32_bf16 v[24:27], v[168:171], v[184:187], v[24:27]
	v_mfma_f32_16x16x32_bf16 v[12:15], v[160:163], v[214:217], v[12:15]
	v_mfma_f32_16x16x32_bf16 v[8:11], v[168:171], v[214:217], v[8:11]
	v_mfma_f32_16x16x32_bf16 v[4:7], v[160:163], v[222:225], v[4:7]
	v_mfma_f32_16x16x32_bf16 v[0:3], v[168:171], v[222:225], v[0:3]
	s_setprio 0
	s_barrier
	s_add_i32 s21, s21, 2
	s_add_u32 s79, s79, 0x100
	s_addc_u32 s20, s20, 0
	s_add_u32 s86, s86, 0x100
	s_addc_u32 s87, s87, 0
	s_cmp_gt_u32 s21, 13
	s_cbranch_scc0 .LBB0_1150
	s_and_b64 vcc, exec, s[16:17]
	s_cbranch_vccz .LBB0_1153
	s_barrier
